# speedup vs baseline: 1.0713x; 1.0713x over previous
; __device__ __forceinline__ void qkt(f32x16& p0, f32x16& p1, const char* Ks, const bf16x8* qr, int r32, int hi, int map, float negM) {
; #pragma unroll
;   for (int r = 0; r < 16; ++r) { p0[r] = negM; p1[r] = negM; }
; #pragma unroll
;   for (int d0 = 0; d0 < 4; ++d0) {
;     int cb = (map * 64 + d0 * 16 + hi * 8) * 2;
;     bf16x8 b0 = *reinterpret_cast<const bf16x8*>(Ks + KSWZ(r32, cb));
;     bf16x8 b1 = *reinterpret_cast<const bf16x8*>(Ks + KSWZ(32 + r32, cb));
;     p0 = __builtin_amdgcn_mfma_f32_32x32x16_bf16(b0, qr[d0], p0, 0, 0, 0);
;     p1 = __builtin_amdgcn_mfma_f32_32x32x16_bf16(b1, qr[d0], p1, 0, 0, 0);
;   }
; template <int MODE> __device__ __forceinline__ void diff_attn_item(const bf16* __restrict__ Qb, const bf16* __restrict__ Kh, const bf16* __restrict__ Vh, ...
;     ...
;   const int ldsbase = (int)(uintptr_t)(__attribute__((address_space(3))) char*)lds;
;   int voff[4];
; #pragma unroll
;   for (int ks = 0; ks < 4; ++ks) voff[ks] = r32 * 128 + ((((ks << 1) | hi) ^ ((r32 >> 1) & 7)) << 4);
;   int ksrc[2], vsrc[2];
; #pragma unroll
;   for (int i = 0; i < 2; ++i) {
;     const int q = tid + i * 512;
;     const int krow = q >> 4, kc = (q & 15) ^ (krow & 15);
;     ksrc[i] = krow * 128 + kc * 8;
;     const int vrow = q >> 3, vc = (q & 7) ^ ((vrow >> 1) & 7);
;     vsrc[i] = vrow * 64 + vc * 8;
;   }
;     ...
;   const int NTL = seq / KVBLK;
;   f32x16 pc0, pc1, pn0, pn1;
;   SLOADW(0, 0);
;   SLOADW(1, KVBLK);
;   asm volatile("s_waitcnt vmcnt(0)" ::: "memory");
;   __syncthreads();
;   qkt(pc0, pc1, lds + SHM_KV, qr, r32, hi, map, negM);
.Lda0_new:
	v_and_b32_e32 v250, 31, v163
	v_bfe_u32 v251, v163, 5, 1
	v_lshrrev_b32_e32 v252, 8, v163
	v_and_b32_e32 v248, 15, v250
	v_lshlrev_b32_e32 v248, 4, v248
	v_lshlrev_b32_e32 v249, 7, v252
	v_lshl_or_b32 v249, v251, 4, v249
	v_xor_b32_e32 v248, v248, v249
	v_lshl_or_b32 v228, v250, 8, v248
	v_add_u32_e32 v228, 0xc000, v228
	v_xor_b32_e32 v229, 32, v228
	v_xor_b32_e32 v230, 64, v228
	v_xor_b32_e32 v231, 96, v228
	v_bfe_u32 v248, v250, 1, 3
	v_xor_b32_e32 v248, v248, v251
	v_lshlrev_b32_e32 v248, 4, v248
	v_lshl_or_b32 v232, v250, 7, v248
	v_xor_b32_e32 v233, 32, v232
	v_xor_b32_e32 v234, 64, v232
	v_xor_b32_e32 v235, 96, v232
	v_lshrrev_b32_e32 v248, 4, v163
	v_xor_b32_e32 v249, v248, v163
	v_and_b32_e32 v249, 15, v249
	v_lshlrev_b32_e32 v249, 4, v249
	v_lshl_or_b32 v236, v248, 8, v249
	v_add_u32_e32 v237, 0x2000, v236
	v_xor_b32_e32 v249, v248, v163
	v_and_b32_e32 v249, 7, v249
	v_lshlrev_b32_e32 v249, 4, v249
	v_lshrrev_b32_e32 v248, 3, v163
	v_lshl_or_b32 v246, v248, 7, v249
	v_add_u32_e32 v247, 0x2000, v246
	v_lshrrev_b32_e32 v248, 6, v163
	v_lshlrev_b32_e32 v248, 10, v248
	v_mov_b32_e32 v190, 0
	v_mov_b32_e32 v191, 0
	v_mov_b32_e32 v66, 0
	v_mov_b32_e32 v67, 0
	v_mov_b32_e32 v68, 0
	v_mov_b32_e32 v69, 0
	v_mov_b32_e32 v70, 0
	v_mov_b32_e32 v71, 0
	v_mov_b32_e32 v72, 0
	v_mov_b32_e32 v73, 0
	v_mov_b32_e32 v74, 0
	v_mov_b32_e32 v75, 0
	v_mov_b32_e32 v76, 0
	v_mov_b32_e32 v77, 0
	v_mov_b32_e32 v78, 0
	v_mov_b32_e32 v79, 0
	v_mov_b32_e32 v80, 0
	v_mov_b32_e32 v81, 0
	v_mov_b32_e32 v50, 0
	v_mov_b32_e32 v51, 0
	v_mov_b32_e32 v52, 0
	v_mov_b32_e32 v53, 0
	v_mov_b32_e32 v54, 0
	v_mov_b32_e32 v55, 0
	v_mov_b32_e32 v56, 0
	v_mov_b32_e32 v57, 0
	v_mov_b32_e32 v58, 0
	v_mov_b32_e32 v59, 0
	v_mov_b32_e32 v60, 0
	v_mov_b32_e32 v61, 0
	v_mov_b32_e32 v62, 0
	v_mov_b32_e32 v63, 0
	v_mov_b32_e32 v64, 0
	v_mov_b32_e32 v65, 0
	v_mov_b32_e32 v34, 0
	v_mov_b32_e32 v35, 0
	v_mov_b32_e32 v36, 0
	v_mov_b32_e32 v37, 0
	v_mov_b32_e32 v38, 0
	v_mov_b32_e32 v39, 0
	v_mov_b32_e32 v40, 0
	v_mov_b32_e32 v41, 0
	v_mov_b32_e32 v42, 0
	v_mov_b32_e32 v43, 0
	v_mov_b32_e32 v44, 0
	v_mov_b32_e32 v45, 0
	v_mov_b32_e32 v46, 0
	v_mov_b32_e32 v47, 0
	v_mov_b32_e32 v48, 0
	v_mov_b32_e32 v49, 0
	v_mov_b32_e32 v18, 0
	v_mov_b32_e32 v19, 0
	v_mov_b32_e32 v20, 0
	v_mov_b32_e32 v21, 0
	v_mov_b32_e32 v22, 0
	v_mov_b32_e32 v23, 0
	v_mov_b32_e32 v24, 0
	v_mov_b32_e32 v25, 0
	v_mov_b32_e32 v26, 0
	v_mov_b32_e32 v27, 0
	v_mov_b32_e32 v28, 0
	v_mov_b32_e32 v29, 0
	v_mov_b32_e32 v30, 0
	v_mov_b32_e32 v31, 0
	v_mov_b32_e32 v32, 0
	v_mov_b32_e32 v33, 0
	v_readfirstlane_b32 s14, v248
	s_waitcnt lgkmcnt(0)
	s_nop 3
	v_mov_b32_e32 v254, 0
	v_mov_b32_e32 v252, v236
	v_mov_b32_e32 v253, 0
	v_mov_b32_e32 v164, v237
	v_mov_b32_e32 v199, v246
	v_mov_b32_e32 v211, v247
	v_lshl_add_u64 v[236:237], s[8:9], 0, v[252:253]
	v_mov_b32_e32 v252, v164
	v_lshl_add_u64 v[248:249], s[8:9], 0, v[252:253]
	v_mov_b32_e32 v252, v199
	v_lshl_add_u64 v[246:247], s[10:11], 0, v[252:253]
	v_mov_b32_e32 v252, v211
	v_lshl_add_u64 v[250:251], s[10:11], 0, v[252:253]
	s_mov_b32 s18, 0x4000
	s_mov_b32 s19, 0
	s_add_u32 s16, s14, 0xc000
	s_mov_b32 m0, s16
	s_nop 0
	global_load_lds_dwordx4 v[236:237], off
	s_add_u32 s16, s14, 0xe000
	s_mov_b32 m0, s16
	s_nop 0
	global_load_lds_dwordx4 v[248:249], off
	v_lshl_add_u64 v[236:237], v[236:237], 0, s[18:19]
	v_lshl_add_u64 v[248:249], v[248:249], 0, s[18:19]
	s_add_u32 s16, s14, 0x10000
	s_mov_b32 m0, s16
	s_nop 0
	global_load_lds_dwordx4 v[236:237], off
	s_add_u32 s16, s14, 0x12000
	s_mov_b32 m0, s16
	s_nop 0
	global_load_lds_dwordx4 v[248:249], off
	v_lshl_add_u64 v[236:237], v[236:237], 0, s[18:19]
	v_lshl_add_u64 v[248:249], v[248:249], 0, s[18:19]
	s_add_u32 s16, s14, 0x14000
	s_mov_b32 m0, s16
	s_nop 0
	global_load_lds_dwordx4 v[236:237], off
	s_add_u32 s16, s14, 0x16000
	s_mov_b32 m0, s16
	s_nop 0
	global_load_lds_dwordx4 v[248:249], off
	v_lshl_add_u64 v[236:237], v[236:237], 0, s[18:19]
	v_lshl_add_u64 v[248:249], v[248:249], 0, s[18:19]
	s_add_u32 s16, s14, 0x0
	s_mov_b32 m0, s16
	s_nop 0
	global_load_lds_dwordx4 v[246:247], off
	s_add_u32 s16, s14, 0x2000
	s_mov_b32 m0, s16
	s_nop 0
	global_load_lds_dwordx4 v[250:251], off
	v_lshl_add_u64 v[246:247], v[246:247], 0, s[18:19]
	v_lshl_add_u64 v[250:251], v[250:251], 0, s[18:19]
	s_waitcnt vmcnt(0)
	s_barrier
	ds_read_b128 v[186:189], v228 offset:0
	ds_read_b128 v[200:203], v229 offset:0
	ds_read_b128 v[204:207], v230 offset:0
	ds_read_b128 v[208:211], v231 offset:0
	ds_read_b128 v[212:215], v228 offset:8192
	ds_read_b128 v[216:219], v229 offset:8192
	ds_read_b128 v[220:223], v230 offset:8192
	ds_read_b128 v[224:227], v231 offset:8192
	s_waitcnt lgkmcnt(7)
	v_mfma_f32_32x32x16_bf16 v[82:97], v[186:189], v[158:161], v[0:15]
	s_waitcnt lgkmcnt(6)
	v_mfma_f32_32x32x16_bf16 v[82:97], v[200:203], v[154:157], v[82:97]
	s_waitcnt lgkmcnt(5)
	v_mfma_f32_32x32x16_bf16 v[82:97], v[204:207], v[150:153], v[82:97]
	s_waitcnt lgkmcnt(4)
	v_mfma_f32_32x32x16_bf16 v[82:97], v[208:211], v[146:149], v[82:97]
	s_waitcnt lgkmcnt(3)
	v_mfma_f32_32x32x16_bf16 v[98:113], v[212:215], v[158:161], v[0:15]
	s_waitcnt lgkmcnt(2)
	v_mfma_f32_32x32x16_bf16 v[98:113], v[216:219], v[154:157], v[98:113]
	s_waitcnt lgkmcnt(1)
	v_mfma_f32_32x32x16_bf16 v[98:113], v[220:223], v[150:153], v[98:113]
	s_waitcnt lgkmcnt(0)
	v_mfma_f32_32x32x16_bf16 v[98:113], v[224:227], v[146:149], v[98:113]
	s_barrier
; template <int MODE> __device__ __forceinline__ void sm_half(f32x16& p, float& lsum, bf16x8& f0, bf16x8& f1) {
;   if (MODE != 3) {
; #pragma unroll
;   for (int r = 0; r < 16; ++r) p[r] = __builtin_amdgcn_exp2f(p[r]);
;   }
;   float s0 = 0, s1 = 0;
; #pragma unroll
;   for (int r = 0; r < 16; r += 2) { s0 += p[r]; s1 += p[r + 1]; }
;   lsum += s0 + s1;
;   u32x4 w0 = {cvtpk(p[0], p[1]), cvtpk(p[2], p[3]), cvtpk(p[4], p[5]), cvtpk(p[6], p[7])};
;   u32x4 w1 = {cvtpk(p[8], p[9]), cvtpk(p[10], p[11]), cvtpk(p[12], p[13]), cvtpk(p[14], p[15])};
;   f0 = *reinterpret_cast<bf16x8*>(&w0); f1 = *reinterpret_cast<bf16x8*>(&w1);
; template <int MODE> __device__ __forceinline__ void diff_attn_item(const bf16* __restrict__ Qb, const bf16* __restrict__ Kh, const bf16* __restrict__ Vh, ...
;     ...
;   for (int j = 0; j < NTL; ++j) {
;     const bool has1 = (j + 1 < NTL), has2 = (j + 2 < NTL);
;     if (has2 && MODE == 0) SLOADW(s_wr, (j + 2) * KVBLK);
;     bf16x8 f0, f1, f2, f3;
;     if (has1) qkt(pn0, pn1, lds + s_nxt * SHM_BUF + SHM_KV, qr, r32, hi, map, negM);
;     sm_half<MODE>(pc0, lsum, f0, f1);
;     const char* vt = lds + s_cur * SHM_BUF;
;     pv_b128(o, vt + voff[0], f0); pv_b128(o, vt + voff[1], f1);
;     sm_half<MODE>(pc1, lsum, f2, f3);
;     pv_b128(o, vt + voff[2], f2); pv_b128(o, vt + voff[3], f3);
	s_add_u32 s16, s14, 0x4000
	s_mov_b32 m0, s16
	s_nop 0
	global_load_lds_dwordx4 v[246:247], off
	s_add_u32 s16, s14, 0x6000
	s_mov_b32 m0, s16
	s_nop 0
	global_load_lds_dwordx4 v[250:251], off
	v_lshl_add_u64 v[246:247], v[246:247], 0, s[18:19]
	v_lshl_add_u64 v[250:251], v[250:251], 0, s[18:19]
	s_add_u32 s16, s14, 0xc000
	s_mov_b32 m0, s16
	s_nop 0
	global_load_lds_dwordx4 v[236:237], off
	s_add_u32 s16, s14, 0xe000
	s_mov_b32 m0, s16
	s_nop 0
	global_load_lds_dwordx4 v[248:249], off
	v_lshl_add_u64 v[236:237], v[236:237], 0, s[18:19]
	v_lshl_add_u64 v[248:249], v[248:249], 0, s[18:19]
	ds_read_b128 v[186:189], v228 offset:16384
	ds_read_b128 v[200:203], v229 offset:16384
	ds_read_b128 v[204:207], v230 offset:16384
	ds_read_b128 v[208:211], v231 offset:16384
	ds_read_b128 v[212:215], v228 offset:24576
	ds_read_b128 v[216:219], v229 offset:24576
	ds_read_b128 v[220:223], v230 offset:24576
	ds_read_b128 v[224:227], v231 offset:24576
	v_exp_f32_e32 v130, v82
	v_exp_f32_e32 v131, v83
	v_add_f32_e32 v190, v190, v130
	v_exp_f32_e32 v132, v84
	v_exp_f32_e32 v133, v85
	v_add_f32_e32 v191, v191, v131
	v_exp_f32_e32 v134, v86
	v_exp_f32_e32 v135, v87
	v_add_f32_e32 v190, v190, v132
	v_exp_f32_e32 v136, v88
	v_exp_f32_e32 v137, v89
	v_add_f32_e32 v191, v191, v133
	v_exp_f32_e32 v138, v90
	v_exp_f32_e32 v139, v91
	v_cvt_pk_bf16_f32 v114, v130, v131
	v_exp_f32_e32 v140, v92
	v_exp_f32_e32 v141, v93
	v_cvt_pk_bf16_f32 v115, v132, v133
	v_exp_f32_e32 v142, v94
	v_exp_f32_e32 v143, v95
	v_add_f32_e32 v190, v190, v134
	v_exp_f32_e32 v144, v96
	v_exp_f32_e32 v145, v97
	v_add_f32_e32 v191, v191, v135
	v_exp_f32_e32 v238, v98
	v_exp_f32_e32 v239, v99
	v_cvt_pk_bf16_f32 v116, v134, v135
	v_exp_f32_e32 v240, v100
	v_exp_f32_e32 v241, v101
	v_add_f32_e32 v190, v190, v136
	v_exp_f32_e32 v242, v102
	v_exp_f32_e32 v243, v103
	v_add_f32_e32 v191, v191, v137
	v_exp_f32_e32 v244, v104
	v_exp_f32_e32 v245, v105
	v_cvt_pk_bf16_f32 v117, v136, v137
	v_exp_f32_e32 v130, v106
	v_exp_f32_e32 v131, v107
	v_add_f32_e32 v190, v190, v138
	v_exp_f32_e32 v132, v108
	v_exp_f32_e32 v133, v109
	v_add_f32_e32 v191, v191, v139
	v_exp_f32_e32 v134, v110
	v_exp_f32_e32 v135, v111
	v_add_f32_e32 v190, v190, v140
	v_exp_f32_e32 v136, v112
	v_exp_f32_e32 v137, v113
	v_add_f32_e32 v191, v191, v141
	s_waitcnt lgkmcnt(7)
	v_mfma_f32_32x32x16_bf16 v[82:97], v[186:189], v[158:161], v[0:15]
	ds_read_b128 v[166:169], v232 offset:0
	v_cvt_pk_bf16_f32 v118, v138, v139
	v_cvt_pk_bf16_f32 v119, v140, v141
	v_add_f32_e32 v190, v190, v142
	v_add_f32_e32 v191, v191, v143
	s_waitcnt lgkmcnt(7)
	v_mfma_f32_32x32x16_bf16 v[82:97], v[200:203], v[154:157], v[82:97]
	ds_read_b128 v[170:173], v232 offset:4096
	v_cvt_pk_bf16_f32 v120, v142, v143
	v_add_f32_e32 v190, v190, v144
	v_add_f32_e32 v191, v191, v145
	v_cvt_pk_bf16_f32 v121, v144, v145
	s_waitcnt lgkmcnt(7)
	v_mfma_f32_32x32x16_bf16 v[82:97], v[204:207], v[150:153], v[82:97]
	ds_read_b128 v[178:181], v232 offset:8192
	v_add_f32_e32 v190, v190, v238
	v_add_f32_e32 v191, v191, v239
	v_cvt_pk_bf16_f32 v122, v238, v239
	v_add_f32_e32 v190, v190, v240
	s_waitcnt lgkmcnt(7)
	v_mfma_f32_32x32x16_bf16 v[82:97], v[208:211], v[146:149], v[82:97]
	ds_read_b128 v[182:185], v232 offset:12288
	v_add_f32_e32 v191, v191, v241
	v_cvt_pk_bf16_f32 v123, v240, v241
	v_add_f32_e32 v190, v190, v242
	v_add_f32_e32 v191, v191, v243
	s_waitcnt lgkmcnt(7)
	v_mfma_f32_32x32x16_bf16 v[98:113], v[212:215], v[158:161], v[0:15]
	ds_read_b128 v[186:189], v233 offset:0
	v_cvt_pk_bf16_f32 v124, v242, v243
	v_add_f32_e32 v190, v190, v244
	v_add_f32_e32 v191, v191, v245
	v_cvt_pk_bf16_f32 v125, v244, v245
	s_waitcnt lgkmcnt(7)
	v_mfma_f32_32x32x16_bf16 v[98:113], v[216:219], v[154:157], v[98:113]
	ds_read_b128 v[200:203], v233 offset:4096
	v_add_f32_e32 v190, v190, v130
	v_add_f32_e32 v191, v191, v131
	v_cvt_pk_bf16_f32 v126, v130, v131
	v_add_f32_e32 v190, v190, v132
	s_waitcnt lgkmcnt(7)
	v_mfma_f32_32x32x16_bf16 v[98:113], v[220:223], v[150:153], v[98:113]
	ds_read_b128 v[204:207], v233 offset:8192
	v_add_f32_e32 v191, v191, v133
	v_cvt_pk_bf16_f32 v127, v132, v133
	v_add_f32_e32 v190, v190, v134
	v_add_f32_e32 v191, v191, v135
	s_waitcnt lgkmcnt(7)
	v_mfma_f32_32x32x16_bf16 v[98:113], v[224:227], v[146:149], v[98:113]
	ds_read_b128 v[208:211], v233 offset:12288
	v_cvt_pk_bf16_f32 v128, v134, v135
	v_add_f32_e32 v190, v190, v136
	v_add_f32_e32 v191, v191, v137
	v_cvt_pk_bf16_f32 v129, v136, v137
	s_waitcnt vmcnt(0) lgkmcnt(0)
	s_movk_i32 s15, 42
; template <int MODE> __device__ __forceinline__ void sm_half(f32x16& p, float& lsum, bf16x8& f0, bf16x8& f1) {
;   if (MODE != 3) {
; #pragma unroll
;   for (int r = 0; r < 16; ++r) p[r] = __builtin_amdgcn_exp2f(p[r]);
;   }
;   float s0 = 0, s1 = 0;
; #pragma unroll
;   for (int r = 0; r < 16; r += 2) { s0 += p[r]; s1 += p[r + 1]; }
;   lsum += s0 + s1;
;   u32x4 w0 = {cvtpk(p[0], p[1]), cvtpk(p[2], p[3]), cvtpk(p[4], p[5]), cvtpk(p[6], p[7])};
;   u32x4 w1 = {cvtpk(p[8], p[9]), cvtpk(p[10], p[11]), cvtpk(p[12], p[13]), cvtpk(p[14], p[15])};
;   f0 = *reinterpret_cast<bf16x8*>(&w0); f1 = *reinterpret_cast<bf16x8*>(&w1);
; template <int MODE> __device__ __forceinline__ void diff_attn_item(const bf16* __restrict__ Qb, const bf16* __restrict__ Kh, const bf16* __restrict__ Vh, ...
;     ...
;   for (int j = 0; j < NTL; ++j) {
;     const bool has1 = (j + 1 < NTL), has2 = (j + 2 < NTL);
;     if (has2 && MODE == 0) SLOADW(s_wr, (j + 2) * KVBLK);
;     bf16x8 f0, f1, f2, f3;
;     if (has1) qkt(pn0, pn1, lds + s_nxt * SHM_BUF + SHM_KV, qr, r32, hi, map, negM);
;     sm_half<MODE>(pc0, lsum, f0, f1);
;     const char* vt = lds + s_cur * SHM_BUF;
;     pv_b128(o, vt + voff[0], f0); pv_b128(o, vt + voff[1], f1);
;     sm_half<MODE>(pc1, lsum, f2, f3);
;     pv_b128(o, vt + voff[2], f2); pv_b128(o, vt + voff[3], f3);
;     asm volatile("s_waitcnt vmcnt(0)" ::: "memory");
;     __syncthreads();
;     pc0 = pn0; pc1 = pn1;
;     const int t = s_cur; s_cur = s_nxt; s_nxt = s_wr; s_wr = t;
;   }
.Lda0_loop:
	s_barrier
	s_waitcnt lgkmcnt(7)
	v_mfma_f32_32x32x16_bf16 v[66:81], v[166:169], v[114:117], v[66:81]
	s_add_u32 s16, s14, 0x8000
	s_mov_b32 m0, s16
	ds_read_b128 v[212:215], v234 offset:0
	global_load_lds_dwordx4 v[246:247], off
	v_exp_f32_e32 v130, v82
	v_exp_f32_e32 v131, v83
	v_add_f32_e32 v190, v190, v130
	s_waitcnt lgkmcnt(7)
	v_mfma_f32_32x32x16_bf16 v[50:65], v[170:173], v[114:117], v[50:65]
	s_add_u32 s16, s14, 0xa000
	s_mov_b32 m0, s16
	ds_read_b128 v[216:219], v234 offset:4096
	global_load_lds_dwordx4 v[250:251], off
	v_lshl_add_u64 v[246:247], v[246:247], 0, s[18:19]
	v_lshl_add_u64 v[250:251], v[250:251], 0, s[18:19]
	v_exp_f32_e32 v132, v84
	v_exp_f32_e32 v133, v85
	v_add_f32_e32 v191, v191, v131
	s_waitcnt lgkmcnt(7)
	v_mfma_f32_32x32x16_bf16 v[34:49], v[178:181], v[114:117], v[34:49]
	s_add_u32 s16, s14, 0x10000
	s_mov_b32 m0, s16
	ds_read_b128 v[220:223], v234 offset:8192
	global_load_lds_dwordx4 v[236:237], off
	v_exp_f32_e32 v134, v86
	v_exp_f32_e32 v135, v87
	v_add_f32_e32 v190, v190, v132
	s_waitcnt lgkmcnt(7)
	v_mfma_f32_32x32x16_bf16 v[18:33], v[182:185], v[114:117], v[18:33]
	s_add_u32 s16, s14, 0x12000
	s_mov_b32 m0, s16
	ds_read_b128 v[224:227], v234 offset:12288
	global_load_lds_dwordx4 v[248:249], off
	v_lshl_add_u64 v[236:237], v[236:237], 0, s[18:19]
	v_lshl_add_u64 v[248:249], v[248:249], 0, s[18:19]
	v_exp_f32_e32 v136, v88
	v_exp_f32_e32 v137, v89
	v_add_f32_e32 v191, v191, v133
	s_waitcnt lgkmcnt(7)
	v_mfma_f32_32x32x16_bf16 v[66:81], v[186:189], v[118:121], v[66:81]
	ds_read_b128 v[166:169], v235 offset:0
	v_exp_f32_e32 v138, v90
	v_exp_f32_e32 v139, v91
	v_cvt_pk_bf16_f32 v114, v130, v131
	s_waitcnt lgkmcnt(7)
	v_mfma_f32_32x32x16_bf16 v[50:65], v[200:203], v[118:121], v[50:65]
	ds_read_b128 v[170:173], v235 offset:4096
	v_exp_f32_e32 v140, v92
	v_exp_f32_e32 v141, v93
	v_cvt_pk_bf16_f32 v115, v132, v133
	s_waitcnt lgkmcnt(7)
	v_mfma_f32_32x32x16_bf16 v[34:49], v[204:207], v[118:121], v[34:49]
	ds_read_b128 v[178:181], v235 offset:8192
	v_exp_f32_e32 v142, v94
	v_exp_f32_e32 v143, v95
	v_add_f32_e32 v190, v190, v134
	s_waitcnt lgkmcnt(7)
	v_mfma_f32_32x32x16_bf16 v[18:33], v[208:211], v[118:121], v[18:33]
	ds_read_b128 v[182:185], v235 offset:12288
	v_exp_f32_e32 v144, v96
	v_exp_f32_e32 v145, v97
	v_add_f32_e32 v191, v191, v135
	s_waitcnt lgkmcnt(7)
	v_mfma_f32_32x32x16_bf16 v[66:81], v[212:215], v[122:125], v[66:81]
	ds_read_b128 v[186:189], v228 offset:32768
	v_exp_f32_e32 v238, v98
	v_exp_f32_e32 v239, v99
	v_cvt_pk_bf16_f32 v116, v134, v135
	s_waitcnt lgkmcnt(7)
	v_mfma_f32_32x32x16_bf16 v[50:65], v[216:219], v[122:125], v[50:65]
	ds_read_b128 v[200:203], v229 offset:32768
	v_exp_f32_e32 v240, v100
	v_exp_f32_e32 v241, v101
	v_add_f32_e32 v190, v190, v136
	s_waitcnt lgkmcnt(7)
	v_mfma_f32_32x32x16_bf16 v[34:49], v[220:223], v[122:125], v[34:49]
	ds_read_b128 v[204:207], v230 offset:32768
	v_exp_f32_e32 v242, v102
	v_exp_f32_e32 v243, v103
	v_add_f32_e32 v191, v191, v137
	s_waitcnt lgkmcnt(7)
	v_mfma_f32_32x32x16_bf16 v[18:33], v[224:227], v[122:125], v[18:33]
	ds_read_b128 v[208:211], v231 offset:32768
	v_exp_f32_e32 v244, v104
	v_exp_f32_e32 v245, v105
	v_cvt_pk_bf16_f32 v117, v136, v137
	s_waitcnt lgkmcnt(7)
	v_mfma_f32_32x32x16_bf16 v[66:81], v[166:169], v[126:129], v[66:81]
	ds_read_b128 v[212:215], v228 offset:40960
	v_exp_f32_e32 v130, v106
	v_exp_f32_e32 v131, v107
	v_add_f32_e32 v190, v190, v138
	s_waitcnt lgkmcnt(7)
	v_mfma_f32_32x32x16_bf16 v[50:65], v[170:173], v[126:129], v[50:65]
	ds_read_b128 v[216:219], v229 offset:40960
	v_exp_f32_e32 v132, v108
	v_exp_f32_e32 v133, v109
	v_add_f32_e32 v191, v191, v139
	s_waitcnt lgkmcnt(7)
	v_mfma_f32_32x32x16_bf16 v[34:49], v[178:181], v[126:129], v[34:49]
	ds_read_b128 v[220:223], v230 offset:40960
	v_exp_f32_e32 v134, v110
	v_exp_f32_e32 v135, v111
	v_add_f32_e32 v190, v190, v140
	s_waitcnt lgkmcnt(7)
	v_mfma_f32_32x32x16_bf16 v[18:33], v[182:185], v[126:129], v[18:33]
	ds_read_b128 v[224:227], v231 offset:40960
	v_exp_f32_e32 v136, v112
	v_exp_f32_e32 v137, v113
	v_add_f32_e32 v191, v191, v141
	s_waitcnt lgkmcnt(7)
	v_mfma_f32_32x32x16_bf16 v[82:97], v[186:189], v[158:161], v[0:15]
	ds_read_b128 v[166:169], v232 offset:16384
	v_cvt_pk_bf16_f32 v118, v138, v139
	v_cvt_pk_bf16_f32 v119, v140, v141
	v_add_f32_e32 v190, v190, v142
	v_add_f32_e32 v191, v191, v143
	s_waitcnt lgkmcnt(7)
	v_mfma_f32_32x32x16_bf16 v[82:97], v[200:203], v[154:157], v[82:97]
	ds_read_b128 v[170:173], v232 offset:20480
	v_cvt_pk_bf16_f32 v120, v142, v143
	v_add_f32_e32 v190, v190, v144
	v_add_f32_e32 v191, v191, v145
	v_cvt_pk_bf16_f32 v121, v144, v145
	s_waitcnt lgkmcnt(7)
	v_mfma_f32_32x32x16_bf16 v[82:97], v[204:207], v[150:153], v[82:97]
	ds_read_b128 v[178:181], v232 offset:24576
	v_add_f32_e32 v190, v190, v238
	v_add_f32_e32 v191, v191, v239
	v_cvt_pk_bf16_f32 v122, v238, v239
	v_add_f32_e32 v190, v190, v240
	s_waitcnt lgkmcnt(7)
	v_mfma_f32_32x32x16_bf16 v[82:97], v[208:211], v[146:149], v[82:97]
	ds_read_b128 v[182:185], v232 offset:28672
	v_add_f32_e32 v191, v191, v241
	v_cvt_pk_bf16_f32 v123, v240, v241
	v_add_f32_e32 v190, v190, v242
	v_add_f32_e32 v191, v191, v243
	s_waitcnt lgkmcnt(7)
	v_mfma_f32_32x32x16_bf16 v[98:113], v[212:215], v[158:161], v[0:15]
	ds_read_b128 v[186:189], v233 offset:16384
	v_cvt_pk_bf16_f32 v124, v242, v243
	v_add_f32_e32 v190, v190, v244
	v_add_f32_e32 v191, v191, v245
	v_cvt_pk_bf16_f32 v125, v244, v245
	s_waitcnt lgkmcnt(7)
	v_mfma_f32_32x32x16_bf16 v[98:113], v[216:219], v[154:157], v[98:113]
	ds_read_b128 v[200:203], v233 offset:20480
	v_add_f32_e32 v190, v190, v130
	v_add_f32_e32 v191, v191, v131
	v_cvt_pk_bf16_f32 v126, v130, v131
	v_add_f32_e32 v190, v190, v132
	s_waitcnt lgkmcnt(7)
	v_mfma_f32_32x32x16_bf16 v[98:113], v[220:223], v[150:153], v[98:113]
	ds_read_b128 v[204:207], v233 offset:24576
	v_add_f32_e32 v191, v191, v133
	v_cvt_pk_bf16_f32 v127, v132, v133
	v_add_f32_e32 v190, v190, v134
	v_add_f32_e32 v191, v191, v135
	s_waitcnt lgkmcnt(7)
	v_mfma_f32_32x32x16_bf16 v[98:113], v[224:227], v[146:149], v[98:113]
	ds_read_b128 v[208:211], v233 offset:28672
	v_cvt_pk_bf16_f32 v128, v134, v135
	v_add_f32_e32 v190, v190, v136
	v_add_f32_e32 v191, v191, v137
	v_cvt_pk_bf16_f32 v129, v136, v137
	s_waitcnt vmcnt(0) lgkmcnt(0)
	s_barrier
; template <int MODE> __device__ __forceinline__ void sm_half(f32x16& p, float& lsum, bf16x8& f0, bf16x8& f1) {
;   if (MODE != 3) {
; #pragma unroll
;   for (int r = 0; r < 16; ++r) p[r] = __builtin_amdgcn_exp2f(p[r]);
;   }
;   float s0 = 0, s1 = 0;
; #pragma unroll
;   for (int r = 0; r < 16; r += 2) { s0 += p[r]; s1 += p[r + 1]; }
;   lsum += s0 + s1;
;   u32x4 w0 = {cvtpk(p[0], p[1]), cvtpk(p[2], p[3]), cvtpk(p[4], p[5]), cvtpk(p[6], p[7])};
;   u32x4 w1 = {cvtpk(p[8], p[9]), cvtpk(p[10], p[11]), cvtpk(p[12], p[13]), cvtpk(p[14], p[15])};
;   f0 = *reinterpret_cast<bf16x8*>(&w0); f1 = *reinterpret_cast<bf16x8*>(&w1);
; template <int MODE> __device__ __forceinline__ void diff_attn_item(const bf16* __restrict__ Qb, const bf16* __restrict__ Kh, const bf16* __restrict__ Vh, ...
;     ...
;   for (int j = 0; j < NTL; ++j) {
;     const bool has1 = (j + 1 < NTL), has2 = (j + 2 < NTL);
;     if (has2 && MODE == 0) SLOADW(s_wr, (j + 2) * KVBLK);
;     bf16x8 f0, f1, f2, f3;
;     if (has1) qkt(pn0, pn1, lds + s_nxt * SHM_BUF + SHM_KV, qr, r32, hi, map, negM);
;     sm_half<MODE>(pc0, lsum, f0, f1);
;     const char* vt = lds + s_cur * SHM_BUF;
;     pv_b128(o, vt + voff[0], f0); pv_b128(o, vt + voff[1], f1);
;     sm_half<MODE>(pc1, lsum, f2, f3);
;     pv_b128(o, vt + voff[2], f2); pv_b128(o, vt + voff[3], f3);
;     asm volatile("s_waitcnt vmcnt(0)" ::: "memory");
;     __syncthreads();
;     pc0 = pn0; pc1 = pn1;
;     const int t = s_cur; s_cur = s_nxt; s_nxt = s_wr; s_wr = t;
;   }
	s_waitcnt lgkmcnt(7)
	v_mfma_f32_32x32x16_bf16 v[66:81], v[166:169], v[114:117], v[66:81]
	s_add_u32 s16, s14, 0x0
	s_mov_b32 m0, s16
	ds_read_b128 v[212:215], v234 offset:16384
	global_load_lds_dwordx4 v[246:247], off
	v_exp_f32_e32 v130, v82
	v_exp_f32_e32 v131, v83
	v_add_f32_e32 v190, v190, v130
	s_waitcnt lgkmcnt(7)
	v_mfma_f32_32x32x16_bf16 v[50:65], v[170:173], v[114:117], v[50:65]
	s_add_u32 s16, s14, 0x2000
	s_mov_b32 m0, s16
	ds_read_b128 v[216:219], v234 offset:20480
	global_load_lds_dwordx4 v[250:251], off
	v_lshl_add_u64 v[246:247], v[246:247], 0, s[18:19]
	v_lshl_add_u64 v[250:251], v[250:251], 0, s[18:19]
	v_exp_f32_e32 v132, v84
	v_exp_f32_e32 v133, v85
	v_add_f32_e32 v191, v191, v131
	s_waitcnt lgkmcnt(7)
	v_mfma_f32_32x32x16_bf16 v[34:49], v[178:181], v[114:117], v[34:49]
	s_add_u32 s16, s14, 0x14000
	s_mov_b32 m0, s16
	ds_read_b128 v[220:223], v234 offset:24576
	global_load_lds_dwordx4 v[236:237], off
	v_exp_f32_e32 v134, v86
	v_exp_f32_e32 v135, v87
	v_add_f32_e32 v190, v190, v132
	s_waitcnt lgkmcnt(7)
	v_mfma_f32_32x32x16_bf16 v[18:33], v[182:185], v[114:117], v[18:33]
	s_add_u32 s16, s14, 0x16000
	s_mov_b32 m0, s16
	ds_read_b128 v[224:227], v234 offset:28672
	global_load_lds_dwordx4 v[248:249], off
	v_lshl_add_u64 v[236:237], v[236:237], 0, s[18:19]
	v_lshl_add_u64 v[248:249], v[248:249], 0, s[18:19]
	v_exp_f32_e32 v136, v88
	v_exp_f32_e32 v137, v89
	v_add_f32_e32 v191, v191, v133
	s_waitcnt lgkmcnt(7)
	v_mfma_f32_32x32x16_bf16 v[66:81], v[186:189], v[118:121], v[66:81]
	ds_read_b128 v[166:169], v235 offset:16384
	v_exp_f32_e32 v138, v90
	v_exp_f32_e32 v139, v91
	v_cvt_pk_bf16_f32 v114, v130, v131
	s_waitcnt lgkmcnt(7)
	v_mfma_f32_32x32x16_bf16 v[50:65], v[200:203], v[118:121], v[50:65]
	ds_read_b128 v[170:173], v235 offset:20480
	v_exp_f32_e32 v140, v92
	v_exp_f32_e32 v141, v93
	v_cvt_pk_bf16_f32 v115, v132, v133
	s_waitcnt lgkmcnt(7)
	v_mfma_f32_32x32x16_bf16 v[34:49], v[204:207], v[118:121], v[34:49]
	ds_read_b128 v[178:181], v235 offset:24576
	v_exp_f32_e32 v142, v94
	v_exp_f32_e32 v143, v95
	v_add_f32_e32 v190, v190, v134
	s_waitcnt lgkmcnt(7)
	v_mfma_f32_32x32x16_bf16 v[18:33], v[208:211], v[118:121], v[18:33]
	ds_read_b128 v[182:185], v235 offset:28672
	v_exp_f32_e32 v144, v96
	v_exp_f32_e32 v145, v97
	v_add_f32_e32 v191, v191, v135
	s_waitcnt lgkmcnt(7)
	v_mfma_f32_32x32x16_bf16 v[66:81], v[212:215], v[122:125], v[66:81]
	ds_read_b128 v[186:189], v228 offset:0
	v_exp_f32_e32 v238, v98
	v_exp_f32_e32 v239, v99
	v_cvt_pk_bf16_f32 v116, v134, v135
	s_waitcnt lgkmcnt(7)
	v_mfma_f32_32x32x16_bf16 v[50:65], v[216:219], v[122:125], v[50:65]
	ds_read_b128 v[200:203], v229 offset:0
	v_exp_f32_e32 v240, v100
	v_exp_f32_e32 v241, v101
	v_add_f32_e32 v190, v190, v136
	s_waitcnt lgkmcnt(7)
	v_mfma_f32_32x32x16_bf16 v[34:49], v[220:223], v[122:125], v[34:49]
	ds_read_b128 v[204:207], v230 offset:0
	v_exp_f32_e32 v242, v102
	v_exp_f32_e32 v243, v103
	v_add_f32_e32 v191, v191, v137
	s_waitcnt lgkmcnt(7)
	v_mfma_f32_32x32x16_bf16 v[18:33], v[224:227], v[122:125], v[18:33]
	ds_read_b128 v[208:211], v231 offset:0
	v_exp_f32_e32 v244, v104
	v_exp_f32_e32 v245, v105
	v_cvt_pk_bf16_f32 v117, v136, v137
	s_waitcnt lgkmcnt(7)
	v_mfma_f32_32x32x16_bf16 v[66:81], v[166:169], v[126:129], v[66:81]
	ds_read_b128 v[212:215], v228 offset:8192
	v_exp_f32_e32 v130, v106
	v_exp_f32_e32 v131, v107
	v_add_f32_e32 v190, v190, v138
	s_waitcnt lgkmcnt(7)
	v_mfma_f32_32x32x16_bf16 v[50:65], v[170:173], v[126:129], v[50:65]
	ds_read_b128 v[216:219], v229 offset:8192
	v_exp_f32_e32 v132, v108
	v_exp_f32_e32 v133, v109
	v_add_f32_e32 v191, v191, v139
	s_waitcnt lgkmcnt(7)
	v_mfma_f32_32x32x16_bf16 v[34:49], v[178:181], v[126:129], v[34:49]
	ds_read_b128 v[220:223], v230 offset:8192
	v_exp_f32_e32 v134, v110
	v_exp_f32_e32 v135, v111
	v_add_f32_e32 v190, v190, v140
	s_waitcnt lgkmcnt(7)
	v_mfma_f32_32x32x16_bf16 v[18:33], v[182:185], v[126:129], v[18:33]
	ds_read_b128 v[224:227], v231 offset:8192
	v_exp_f32_e32 v136, v112
	v_exp_f32_e32 v137, v113
	v_add_f32_e32 v191, v191, v141
	s_waitcnt lgkmcnt(7)
	v_mfma_f32_32x32x16_bf16 v[82:97], v[186:189], v[158:161], v[0:15]
	ds_read_b128 v[166:169], v232 offset:32768
	v_cvt_pk_bf16_f32 v118, v138, v139
	v_cvt_pk_bf16_f32 v119, v140, v141
	v_add_f32_e32 v190, v190, v142
	v_add_f32_e32 v191, v191, v143
	s_waitcnt lgkmcnt(7)
	v_mfma_f32_32x32x16_bf16 v[82:97], v[200:203], v[154:157], v[82:97]
	ds_read_b128 v[170:173], v232 offset:36864
	v_cvt_pk_bf16_f32 v120, v142, v143
	v_add_f32_e32 v190, v190, v144
	v_add_f32_e32 v191, v191, v145
	v_cvt_pk_bf16_f32 v121, v144, v145
	s_waitcnt lgkmcnt(7)
	v_mfma_f32_32x32x16_bf16 v[82:97], v[204:207], v[150:153], v[82:97]
	ds_read_b128 v[178:181], v232 offset:40960
	v_add_f32_e32 v190, v190, v238
	v_add_f32_e32 v191, v191, v239
	v_cvt_pk_bf16_f32 v122, v238, v239
	v_add_f32_e32 v190, v190, v240
	s_waitcnt lgkmcnt(7)
	v_mfma_f32_32x32x16_bf16 v[82:97], v[208:211], v[146:149], v[82:97]
	ds_read_b128 v[182:185], v232 offset:45056
	v_add_f32_e32 v191, v191, v241
	v_cvt_pk_bf16_f32 v123, v240, v241
	v_add_f32_e32 v190, v190, v242
	v_add_f32_e32 v191, v191, v243
	s_waitcnt lgkmcnt(7)
	v_mfma_f32_32x32x16_bf16 v[98:113], v[212:215], v[158:161], v[0:15]
	ds_read_b128 v[186:189], v233 offset:32768
	v_cvt_pk_bf16_f32 v124, v242, v243
	v_add_f32_e32 v190, v190, v244
	v_add_f32_e32 v191, v191, v245
	v_cvt_pk_bf16_f32 v125, v244, v245
	s_waitcnt lgkmcnt(7)
	v_mfma_f32_32x32x16_bf16 v[98:113], v[216:219], v[154:157], v[98:113]
	ds_read_b128 v[200:203], v233 offset:36864
	v_add_f32_e32 v190, v190, v130
	v_add_f32_e32 v191, v191, v131
	v_cvt_pk_bf16_f32 v126, v130, v131
	v_add_f32_e32 v190, v190, v132
	s_waitcnt lgkmcnt(7)
	v_mfma_f32_32x32x16_bf16 v[98:113], v[220:223], v[150:153], v[98:113]
	ds_read_b128 v[204:207], v233 offset:40960
	v_add_f32_e32 v191, v191, v133
	v_cvt_pk_bf16_f32 v127, v132, v133
	v_add_f32_e32 v190, v190, v134
	v_add_f32_e32 v191, v191, v135
	s_waitcnt lgkmcnt(7)
	v_mfma_f32_32x32x16_bf16 v[98:113], v[224:227], v[146:149], v[98:113]
	ds_read_b128 v[208:211], v233 offset:45056
	v_cvt_pk_bf16_f32 v128, v134, v135
	v_add_f32_e32 v190, v190, v136
	v_add_f32_e32 v191, v191, v137
	v_cvt_pk_bf16_f32 v129, v136, v137
	s_waitcnt vmcnt(0) lgkmcnt(0)
	s_barrier
; template <int MODE> __device__ __forceinline__ void sm_half(f32x16& p, float& lsum, bf16x8& f0, bf16x8& f1) {
;   if (MODE != 3) {
; #pragma unroll
;   for (int r = 0; r < 16; ++r) p[r] = __builtin_amdgcn_exp2f(p[r]);
;   }
;   float s0 = 0, s1 = 0;
; #pragma unroll
;   for (int r = 0; r < 16; r += 2) { s0 += p[r]; s1 += p[r + 1]; }
;   lsum += s0 + s1;
;   u32x4 w0 = {cvtpk(p[0], p[1]), cvtpk(p[2], p[3]), cvtpk(p[4], p[5]), cvtpk(p[6], p[7])};
;   u32x4 w1 = {cvtpk(p[8], p[9]), cvtpk(p[10], p[11]), cvtpk(p[12], p[13]), cvtpk(p[14], p[15])};
;   f0 = *reinterpret_cast<bf16x8*>(&w0); f1 = *reinterpret_cast<bf16x8*>(&w1);
; template <int MODE> __device__ __forceinline__ void diff_attn_item(const bf16* __restrict__ Qb, const bf16* __restrict__ Kh, const bf16* __restrict__ Vh, ...
;     ...
;   for (int j = 0; j < NTL; ++j) {
;     const bool has1 = (j + 1 < NTL), has2 = (j + 2 < NTL);
;     if (has2 && MODE == 0) SLOADW(s_wr, (j + 2) * KVBLK);
;     bf16x8 f0, f1, f2, f3;
;     if (has1) qkt(pn0, pn1, lds + s_nxt * SHM_BUF + SHM_KV, qr, r32, hi, map, negM);
;     sm_half<MODE>(pc0, lsum, f0, f1);
;     const char* vt = lds + s_cur * SHM_BUF;
;     pv_b128(o, vt + voff[0], f0); pv_b128(o, vt + voff[1], f1);
;     sm_half<MODE>(pc1, lsum, f2, f3);
;     pv_b128(o, vt + voff[2], f2); pv_b128(o, vt + voff[3], f3);
;     asm volatile("s_waitcnt vmcnt(0)" ::: "memory");
;     __syncthreads();
;     pc0 = pn0; pc1 = pn1;
;     const int t = s_cur; s_cur = s_nxt; s_nxt = s_wr; s_wr = t;
;   }
	s_waitcnt lgkmcnt(7)
	v_mfma_f32_32x32x16_bf16 v[66:81], v[166:169], v[114:117], v[66:81]
	s_add_u32 s16, s14, 0x4000
	s_mov_b32 m0, s16
	ds_read_b128 v[212:215], v234 offset:32768
	global_load_lds_dwordx4 v[246:247], off
	v_exp_f32_e32 v130, v82
	v_exp_f32_e32 v131, v83
	v_add_f32_e32 v190, v190, v130
	s_waitcnt lgkmcnt(7)
	v_mfma_f32_32x32x16_bf16 v[50:65], v[170:173], v[114:117], v[50:65]
	s_add_u32 s16, s14, 0x6000
	s_mov_b32 m0, s16
	ds_read_b128 v[216:219], v234 offset:36864
	global_load_lds_dwordx4 v[250:251], off
	v_lshl_add_u64 v[246:247], v[246:247], 0, s[18:19]
	v_lshl_add_u64 v[250:251], v[250:251], 0, s[18:19]
	v_exp_f32_e32 v132, v84
	v_exp_f32_e32 v133, v85
	v_add_f32_e32 v191, v191, v131
	s_waitcnt lgkmcnt(7)
	v_mfma_f32_32x32x16_bf16 v[34:49], v[178:181], v[114:117], v[34:49]
	s_add_u32 s16, s14, 0xc000
	s_mov_b32 m0, s16
	ds_read_b128 v[220:223], v234 offset:40960
	global_load_lds_dwordx4 v[236:237], off
	v_exp_f32_e32 v134, v86
	v_exp_f32_e32 v135, v87
	v_add_f32_e32 v190, v190, v132
	s_waitcnt lgkmcnt(7)
	v_mfma_f32_32x32x16_bf16 v[18:33], v[182:185], v[114:117], v[18:33]
	s_add_u32 s16, s14, 0xe000
	s_mov_b32 m0, s16
	ds_read_b128 v[224:227], v234 offset:45056
	global_load_lds_dwordx4 v[248:249], off
	v_lshl_add_u64 v[236:237], v[236:237], 0, s[18:19]
	v_lshl_add_u64 v[248:249], v[248:249], 0, s[18:19]
	v_exp_f32_e32 v136, v88
	v_exp_f32_e32 v137, v89
	v_add_f32_e32 v191, v191, v133
	s_waitcnt lgkmcnt(7)
	v_mfma_f32_32x32x16_bf16 v[66:81], v[186:189], v[118:121], v[66:81]
	ds_read_b128 v[166:169], v235 offset:32768
	v_exp_f32_e32 v138, v90
	v_exp_f32_e32 v139, v91
	v_cvt_pk_bf16_f32 v114, v130, v131
	s_waitcnt lgkmcnt(7)
	v_mfma_f32_32x32x16_bf16 v[50:65], v[200:203], v[118:121], v[50:65]
	ds_read_b128 v[170:173], v235 offset:36864
	v_exp_f32_e32 v140, v92
	v_exp_f32_e32 v141, v93
	v_cvt_pk_bf16_f32 v115, v132, v133
	s_waitcnt lgkmcnt(7)
	v_mfma_f32_32x32x16_bf16 v[34:49], v[204:207], v[118:121], v[34:49]
	ds_read_b128 v[178:181], v235 offset:40960
	v_exp_f32_e32 v142, v94
	v_exp_f32_e32 v143, v95
	v_add_f32_e32 v190, v190, v134
	s_waitcnt lgkmcnt(7)
	v_mfma_f32_32x32x16_bf16 v[18:33], v[208:211], v[118:121], v[18:33]
	ds_read_b128 v[182:185], v235 offset:45056
	v_exp_f32_e32 v144, v96
	v_exp_f32_e32 v145, v97
	v_add_f32_e32 v191, v191, v135
	s_waitcnt lgkmcnt(7)
	v_mfma_f32_32x32x16_bf16 v[66:81], v[212:215], v[122:125], v[66:81]
	ds_read_b128 v[186:189], v228 offset:16384
	v_exp_f32_e32 v238, v98
	v_exp_f32_e32 v239, v99
	v_cvt_pk_bf16_f32 v116, v134, v135
	s_waitcnt lgkmcnt(7)
	v_mfma_f32_32x32x16_bf16 v[50:65], v[216:219], v[122:125], v[50:65]
	ds_read_b128 v[200:203], v229 offset:16384
	v_exp_f32_e32 v240, v100
	v_exp_f32_e32 v241, v101
	v_add_f32_e32 v190, v190, v136
	s_waitcnt lgkmcnt(7)
	v_mfma_f32_32x32x16_bf16 v[34:49], v[220:223], v[122:125], v[34:49]
	ds_read_b128 v[204:207], v230 offset:16384
	v_exp_f32_e32 v242, v102
	v_exp_f32_e32 v243, v103
	v_add_f32_e32 v191, v191, v137
	s_waitcnt lgkmcnt(7)
	v_mfma_f32_32x32x16_bf16 v[18:33], v[224:227], v[122:125], v[18:33]
	ds_read_b128 v[208:211], v231 offset:16384
	v_exp_f32_e32 v244, v104
	v_exp_f32_e32 v245, v105
	v_cvt_pk_bf16_f32 v117, v136, v137
	s_waitcnt lgkmcnt(7)
	v_mfma_f32_32x32x16_bf16 v[66:81], v[166:169], v[126:129], v[66:81]
	ds_read_b128 v[212:215], v228 offset:24576
	v_exp_f32_e32 v130, v106
	v_exp_f32_e32 v131, v107
	v_add_f32_e32 v190, v190, v138
	s_waitcnt lgkmcnt(7)
	v_mfma_f32_32x32x16_bf16 v[50:65], v[170:173], v[126:129], v[50:65]
	ds_read_b128 v[216:219], v229 offset:24576
	v_exp_f32_e32 v132, v108
	v_exp_f32_e32 v133, v109
	v_add_f32_e32 v191, v191, v139
	s_waitcnt lgkmcnt(7)
	v_mfma_f32_32x32x16_bf16 v[34:49], v[178:181], v[126:129], v[34:49]
	ds_read_b128 v[220:223], v230 offset:24576
	v_exp_f32_e32 v134, v110
	v_exp_f32_e32 v135, v111
	v_add_f32_e32 v190, v190, v140
	s_waitcnt lgkmcnt(7)
	v_mfma_f32_32x32x16_bf16 v[18:33], v[182:185], v[126:129], v[18:33]
	ds_read_b128 v[224:227], v231 offset:24576
	v_exp_f32_e32 v136, v112
	v_exp_f32_e32 v137, v113
	v_add_f32_e32 v191, v191, v141
	s_waitcnt lgkmcnt(7)
	v_mfma_f32_32x32x16_bf16 v[82:97], v[186:189], v[158:161], v[0:15]
	ds_read_b128 v[166:169], v232 offset:0
	v_cvt_pk_bf16_f32 v118, v138, v139
	v_cvt_pk_bf16_f32 v119, v140, v141
	v_add_f32_e32 v190, v190, v142
	v_add_f32_e32 v191, v191, v143
	s_waitcnt lgkmcnt(7)
	v_mfma_f32_32x32x16_bf16 v[82:97], v[200:203], v[154:157], v[82:97]
	ds_read_b128 v[170:173], v232 offset:4096
	v_cvt_pk_bf16_f32 v120, v142, v143
	v_add_f32_e32 v190, v190, v144
	v_add_f32_e32 v191, v191, v145
	v_cvt_pk_bf16_f32 v121, v144, v145
	s_waitcnt lgkmcnt(7)
	v_mfma_f32_32x32x16_bf16 v[82:97], v[204:207], v[150:153], v[82:97]
	ds_read_b128 v[178:181], v232 offset:8192
	v_add_f32_e32 v190, v190, v238
	v_add_f32_e32 v191, v191, v239
	v_cvt_pk_bf16_f32 v122, v238, v239
	v_add_f32_e32 v190, v190, v240
	s_waitcnt lgkmcnt(7)
	v_mfma_f32_32x32x16_bf16 v[82:97], v[208:211], v[146:149], v[82:97]
	ds_read_b128 v[182:185], v232 offset:12288
	v_add_f32_e32 v191, v191, v241
	v_cvt_pk_bf16_f32 v123, v240, v241
	v_add_f32_e32 v190, v190, v242
	v_add_f32_e32 v191, v191, v243
	s_waitcnt lgkmcnt(7)
	v_mfma_f32_32x32x16_bf16 v[98:113], v[212:215], v[158:161], v[0:15]
	ds_read_b128 v[186:189], v233 offset:0
	v_cvt_pk_bf16_f32 v124, v242, v243
	v_add_f32_e32 v190, v190, v244
	v_add_f32_e32 v191, v191, v245
	v_cvt_pk_bf16_f32 v125, v244, v245
	s_waitcnt lgkmcnt(7)
	v_mfma_f32_32x32x16_bf16 v[98:113], v[216:219], v[154:157], v[98:113]
	ds_read_b128 v[200:203], v233 offset:4096
	v_add_f32_e32 v190, v190, v130
	v_add_f32_e32 v191, v191, v131
	v_cvt_pk_bf16_f32 v126, v130, v131
	v_add_f32_e32 v190, v190, v132
	s_waitcnt lgkmcnt(7)
	v_mfma_f32_32x32x16_bf16 v[98:113], v[220:223], v[150:153], v[98:113]
	ds_read_b128 v[204:207], v233 offset:8192
	v_add_f32_e32 v191, v191, v133
	v_cvt_pk_bf16_f32 v127, v132, v133
	v_add_f32_e32 v190, v190, v134
	v_add_f32_e32 v191, v191, v135
	s_waitcnt lgkmcnt(7)
	v_mfma_f32_32x32x16_bf16 v[98:113], v[224:227], v[146:149], v[98:113]
	ds_read_b128 v[208:211], v233 offset:12288
	v_cvt_pk_bf16_f32 v128, v134, v135
	v_add_f32_e32 v190, v190, v136
	v_add_f32_e32 v191, v191, v137
	v_cvt_pk_bf16_f32 v129, v136, v137
	s_waitcnt vmcnt(0) lgkmcnt(0)
	s_sub_u32 s15, s15, 1
	s_cmp_lg_u32 s15, 0
	s_cbranch_scc1 .Lda0_loop
; template <int MODE> __device__ __forceinline__ void sm_half(f32x16& p, float& lsum, bf16x8& f0, bf16x8& f1) {
;   if (MODE != 3) {
; #pragma unroll
;   for (int r = 0; r < 16; ++r) p[r] = __builtin_amdgcn_exp2f(p[r]);
;   }
;   float s0 = 0, s1 = 0;
; #pragma unroll
;   for (int r = 0; r < 16; r += 2) { s0 += p[r]; s1 += p[r + 1]; }
;   lsum += s0 + s1;
;   u32x4 w0 = {cvtpk(p[0], p[1]), cvtpk(p[2], p[3]), cvtpk(p[4], p[5]), cvtpk(p[6], p[7])};
;   u32x4 w1 = {cvtpk(p[8], p[9]), cvtpk(p[10], p[11]), cvtpk(p[12], p[13]), cvtpk(p[14], p[15])};
;   f0 = *reinterpret_cast<bf16x8*>(&w0); f1 = *reinterpret_cast<bf16x8*>(&w1);
; template <int MODE> __device__ __forceinline__ void diff_attn_item(const bf16* __restrict__ Qb, const bf16* __restrict__ Kh, const bf16* __restrict__ Vh, ...
;     ...
;   for (int j = 0; j < NTL; ++j) {
;     const bool has1 = (j + 1 < NTL), has2 = (j + 2 < NTL);
;     if (has2 && MODE == 0) SLOADW(s_wr, (j + 2) * KVBLK);
;     bf16x8 f0, f1, f2, f3;
;     if (has1) qkt(pn0, pn1, lds + s_nxt * SHM_BUF + SHM_KV, qr, r32, hi, map, negM);
;     sm_half<MODE>(pc0, lsum, f0, f1);
;     const char* vt = lds + s_cur * SHM_BUF;
;     pv_b128(o, vt + voff[0], f0); pv_b128(o, vt + voff[1], f1);
;     sm_half<MODE>(pc1, lsum, f2, f3);
;     pv_b128(o, vt + voff[2], f2); pv_b128(o, vt + voff[3], f3);
;     asm volatile("s_waitcnt vmcnt(0)" ::: "memory");
;     __syncthreads();
;     pc0 = pn0; pc1 = pn1;
;     const int t = s_cur; s_cur = s_nxt; s_nxt = s_wr; s_wr = t;
;   }
	s_barrier
	s_waitcnt lgkmcnt(7)
	v_mfma_f32_32x32x16_bf16 v[66:81], v[166:169], v[114:117], v[66:81]
	s_add_u32 s16, s14, 0x8000
	s_mov_b32 m0, s16
	ds_read_b128 v[212:215], v234 offset:0
	global_load_lds_dwordx4 v[246:247], off
	v_exp_f32_e32 v130, v82
	v_exp_f32_e32 v131, v83
	v_add_f32_e32 v190, v190, v130
	s_waitcnt lgkmcnt(7)
	v_mfma_f32_32x32x16_bf16 v[50:65], v[170:173], v[114:117], v[50:65]
	s_add_u32 s16, s14, 0xa000
	s_mov_b32 m0, s16
	ds_read_b128 v[216:219], v234 offset:4096
	global_load_lds_dwordx4 v[250:251], off
	v_lshl_add_u64 v[246:247], v[246:247], 0, s[18:19]
	v_lshl_add_u64 v[250:251], v[250:251], 0, s[18:19]
	v_exp_f32_e32 v132, v84
	v_exp_f32_e32 v133, v85
	v_add_f32_e32 v191, v191, v131
	s_waitcnt lgkmcnt(7)
	v_mfma_f32_32x32x16_bf16 v[34:49], v[178:181], v[114:117], v[34:49]
	s_add_u32 s16, s14, 0x10000
	s_mov_b32 m0, s16
	ds_read_b128 v[220:223], v234 offset:8192
	global_load_lds_dwordx4 v[236:237], off
	v_exp_f32_e32 v134, v86
	v_exp_f32_e32 v135, v87
	v_add_f32_e32 v190, v190, v132
	s_waitcnt lgkmcnt(7)
	v_mfma_f32_32x32x16_bf16 v[18:33], v[182:185], v[114:117], v[18:33]
	s_add_u32 s16, s14, 0x12000
	s_mov_b32 m0, s16
	ds_read_b128 v[224:227], v234 offset:12288
	global_load_lds_dwordx4 v[248:249], off
	v_lshl_add_u64 v[236:237], v[236:237], 0, s[18:19]
	v_lshl_add_u64 v[248:249], v[248:249], 0, s[18:19]
	v_exp_f32_e32 v136, v88
	v_exp_f32_e32 v137, v89
	v_add_f32_e32 v191, v191, v133
	s_waitcnt lgkmcnt(7)
	v_mfma_f32_32x32x16_bf16 v[66:81], v[186:189], v[118:121], v[66:81]
	ds_read_b128 v[166:169], v235 offset:0
	v_exp_f32_e32 v138, v90
	v_exp_f32_e32 v139, v91
	v_cvt_pk_bf16_f32 v114, v130, v131
	s_waitcnt lgkmcnt(7)
	v_mfma_f32_32x32x16_bf16 v[50:65], v[200:203], v[118:121], v[50:65]
	ds_read_b128 v[170:173], v235 offset:4096
	v_exp_f32_e32 v140, v92
	v_exp_f32_e32 v141, v93
	v_cvt_pk_bf16_f32 v115, v132, v133
	s_waitcnt lgkmcnt(7)
	v_mfma_f32_32x32x16_bf16 v[34:49], v[204:207], v[118:121], v[34:49]
	ds_read_b128 v[178:181], v235 offset:8192
	v_exp_f32_e32 v142, v94
	v_exp_f32_e32 v143, v95
	v_add_f32_e32 v190, v190, v134
	s_waitcnt lgkmcnt(7)
	v_mfma_f32_32x32x16_bf16 v[18:33], v[208:211], v[118:121], v[18:33]
	ds_read_b128 v[182:185], v235 offset:12288
	v_exp_f32_e32 v144, v96
	v_exp_f32_e32 v145, v97
	v_add_f32_e32 v191, v191, v135
	s_waitcnt lgkmcnt(7)
	v_mfma_f32_32x32x16_bf16 v[66:81], v[212:215], v[122:125], v[66:81]
	ds_read_b128 v[186:189], v228 offset:32768
	v_exp_f32_e32 v238, v98
	v_exp_f32_e32 v239, v99
	v_cvt_pk_bf16_f32 v116, v134, v135
	s_waitcnt lgkmcnt(7)
	v_mfma_f32_32x32x16_bf16 v[50:65], v[216:219], v[122:125], v[50:65]
	ds_read_b128 v[200:203], v229 offset:32768
	v_exp_f32_e32 v240, v100
	v_exp_f32_e32 v241, v101
	v_add_f32_e32 v190, v190, v136
	s_waitcnt lgkmcnt(7)
	v_mfma_f32_32x32x16_bf16 v[34:49], v[220:223], v[122:125], v[34:49]
	ds_read_b128 v[204:207], v230 offset:32768
	v_exp_f32_e32 v242, v102
	v_exp_f32_e32 v243, v103
	v_add_f32_e32 v191, v191, v137
	s_waitcnt lgkmcnt(7)
	v_mfma_f32_32x32x16_bf16 v[18:33], v[224:227], v[122:125], v[18:33]
	ds_read_b128 v[208:211], v231 offset:32768
	v_exp_f32_e32 v244, v104
	v_exp_f32_e32 v245, v105
	v_cvt_pk_bf16_f32 v117, v136, v137
	s_waitcnt lgkmcnt(7)
	v_mfma_f32_32x32x16_bf16 v[66:81], v[166:169], v[126:129], v[66:81]
	ds_read_b128 v[212:215], v228 offset:40960
	v_exp_f32_e32 v130, v106
	v_exp_f32_e32 v131, v107
	v_add_f32_e32 v190, v190, v138
	s_waitcnt lgkmcnt(7)
	v_mfma_f32_32x32x16_bf16 v[50:65], v[170:173], v[126:129], v[50:65]
	ds_read_b128 v[216:219], v229 offset:40960
	v_exp_f32_e32 v132, v108
	v_exp_f32_e32 v133, v109
	v_add_f32_e32 v191, v191, v139
	s_waitcnt lgkmcnt(7)
	v_mfma_f32_32x32x16_bf16 v[34:49], v[178:181], v[126:129], v[34:49]
	ds_read_b128 v[220:223], v230 offset:40960
	v_exp_f32_e32 v134, v110
	v_exp_f32_e32 v135, v111
	v_add_f32_e32 v190, v190, v140
	s_waitcnt lgkmcnt(7)
	v_mfma_f32_32x32x16_bf16 v[18:33], v[182:185], v[126:129], v[18:33]
	ds_read_b128 v[224:227], v231 offset:40960
	v_exp_f32_e32 v136, v112
	v_exp_f32_e32 v137, v113
	v_add_f32_e32 v191, v191, v141
	s_waitcnt lgkmcnt(7)
	v_mfma_f32_32x32x16_bf16 v[82:97], v[186:189], v[158:161], v[0:15]
	ds_read_b128 v[166:169], v232 offset:16384
	v_cvt_pk_bf16_f32 v118, v138, v139
	v_cvt_pk_bf16_f32 v119, v140, v141
	v_add_f32_e32 v190, v190, v142
	v_add_f32_e32 v191, v191, v143
	s_waitcnt lgkmcnt(7)
	v_mfma_f32_32x32x16_bf16 v[82:97], v[200:203], v[154:157], v[82:97]
	ds_read_b128 v[170:173], v232 offset:20480
	v_cvt_pk_bf16_f32 v120, v142, v143
	v_add_f32_e32 v190, v190, v144
	v_add_f32_e32 v191, v191, v145
	v_cvt_pk_bf16_f32 v121, v144, v145
	s_waitcnt lgkmcnt(7)
	v_mfma_f32_32x32x16_bf16 v[82:97], v[204:207], v[150:153], v[82:97]
	ds_read_b128 v[178:181], v232 offset:24576
	v_add_f32_e32 v190, v190, v238
	v_add_f32_e32 v191, v191, v239
	v_cvt_pk_bf16_f32 v122, v238, v239
	v_add_f32_e32 v190, v190, v240
	s_waitcnt lgkmcnt(7)
	v_mfma_f32_32x32x16_bf16 v[82:97], v[208:211], v[146:149], v[82:97]
	ds_read_b128 v[182:185], v232 offset:28672
	v_add_f32_e32 v191, v191, v241
	v_cvt_pk_bf16_f32 v123, v240, v241
	v_add_f32_e32 v190, v190, v242
	v_add_f32_e32 v191, v191, v243
	s_waitcnt lgkmcnt(7)
	v_mfma_f32_32x32x16_bf16 v[98:113], v[212:215], v[158:161], v[0:15]
	ds_read_b128 v[186:189], v233 offset:16384
	v_cvt_pk_bf16_f32 v124, v242, v243
	v_add_f32_e32 v190, v190, v244
	v_add_f32_e32 v191, v191, v245
	v_cvt_pk_bf16_f32 v125, v244, v245
	s_waitcnt lgkmcnt(7)
	v_mfma_f32_32x32x16_bf16 v[98:113], v[216:219], v[154:157], v[98:113]
	ds_read_b128 v[200:203], v233 offset:20480
	v_add_f32_e32 v190, v190, v130
	v_add_f32_e32 v191, v191, v131
	v_cvt_pk_bf16_f32 v126, v130, v131
	v_add_f32_e32 v190, v190, v132
	s_waitcnt lgkmcnt(7)
	v_mfma_f32_32x32x16_bf16 v[98:113], v[220:223], v[150:153], v[98:113]
	ds_read_b128 v[204:207], v233 offset:24576
	v_add_f32_e32 v191, v191, v133
	v_cvt_pk_bf16_f32 v127, v132, v133
	v_add_f32_e32 v190, v190, v134
	v_add_f32_e32 v191, v191, v135
	s_waitcnt lgkmcnt(7)
	v_mfma_f32_32x32x16_bf16 v[98:113], v[224:227], v[146:149], v[98:113]
	ds_read_b128 v[208:211], v233 offset:28672
	v_cvt_pk_bf16_f32 v128, v134, v135
	v_add_f32_e32 v190, v190, v136
	v_add_f32_e32 v191, v191, v137
	v_cvt_pk_bf16_f32 v129, v136, v137
	s_waitcnt vmcnt(0) lgkmcnt(0)
	s_barrier
; template <int MODE> __device__ __forceinline__ void sm_half(f32x16& p, float& lsum, bf16x8& f0, bf16x8& f1) {
;   if (MODE != 3) {
; #pragma unroll
;   for (int r = 0; r < 16; ++r) p[r] = __builtin_amdgcn_exp2f(p[r]);
;   }
;   float s0 = 0, s1 = 0;
; #pragma unroll
;   for (int r = 0; r < 16; r += 2) { s0 += p[r]; s1 += p[r + 1]; }
;   lsum += s0 + s1;
;   u32x4 w0 = {cvtpk(p[0], p[1]), cvtpk(p[2], p[3]), cvtpk(p[4], p[5]), cvtpk(p[6], p[7])};
;   u32x4 w1 = {cvtpk(p[8], p[9]), cvtpk(p[10], p[11]), cvtpk(p[12], p[13]), cvtpk(p[14], p[15])};
;   f0 = *reinterpret_cast<bf16x8*>(&w0); f1 = *reinterpret_cast<bf16x8*>(&w1);
; template <int MODE> __device__ __forceinline__ void diff_attn_item(const bf16* __restrict__ Qb, const bf16* __restrict__ Kh, const bf16* __restrict__ Vh, ...
;     ...
;   for (int j = 0; j < NTL; ++j) {
;     const bool has1 = (j + 1 < NTL), has2 = (j + 2 < NTL);
;     if (has2 && MODE == 0) SLOADW(s_wr, (j + 2) * KVBLK);
;     bf16x8 f0, f1, f2, f3;
;     if (has1) qkt(pn0, pn1, lds + s_nxt * SHM_BUF + SHM_KV, qr, r32, hi, map, negM);
;     sm_half<MODE>(pc0, lsum, f0, f1);
;     const char* vt = lds + s_cur * SHM_BUF;
;     pv_b128(o, vt + voff[0], f0); pv_b128(o, vt + voff[1], f1);
;     sm_half<MODE>(pc1, lsum, f2, f3);
;     pv_b128(o, vt + voff[2], f2); pv_b128(o, vt + voff[3], f3);
;     asm volatile("s_waitcnt vmcnt(0)" ::: "memory");
;     __syncthreads();
;     pc0 = pn0; pc1 = pn1;
;     const int t = s_cur; s_cur = s_nxt; s_nxt = s_wr; s_wr = t;
;   }
	s_waitcnt lgkmcnt(7)
	v_mfma_f32_32x32x16_bf16 v[66:81], v[166:169], v[114:117], v[66:81]
	s_add_u32 s16, s14, 0x0
	s_mov_b32 m0, s16
	ds_read_b128 v[212:215], v234 offset:16384
	global_load_lds_dwordx4 v[246:247], off
	v_exp_f32_e32 v130, v82
	v_exp_f32_e32 v131, v83
	v_add_f32_e32 v190, v190, v130
	s_waitcnt lgkmcnt(7)
	v_mfma_f32_32x32x16_bf16 v[50:65], v[170:173], v[114:117], v[50:65]
	s_add_u32 s16, s14, 0x2000
	s_mov_b32 m0, s16
	ds_read_b128 v[216:219], v234 offset:20480
	global_load_lds_dwordx4 v[250:251], off
	v_lshl_add_u64 v[246:247], v[246:247], 0, s[18:19]
	v_lshl_add_u64 v[250:251], v[250:251], 0, s[18:19]
	v_exp_f32_e32 v132, v84
	v_exp_f32_e32 v133, v85
	v_add_f32_e32 v191, v191, v131
	s_waitcnt lgkmcnt(7)
	v_mfma_f32_32x32x16_bf16 v[34:49], v[178:181], v[114:117], v[34:49]
	s_add_u32 s16, s14, 0x14000
	s_mov_b32 m0, s16
	ds_read_b128 v[220:223], v234 offset:24576
	global_load_lds_dwordx4 v[236:237], off
	v_exp_f32_e32 v134, v86
	v_exp_f32_e32 v135, v87
	v_add_f32_e32 v190, v190, v132
	s_waitcnt lgkmcnt(7)
	v_mfma_f32_32x32x16_bf16 v[18:33], v[182:185], v[114:117], v[18:33]
	s_add_u32 s16, s14, 0x16000
	s_mov_b32 m0, s16
	ds_read_b128 v[224:227], v234 offset:28672
	global_load_lds_dwordx4 v[248:249], off
	v_lshl_add_u64 v[236:237], v[236:237], 0, s[18:19]
	v_lshl_add_u64 v[248:249], v[248:249], 0, s[18:19]
	v_exp_f32_e32 v136, v88
	v_exp_f32_e32 v137, v89
	v_add_f32_e32 v191, v191, v133
	s_waitcnt lgkmcnt(7)
	v_mfma_f32_32x32x16_bf16 v[66:81], v[186:189], v[118:121], v[66:81]
	ds_read_b128 v[166:169], v235 offset:16384
	v_exp_f32_e32 v138, v90
	v_exp_f32_e32 v139, v91
	v_cvt_pk_bf16_f32 v114, v130, v131
	s_waitcnt lgkmcnt(7)
	v_mfma_f32_32x32x16_bf16 v[50:65], v[200:203], v[118:121], v[50:65]
	ds_read_b128 v[170:173], v235 offset:20480
	v_exp_f32_e32 v140, v92
	v_exp_f32_e32 v141, v93
	v_cvt_pk_bf16_f32 v115, v132, v133
	s_waitcnt lgkmcnt(7)
	v_mfma_f32_32x32x16_bf16 v[34:49], v[204:207], v[118:121], v[34:49]
	ds_read_b128 v[178:181], v235 offset:24576
	v_exp_f32_e32 v142, v94
	v_exp_f32_e32 v143, v95
	v_add_f32_e32 v190, v190, v134
	s_waitcnt lgkmcnt(7)
	v_mfma_f32_32x32x16_bf16 v[18:33], v[208:211], v[118:121], v[18:33]
	ds_read_b128 v[182:185], v235 offset:28672
	v_exp_f32_e32 v144, v96
	v_exp_f32_e32 v145, v97
	v_add_f32_e32 v191, v191, v135
	s_waitcnt lgkmcnt(7)
	v_mfma_f32_32x32x16_bf16 v[66:81], v[212:215], v[122:125], v[66:81]
	ds_read_b128 v[186:189], v228 offset:0
	v_exp_f32_e32 v238, v98
	v_exp_f32_e32 v239, v99
	v_cvt_pk_bf16_f32 v116, v134, v135
	s_waitcnt lgkmcnt(7)
	v_mfma_f32_32x32x16_bf16 v[50:65], v[216:219], v[122:125], v[50:65]
	ds_read_b128 v[200:203], v229 offset:0
	v_exp_f32_e32 v240, v100
	v_exp_f32_e32 v241, v101
	v_add_f32_e32 v190, v190, v136
	s_waitcnt lgkmcnt(7)
	v_mfma_f32_32x32x16_bf16 v[34:49], v[220:223], v[122:125], v[34:49]
	ds_read_b128 v[204:207], v230 offset:0
	v_exp_f32_e32 v242, v102
	v_exp_f32_e32 v243, v103
	v_add_f32_e32 v191, v191, v137
	s_waitcnt lgkmcnt(7)
	v_mfma_f32_32x32x16_bf16 v[18:33], v[224:227], v[122:125], v[18:33]
	ds_read_b128 v[208:211], v231 offset:0
	v_exp_f32_e32 v244, v104
	v_exp_f32_e32 v245, v105
	v_cvt_pk_bf16_f32 v117, v136, v137
	s_waitcnt lgkmcnt(7)
	v_mfma_f32_32x32x16_bf16 v[66:81], v[166:169], v[126:129], v[66:81]
	ds_read_b128 v[212:215], v228 offset:8192
	v_exp_f32_e32 v130, v106
	v_exp_f32_e32 v131, v107
	v_add_f32_e32 v190, v190, v138
	s_waitcnt lgkmcnt(7)
	v_mfma_f32_32x32x16_bf16 v[50:65], v[170:173], v[126:129], v[50:65]
	ds_read_b128 v[216:219], v229 offset:8192
	v_exp_f32_e32 v132, v108
	v_exp_f32_e32 v133, v109
	v_add_f32_e32 v191, v191, v139
	s_waitcnt lgkmcnt(7)
	v_mfma_f32_32x32x16_bf16 v[34:49], v[178:181], v[126:129], v[34:49]
	ds_read_b128 v[220:223], v230 offset:8192
	v_exp_f32_e32 v134, v110
	v_exp_f32_e32 v135, v111
	v_add_f32_e32 v190, v190, v140
	s_waitcnt lgkmcnt(7)
	v_mfma_f32_32x32x16_bf16 v[18:33], v[182:185], v[126:129], v[18:33]
	ds_read_b128 v[224:227], v231 offset:8192
	v_exp_f32_e32 v136, v112
	v_exp_f32_e32 v137, v113
	v_add_f32_e32 v191, v191, v141
	s_waitcnt lgkmcnt(7)
	v_mfma_f32_32x32x16_bf16 v[82:97], v[186:189], v[158:161], v[0:15]
	ds_read_b128 v[166:169], v232 offset:32768
	v_cvt_pk_bf16_f32 v118, v138, v139
	v_cvt_pk_bf16_f32 v119, v140, v141
	v_add_f32_e32 v190, v190, v142
	v_add_f32_e32 v191, v191, v143
	s_waitcnt lgkmcnt(7)
	v_mfma_f32_32x32x16_bf16 v[82:97], v[200:203], v[154:157], v[82:97]
	ds_read_b128 v[170:173], v232 offset:36864
	v_cvt_pk_bf16_f32 v120, v142, v143
	v_add_f32_e32 v190, v190, v144
	v_add_f32_e32 v191, v191, v145
	v_cvt_pk_bf16_f32 v121, v144, v145
	s_waitcnt lgkmcnt(7)
	v_mfma_f32_32x32x16_bf16 v[82:97], v[204:207], v[150:153], v[82:97]
	ds_read_b128 v[178:181], v232 offset:40960
	v_add_f32_e32 v190, v190, v238
	v_add_f32_e32 v191, v191, v239
	v_cvt_pk_bf16_f32 v122, v238, v239
	v_add_f32_e32 v190, v190, v240
	s_waitcnt lgkmcnt(7)
	v_mfma_f32_32x32x16_bf16 v[82:97], v[208:211], v[146:149], v[82:97]
	ds_read_b128 v[182:185], v232 offset:45056
	v_add_f32_e32 v191, v191, v241
	v_cvt_pk_bf16_f32 v123, v240, v241
	v_add_f32_e32 v190, v190, v242
	v_add_f32_e32 v191, v191, v243
	s_waitcnt lgkmcnt(7)
	v_mfma_f32_32x32x16_bf16 v[98:113], v[212:215], v[158:161], v[0:15]
	ds_read_b128 v[186:189], v233 offset:32768
	v_cvt_pk_bf16_f32 v124, v242, v243
	v_add_f32_e32 v190, v190, v244
	v_add_f32_e32 v191, v191, v245
	v_cvt_pk_bf16_f32 v125, v244, v245
	s_waitcnt lgkmcnt(7)
	v_mfma_f32_32x32x16_bf16 v[98:113], v[216:219], v[154:157], v[98:113]
	ds_read_b128 v[200:203], v233 offset:36864
	v_add_f32_e32 v190, v190, v130
	v_add_f32_e32 v191, v191, v131
	v_cvt_pk_bf16_f32 v126, v130, v131
	v_add_f32_e32 v190, v190, v132
	s_waitcnt lgkmcnt(7)
	v_mfma_f32_32x32x16_bf16 v[98:113], v[220:223], v[150:153], v[98:113]
	ds_read_b128 v[204:207], v233 offset:40960
	v_add_f32_e32 v191, v191, v133
	v_cvt_pk_bf16_f32 v127, v132, v133
	v_add_f32_e32 v190, v190, v134
	v_add_f32_e32 v191, v191, v135
	s_waitcnt lgkmcnt(7)
	v_mfma_f32_32x32x16_bf16 v[98:113], v[224:227], v[146:149], v[98:113]
	ds_read_b128 v[208:211], v233 offset:45056
	v_cvt_pk_bf16_f32 v128, v134, v135
	v_add_f32_e32 v190, v190, v136
	v_add_f32_e32 v191, v191, v137
	v_cvt_pk_bf16_f32 v129, v136, v137
	s_waitcnt vmcnt(0) lgkmcnt(0)
	s_barrier
; template <int MODE> __device__ __forceinline__ void sm_half(f32x16& p, float& lsum, bf16x8& f0, bf16x8& f1) {
;   if (MODE != 3) {
; #pragma unroll
;   for (int r = 0; r < 16; ++r) p[r] = __builtin_amdgcn_exp2f(p[r]);
;   }
;   float s0 = 0, s1 = 0;
; #pragma unroll
;   for (int r = 0; r < 16; r += 2) { s0 += p[r]; s1 += p[r + 1]; }
;   lsum += s0 + s1;
;   u32x4 w0 = {cvtpk(p[0], p[1]), cvtpk(p[2], p[3]), cvtpk(p[4], p[5]), cvtpk(p[6], p[7])};
;   u32x4 w1 = {cvtpk(p[8], p[9]), cvtpk(p[10], p[11]), cvtpk(p[12], p[13]), cvtpk(p[14], p[15])};
;   f0 = *reinterpret_cast<bf16x8*>(&w0); f1 = *reinterpret_cast<bf16x8*>(&w1);
; template <int MODE> __device__ __forceinline__ void diff_attn_item(const bf16* __restrict__ Qb, const bf16* __restrict__ Kh, const bf16* __restrict__ Vh, ...
;     ...
;   for (int j = 0; j < NTL; ++j) {
;     const bool has1 = (j + 1 < NTL), has2 = (j + 2 < NTL);
;     if (has2 && MODE == 0) SLOADW(s_wr, (j + 2) * KVBLK);
;     bf16x8 f0, f1, f2, f3;
;     if (has1) qkt(pn0, pn1, lds + s_nxt * SHM_BUF + SHM_KV, qr, r32, hi, map, negM);
;     sm_half<MODE>(pc0, lsum, f0, f1);
;     const char* vt = lds + s_cur * SHM_BUF;
;     pv_b128(o, vt + voff[0], f0); pv_b128(o, vt + voff[1], f1);
;     sm_half<MODE>(pc1, lsum, f2, f3);
;     pv_b128(o, vt + voff[2], f2); pv_b128(o, vt + voff[3], f3);
;     asm volatile("s_waitcnt vmcnt(0)" ::: "memory");
;     __syncthreads();
;     pc0 = pn0; pc1 = pn1;
;     const int t = s_cur; s_cur = s_nxt; s_nxt = s_wr; s_wr = t;
;   }
	s_waitcnt lgkmcnt(7)
	v_mfma_f32_32x32x16_bf16 v[66:81], v[166:169], v[114:117], v[66:81]
	s_add_u32 s16, s14, 0x4000
	s_mov_b32 m0, s16
	ds_read_b128 v[212:215], v234 offset:32768
	global_load_lds_dwordx4 v[246:247], off
	v_exp_f32_e32 v130, v82
	v_exp_f32_e32 v131, v83
	v_add_f32_e32 v190, v190, v130
	s_waitcnt lgkmcnt(7)
	v_mfma_f32_32x32x16_bf16 v[50:65], v[170:173], v[114:117], v[50:65]
	s_add_u32 s16, s14, 0x6000
	s_mov_b32 m0, s16
	ds_read_b128 v[216:219], v234 offset:36864
	global_load_lds_dwordx4 v[250:251], off
	v_lshl_add_u64 v[246:247], v[246:247], 0, s[18:19]
	v_lshl_add_u64 v[250:251], v[250:251], 0, s[18:19]
	v_exp_f32_e32 v132, v84
	v_exp_f32_e32 v133, v85
	v_add_f32_e32 v191, v191, v131
	s_waitcnt lgkmcnt(7)
	v_mfma_f32_32x32x16_bf16 v[34:49], v[178:181], v[114:117], v[34:49]
	ds_read_b128 v[220:223], v234 offset:40960
	v_exp_f32_e32 v134, v86
	v_exp_f32_e32 v135, v87
	v_add_f32_e32 v190, v190, v132
	s_waitcnt lgkmcnt(7)
	v_mfma_f32_32x32x16_bf16 v[18:33], v[182:185], v[114:117], v[18:33]
	ds_read_b128 v[224:227], v234 offset:45056
	v_exp_f32_e32 v136, v88
	v_exp_f32_e32 v137, v89
	v_add_f32_e32 v191, v191, v133
	s_waitcnt lgkmcnt(7)
	v_mfma_f32_32x32x16_bf16 v[66:81], v[186:189], v[118:121], v[66:81]
	ds_read_b128 v[166:169], v235 offset:32768
	v_exp_f32_e32 v138, v90
	v_exp_f32_e32 v139, v91
	v_cvt_pk_bf16_f32 v114, v130, v131
	s_waitcnt lgkmcnt(7)
	v_mfma_f32_32x32x16_bf16 v[50:65], v[200:203], v[118:121], v[50:65]
	ds_read_b128 v[170:173], v235 offset:36864
	v_exp_f32_e32 v140, v92
	v_exp_f32_e32 v141, v93
	v_cvt_pk_bf16_f32 v115, v132, v133
	s_waitcnt lgkmcnt(7)
	v_mfma_f32_32x32x16_bf16 v[34:49], v[204:207], v[118:121], v[34:49]
	ds_read_b128 v[178:181], v235 offset:40960
	v_exp_f32_e32 v142, v94
	v_exp_f32_e32 v143, v95
	v_add_f32_e32 v190, v190, v134
	s_waitcnt lgkmcnt(7)
	v_mfma_f32_32x32x16_bf16 v[18:33], v[208:211], v[118:121], v[18:33]
	ds_read_b128 v[182:185], v235 offset:45056
	v_exp_f32_e32 v144, v96
	v_exp_f32_e32 v145, v97
	v_add_f32_e32 v191, v191, v135
	s_waitcnt lgkmcnt(7)
	v_mfma_f32_32x32x16_bf16 v[66:81], v[212:215], v[122:125], v[66:81]
	ds_read_b128 v[186:189], v228 offset:16384
	v_exp_f32_e32 v238, v98
	v_exp_f32_e32 v239, v99
	v_cvt_pk_bf16_f32 v116, v134, v135
	s_waitcnt lgkmcnt(7)
	v_mfma_f32_32x32x16_bf16 v[50:65], v[216:219], v[122:125], v[50:65]
	ds_read_b128 v[200:203], v229 offset:16384
	v_exp_f32_e32 v240, v100
	v_exp_f32_e32 v241, v101
	v_add_f32_e32 v190, v190, v136
	s_waitcnt lgkmcnt(7)
	v_mfma_f32_32x32x16_bf16 v[34:49], v[220:223], v[122:125], v[34:49]
	ds_read_b128 v[204:207], v230 offset:16384
	v_exp_f32_e32 v242, v102
	v_exp_f32_e32 v243, v103
	v_add_f32_e32 v191, v191, v137
	s_waitcnt lgkmcnt(7)
	v_mfma_f32_32x32x16_bf16 v[18:33], v[224:227], v[122:125], v[18:33]
	ds_read_b128 v[208:211], v231 offset:16384
	v_exp_f32_e32 v244, v104
	v_exp_f32_e32 v245, v105
	v_cvt_pk_bf16_f32 v117, v136, v137
	s_waitcnt lgkmcnt(7)
	v_mfma_f32_32x32x16_bf16 v[66:81], v[166:169], v[126:129], v[66:81]
	ds_read_b128 v[212:215], v228 offset:24576
	v_exp_f32_e32 v130, v106
	v_exp_f32_e32 v131, v107
	v_add_f32_e32 v190, v190, v138
	s_waitcnt lgkmcnt(7)
	v_mfma_f32_32x32x16_bf16 v[50:65], v[170:173], v[126:129], v[50:65]
	ds_read_b128 v[216:219], v229 offset:24576
	v_exp_f32_e32 v132, v108
	v_exp_f32_e32 v133, v109
	v_add_f32_e32 v191, v191, v139
	s_waitcnt lgkmcnt(7)
	v_mfma_f32_32x32x16_bf16 v[34:49], v[178:181], v[126:129], v[34:49]
	ds_read_b128 v[220:223], v230 offset:24576
	v_exp_f32_e32 v134, v110
	v_exp_f32_e32 v135, v111
	v_add_f32_e32 v190, v190, v140
	s_waitcnt lgkmcnt(7)
	v_mfma_f32_32x32x16_bf16 v[18:33], v[182:185], v[126:129], v[18:33]
	ds_read_b128 v[224:227], v231 offset:24576
	v_exp_f32_e32 v136, v112
	v_exp_f32_e32 v137, v113
	v_add_f32_e32 v191, v191, v141
	s_waitcnt lgkmcnt(7)
	v_mfma_f32_32x32x16_bf16 v[82:97], v[186:189], v[158:161], v[0:15]
	ds_read_b128 v[166:169], v232 offset:0
	v_cvt_pk_bf16_f32 v118, v138, v139
	v_cvt_pk_bf16_f32 v119, v140, v141
	v_add_f32_e32 v190, v190, v142
	v_add_f32_e32 v191, v191, v143
	s_waitcnt lgkmcnt(7)
	v_mfma_f32_32x32x16_bf16 v[82:97], v[200:203], v[154:157], v[82:97]
	ds_read_b128 v[170:173], v232 offset:4096
	v_cvt_pk_bf16_f32 v120, v142, v143
	v_add_f32_e32 v190, v190, v144
	v_add_f32_e32 v191, v191, v145
	v_cvt_pk_bf16_f32 v121, v144, v145
	s_waitcnt lgkmcnt(7)
	v_mfma_f32_32x32x16_bf16 v[82:97], v[204:207], v[150:153], v[82:97]
	ds_read_b128 v[178:181], v232 offset:8192
	v_add_f32_e32 v190, v190, v238
	v_add_f32_e32 v191, v191, v239
	v_cvt_pk_bf16_f32 v122, v238, v239
	v_add_f32_e32 v190, v190, v240
	s_waitcnt lgkmcnt(7)
	v_mfma_f32_32x32x16_bf16 v[82:97], v[208:211], v[146:149], v[82:97]
	ds_read_b128 v[182:185], v232 offset:12288
	v_add_f32_e32 v191, v191, v241
	v_cvt_pk_bf16_f32 v123, v240, v241
	v_add_f32_e32 v190, v190, v242
	v_add_f32_e32 v191, v191, v243
	s_waitcnt lgkmcnt(7)
	v_mfma_f32_32x32x16_bf16 v[98:113], v[212:215], v[158:161], v[0:15]
	ds_read_b128 v[186:189], v233 offset:0
	v_cvt_pk_bf16_f32 v124, v242, v243
	v_add_f32_e32 v190, v190, v244
	v_add_f32_e32 v191, v191, v245
	v_cvt_pk_bf16_f32 v125, v244, v245
	s_waitcnt lgkmcnt(7)
	v_mfma_f32_32x32x16_bf16 v[98:113], v[216:219], v[154:157], v[98:113]
	ds_read_b128 v[200:203], v233 offset:4096
	v_add_f32_e32 v190, v190, v130
	v_add_f32_e32 v191, v191, v131
	v_cvt_pk_bf16_f32 v126, v130, v131
	v_add_f32_e32 v190, v190, v132
	s_waitcnt lgkmcnt(7)
	v_mfma_f32_32x32x16_bf16 v[98:113], v[220:223], v[150:153], v[98:113]
	ds_read_b128 v[204:207], v233 offset:8192
	v_add_f32_e32 v191, v191, v133
	v_cvt_pk_bf16_f32 v127, v132, v133
	v_add_f32_e32 v190, v190, v134
	v_add_f32_e32 v191, v191, v135
	s_waitcnt lgkmcnt(7)
	v_mfma_f32_32x32x16_bf16 v[98:113], v[224:227], v[146:149], v[98:113]
	ds_read_b128 v[208:211], v233 offset:12288
	v_cvt_pk_bf16_f32 v128, v134, v135
	v_add_f32_e32 v190, v190, v136
	v_add_f32_e32 v191, v191, v137
	v_cvt_pk_bf16_f32 v129, v136, v137
	s_waitcnt vmcnt(0) lgkmcnt(0)
	s_barrier
; template <int MODE> __device__ __forceinline__ void sm_half(f32x16& p, float& lsum, bf16x8& f0, bf16x8& f1) {
;   if (MODE != 3) {
; #pragma unroll
;   for (int r = 0; r < 16; ++r) p[r] = __builtin_amdgcn_exp2f(p[r]);
;   }
;   float s0 = 0, s1 = 0;
; #pragma unroll
;   for (int r = 0; r < 16; r += 2) { s0 += p[r]; s1 += p[r + 1]; }
;   lsum += s0 + s1;
;   u32x4 w0 = {cvtpk(p[0], p[1]), cvtpk(p[2], p[3]), cvtpk(p[4], p[5]), cvtpk(p[6], p[7])};
;   u32x4 w1 = {cvtpk(p[8], p[9]), cvtpk(p[10], p[11]), cvtpk(p[12], p[13]), cvtpk(p[14], p[15])};
;   f0 = *reinterpret_cast<bf16x8*>(&w0); f1 = *reinterpret_cast<bf16x8*>(&w1);
; template <int MODE> __device__ __forceinline__ void diff_attn_item(const bf16* __restrict__ Qb, const bf16* __restrict__ Kh, const bf16* __restrict__ Vh, ...
;     ...
;   for (int j = 0; j < NTL; ++j) {
;     const bool has1 = (j + 1 < NTL), has2 = (j + 2 < NTL);
;     if (has2 && MODE == 0) SLOADW(s_wr, (j + 2) * KVBLK);
;     bf16x8 f0, f1, f2, f3;
;     if (has1) qkt(pn0, pn1, lds + s_nxt * SHM_BUF + SHM_KV, qr, r32, hi, map, negM);
;     sm_half<MODE>(pc0, lsum, f0, f1);
;     const char* vt = lds + s_cur * SHM_BUF;
;     pv_b128(o, vt + voff[0], f0); pv_b128(o, vt + voff[1], f1);
;     sm_half<MODE>(pc1, lsum, f2, f3);
;     pv_b128(o, vt + voff[2], f2); pv_b128(o, vt + voff[3], f3);
;     asm volatile("s_waitcnt vmcnt(0)" ::: "memory");
;     __syncthreads();
;     pc0 = pn0; pc1 = pn1;
;     const int t = s_cur; s_cur = s_nxt; s_nxt = s_wr; s_wr = t;
;   }
	s_waitcnt lgkmcnt(7)
	v_mfma_f32_32x32x16_bf16 v[66:81], v[166:169], v[114:117], v[66:81]
	s_add_u32 s16, s14, 0x8000
	s_mov_b32 m0, s16
	ds_read_b128 v[212:215], v234 offset:0
	global_load_lds_dwordx4 v[246:247], off
	v_exp_f32_e32 v130, v82
	v_exp_f32_e32 v131, v83
	v_add_f32_e32 v190, v190, v130
	s_waitcnt lgkmcnt(7)
	v_mfma_f32_32x32x16_bf16 v[50:65], v[170:173], v[114:117], v[50:65]
	s_add_u32 s16, s14, 0xa000
	s_mov_b32 m0, s16
	ds_read_b128 v[216:219], v234 offset:4096
	global_load_lds_dwordx4 v[250:251], off
	v_lshl_add_u64 v[246:247], v[246:247], 0, s[18:19]
	v_lshl_add_u64 v[250:251], v[250:251], 0, s[18:19]
	v_exp_f32_e32 v132, v84
	v_exp_f32_e32 v133, v85
	v_add_f32_e32 v191, v191, v131
	s_waitcnt lgkmcnt(7)
	v_mfma_f32_32x32x16_bf16 v[34:49], v[178:181], v[114:117], v[34:49]
	ds_read_b128 v[220:223], v234 offset:8192
	v_exp_f32_e32 v134, v86
	v_exp_f32_e32 v135, v87
	v_add_f32_e32 v190, v190, v132
	s_waitcnt lgkmcnt(7)
	v_mfma_f32_32x32x16_bf16 v[18:33], v[182:185], v[114:117], v[18:33]
	ds_read_b128 v[224:227], v234 offset:12288
	v_exp_f32_e32 v136, v88
	v_exp_f32_e32 v137, v89
	v_add_f32_e32 v191, v191, v133
	s_waitcnt lgkmcnt(7)
	v_mfma_f32_32x32x16_bf16 v[66:81], v[186:189], v[118:121], v[66:81]
	ds_read_b128 v[166:169], v235 offset:0
	v_exp_f32_e32 v138, v90
	v_exp_f32_e32 v139, v91
	v_cvt_pk_bf16_f32 v114, v130, v131
	s_waitcnt lgkmcnt(7)
	v_mfma_f32_32x32x16_bf16 v[50:65], v[200:203], v[118:121], v[50:65]
	ds_read_b128 v[170:173], v235 offset:4096
	v_exp_f32_e32 v140, v92
	v_exp_f32_e32 v141, v93
	v_cvt_pk_bf16_f32 v115, v132, v133
	s_waitcnt lgkmcnt(7)
	v_mfma_f32_32x32x16_bf16 v[34:49], v[204:207], v[118:121], v[34:49]
	ds_read_b128 v[178:181], v235 offset:8192
	v_exp_f32_e32 v142, v94
	v_exp_f32_e32 v143, v95
	v_add_f32_e32 v190, v190, v134
	s_waitcnt lgkmcnt(7)
	v_mfma_f32_32x32x16_bf16 v[18:33], v[208:211], v[118:121], v[18:33]
	ds_read_b128 v[182:185], v235 offset:12288
	v_exp_f32_e32 v144, v96
	v_exp_f32_e32 v145, v97
	v_add_f32_e32 v191, v191, v135
	s_waitcnt lgkmcnt(7)
	v_mfma_f32_32x32x16_bf16 v[66:81], v[212:215], v[122:125], v[66:81]
	ds_read_b128 v[186:189], v228 offset:32768
	v_exp_f32_e32 v238, v98
	v_exp_f32_e32 v239, v99
	v_cvt_pk_bf16_f32 v116, v134, v135
	s_waitcnt lgkmcnt(7)
	v_mfma_f32_32x32x16_bf16 v[50:65], v[216:219], v[122:125], v[50:65]
	ds_read_b128 v[200:203], v229 offset:32768
	v_exp_f32_e32 v240, v100
	v_exp_f32_e32 v241, v101
	v_add_f32_e32 v190, v190, v136
	s_waitcnt lgkmcnt(7)
	v_mfma_f32_32x32x16_bf16 v[34:49], v[220:223], v[122:125], v[34:49]
	ds_read_b128 v[204:207], v230 offset:32768
	v_exp_f32_e32 v242, v102
	v_exp_f32_e32 v243, v103
	v_add_f32_e32 v191, v191, v137
	s_waitcnt lgkmcnt(7)
	v_mfma_f32_32x32x16_bf16 v[18:33], v[224:227], v[122:125], v[18:33]
	ds_read_b128 v[208:211], v231 offset:32768
	v_exp_f32_e32 v244, v104
	v_exp_f32_e32 v245, v105
	v_cvt_pk_bf16_f32 v117, v136, v137
	s_waitcnt lgkmcnt(7)
	v_mfma_f32_32x32x16_bf16 v[66:81], v[166:169], v[126:129], v[66:81]
	ds_read_b128 v[212:215], v228 offset:40960
	v_exp_f32_e32 v130, v106
	v_exp_f32_e32 v131, v107
	v_add_f32_e32 v190, v190, v138
	s_waitcnt lgkmcnt(7)
	v_mfma_f32_32x32x16_bf16 v[50:65], v[170:173], v[126:129], v[50:65]
	ds_read_b128 v[216:219], v229 offset:40960
	v_exp_f32_e32 v132, v108
	v_exp_f32_e32 v133, v109
	v_add_f32_e32 v191, v191, v139
	s_waitcnt lgkmcnt(7)
	v_mfma_f32_32x32x16_bf16 v[34:49], v[178:181], v[126:129], v[34:49]
	ds_read_b128 v[220:223], v230 offset:40960
	v_exp_f32_e32 v134, v110
	v_exp_f32_e32 v135, v111
	v_add_f32_e32 v190, v190, v140
	s_waitcnt lgkmcnt(7)
	v_mfma_f32_32x32x16_bf16 v[18:33], v[182:185], v[126:129], v[18:33]
	ds_read_b128 v[224:227], v231 offset:40960
	v_exp_f32_e32 v136, v112
	v_exp_f32_e32 v137, v113
	v_add_f32_e32 v191, v191, v141
	s_waitcnt lgkmcnt(7)
	v_mfma_f32_32x32x16_bf16 v[82:97], v[186:189], v[158:161], v[0:15]
	ds_read_b128 v[166:169], v232 offset:16384
	v_cvt_pk_bf16_f32 v118, v138, v139
	v_cvt_pk_bf16_f32 v119, v140, v141
	v_add_f32_e32 v190, v190, v142
	v_add_f32_e32 v191, v191, v143
	s_waitcnt lgkmcnt(7)
	v_mfma_f32_32x32x16_bf16 v[82:97], v[200:203], v[154:157], v[82:97]
	ds_read_b128 v[170:173], v232 offset:20480
	v_cvt_pk_bf16_f32 v120, v142, v143
	v_add_f32_e32 v190, v190, v144
	v_add_f32_e32 v191, v191, v145
	v_cvt_pk_bf16_f32 v121, v144, v145
	s_waitcnt lgkmcnt(7)
	v_mfma_f32_32x32x16_bf16 v[82:97], v[204:207], v[150:153], v[82:97]
	ds_read_b128 v[178:181], v232 offset:24576
	v_add_f32_e32 v190, v190, v238
	v_add_f32_e32 v191, v191, v239
	v_cvt_pk_bf16_f32 v122, v238, v239
	v_add_f32_e32 v190, v190, v240
	s_waitcnt lgkmcnt(7)
	v_mfma_f32_32x32x16_bf16 v[82:97], v[208:211], v[146:149], v[82:97]
	ds_read_b128 v[182:185], v232 offset:28672
	v_add_f32_e32 v191, v191, v241
	v_cvt_pk_bf16_f32 v123, v240, v241
	v_add_f32_e32 v190, v190, v242
	v_add_f32_e32 v191, v191, v243
	s_waitcnt lgkmcnt(7)
	v_mfma_f32_32x32x16_bf16 v[98:113], v[212:215], v[158:161], v[0:15]
	ds_read_b128 v[186:189], v233 offset:16384
	v_cvt_pk_bf16_f32 v124, v242, v243
	v_add_f32_e32 v190, v190, v244
	v_add_f32_e32 v191, v191, v245
	v_cvt_pk_bf16_f32 v125, v244, v245
	s_waitcnt lgkmcnt(7)
	v_mfma_f32_32x32x16_bf16 v[98:113], v[216:219], v[154:157], v[98:113]
	ds_read_b128 v[200:203], v233 offset:20480
	v_add_f32_e32 v190, v190, v130
	v_add_f32_e32 v191, v191, v131
	v_cvt_pk_bf16_f32 v126, v130, v131
	v_add_f32_e32 v190, v190, v132
	s_waitcnt lgkmcnt(7)
	v_mfma_f32_32x32x16_bf16 v[98:113], v[220:223], v[150:153], v[98:113]
	ds_read_b128 v[204:207], v233 offset:24576
	v_add_f32_e32 v191, v191, v133
	v_cvt_pk_bf16_f32 v127, v132, v133
	v_add_f32_e32 v190, v190, v134
	v_add_f32_e32 v191, v191, v135
	s_waitcnt lgkmcnt(7)
	v_mfma_f32_32x32x16_bf16 v[98:113], v[224:227], v[146:149], v[98:113]
	ds_read_b128 v[208:211], v233 offset:28672
	v_cvt_pk_bf16_f32 v128, v134, v135
	v_add_f32_e32 v190, v190, v136
	v_add_f32_e32 v191, v191, v137
	v_cvt_pk_bf16_f32 v129, v136, v137
	s_waitcnt vmcnt(0) lgkmcnt(0)
	s_barrier
; template <int MODE> __device__ __forceinline__ void sm_half(f32x16& p, float& lsum, bf16x8& f0, bf16x8& f1) {
;   if (MODE != 3) {
; #pragma unroll
;   for (int r = 0; r < 16; ++r) p[r] = __builtin_amdgcn_exp2f(p[r]);
;   }
;   float s0 = 0, s1 = 0;
; #pragma unroll
;   for (int r = 0; r < 16; r += 2) { s0 += p[r]; s1 += p[r + 1]; }
;   lsum += s0 + s1;
;   u32x4 w0 = {cvtpk(p[0], p[1]), cvtpk(p[2], p[3]), cvtpk(p[4], p[5]), cvtpk(p[6], p[7])};
;   u32x4 w1 = {cvtpk(p[8], p[9]), cvtpk(p[10], p[11]), cvtpk(p[12], p[13]), cvtpk(p[14], p[15])};
;   f0 = *reinterpret_cast<bf16x8*>(&w0); f1 = *reinterpret_cast<bf16x8*>(&w1);
; template <int MODE> __device__ __forceinline__ void diff_attn_item(const bf16* __restrict__ Qb, const bf16* __restrict__ Kh, const bf16* __restrict__ Vh, ...
;     ...
;     if (has1) qkt(pn0, pn1, lds + s_nxt * SHM_BUF + SHM_KV, qr, r32, hi, map, negM);
;     sm_half<MODE>(pc0, lsum, f0, f1);
;     const char* vt = lds + s_cur * SHM_BUF;
;     pv_b128(o, vt + voff[0], f0); pv_b128(o, vt + voff[1], f1);
;     sm_half<MODE>(pc1, lsum, f2, f3);
;     pv_b128(o, vt + voff[2], f2); pv_b128(o, vt + voff[3], f3);
;     asm volatile("s_waitcnt vmcnt(0)" ::: "memory");
;     __syncthreads();
;     pc0 = pn0; pc1 = pn1;
;     const int t = s_cur; s_cur = s_nxt; s_nxt = s_wr; s_wr = t;
;   }
;   lsum += __shfl_xor(lsum, 32);
	s_waitcnt lgkmcnt(7)
	v_mfma_f32_32x32x16_bf16 v[66:81], v[166:169], v[114:117], v[66:81]
	ds_read_b128 v[212:215], v234 offset:16384
	v_exp_f32_e32 v130, v82
	v_exp_f32_e32 v131, v83
	v_add_f32_e32 v190, v190, v130
	s_waitcnt lgkmcnt(7)
	v_mfma_f32_32x32x16_bf16 v[50:65], v[170:173], v[114:117], v[50:65]
	ds_read_b128 v[216:219], v234 offset:20480
	v_exp_f32_e32 v132, v84
	v_exp_f32_e32 v133, v85
	v_add_f32_e32 v191, v191, v131
	s_waitcnt lgkmcnt(7)
	v_mfma_f32_32x32x16_bf16 v[34:49], v[178:181], v[114:117], v[34:49]
	ds_read_b128 v[220:223], v234 offset:24576
	v_exp_f32_e32 v134, v86
	v_exp_f32_e32 v135, v87
	v_add_f32_e32 v190, v190, v132
	s_waitcnt lgkmcnt(7)
	v_mfma_f32_32x32x16_bf16 v[18:33], v[182:185], v[114:117], v[18:33]
	ds_read_b128 v[224:227], v234 offset:28672
	v_exp_f32_e32 v136, v88
	v_exp_f32_e32 v137, v89
	v_add_f32_e32 v191, v191, v133
	s_waitcnt lgkmcnt(7)
	v_mfma_f32_32x32x16_bf16 v[66:81], v[186:189], v[118:121], v[66:81]
	ds_read_b128 v[166:169], v235 offset:16384
	v_exp_f32_e32 v138, v90
	v_exp_f32_e32 v139, v91
	v_cvt_pk_bf16_f32 v114, v130, v131
	s_waitcnt lgkmcnt(7)
	v_mfma_f32_32x32x16_bf16 v[50:65], v[200:203], v[118:121], v[50:65]
	ds_read_b128 v[170:173], v235 offset:20480
	v_exp_f32_e32 v140, v92
	v_exp_f32_e32 v141, v93
	v_cvt_pk_bf16_f32 v115, v132, v133
	s_waitcnt lgkmcnt(7)
	v_mfma_f32_32x32x16_bf16 v[34:49], v[204:207], v[118:121], v[34:49]
	ds_read_b128 v[178:181], v235 offset:24576
	v_exp_f32_e32 v142, v94
	v_exp_f32_e32 v143, v95
	v_add_f32_e32 v190, v190, v134
	s_waitcnt lgkmcnt(7)
	v_mfma_f32_32x32x16_bf16 v[18:33], v[208:211], v[118:121], v[18:33]
	ds_read_b128 v[182:185], v235 offset:28672
	v_exp_f32_e32 v144, v96
	v_exp_f32_e32 v145, v97
	v_add_f32_e32 v191, v191, v135
	s_waitcnt lgkmcnt(7)
	v_mfma_f32_32x32x16_bf16 v[66:81], v[212:215], v[122:125], v[66:81]
	ds_read_b128 v[186:189], v233 offset:32768
	v_exp_f32_e32 v238, v98
	v_exp_f32_e32 v239, v99
	v_cvt_pk_bf16_f32 v116, v134, v135
	s_waitcnt lgkmcnt(7)
	v_mfma_f32_32x32x16_bf16 v[50:65], v[216:219], v[122:125], v[50:65]
	ds_read_b128 v[200:203], v233 offset:36864
	v_exp_f32_e32 v240, v100
	v_exp_f32_e32 v241, v101
	v_add_f32_e32 v190, v190, v136
	s_waitcnt lgkmcnt(7)
	v_mfma_f32_32x32x16_bf16 v[34:49], v[220:223], v[122:125], v[34:49]
	ds_read_b128 v[204:207], v233 offset:40960
	v_exp_f32_e32 v242, v102
	v_exp_f32_e32 v243, v103
	v_add_f32_e32 v191, v191, v137
	s_waitcnt lgkmcnt(7)
	v_mfma_f32_32x32x16_bf16 v[18:33], v[224:227], v[122:125], v[18:33]
	ds_read_b128 v[208:211], v233 offset:45056
	v_exp_f32_e32 v244, v104
	v_exp_f32_e32 v245, v105
	v_cvt_pk_bf16_f32 v117, v136, v137
	s_waitcnt lgkmcnt(7)
	v_mfma_f32_32x32x16_bf16 v[66:81], v[166:169], v[126:129], v[66:81]
	ds_read_b128 v[166:169], v232 offset:32768
	v_exp_f32_e32 v130, v106
	v_exp_f32_e32 v131, v107
	v_add_f32_e32 v190, v190, v138
	s_waitcnt lgkmcnt(7)
	v_mfma_f32_32x32x16_bf16 v[50:65], v[170:173], v[126:129], v[50:65]
	ds_read_b128 v[170:173], v232 offset:36864
	v_exp_f32_e32 v132, v108
	v_exp_f32_e32 v133, v109
	v_add_f32_e32 v191, v191, v139
	s_waitcnt lgkmcnt(7)
	v_mfma_f32_32x32x16_bf16 v[34:49], v[178:181], v[126:129], v[34:49]
	ds_read_b128 v[178:181], v232 offset:40960
	v_exp_f32_e32 v134, v110
	v_exp_f32_e32 v135, v111
	v_add_f32_e32 v190, v190, v140
	s_waitcnt lgkmcnt(7)
	v_mfma_f32_32x32x16_bf16 v[18:33], v[182:185], v[126:129], v[18:33]
	ds_read_b128 v[182:185], v232 offset:45056
	v_exp_f32_e32 v136, v112
	v_exp_f32_e32 v137, v113
	v_add_f32_e32 v191, v191, v141
	v_cvt_pk_bf16_f32 v118, v138, v139
	v_cvt_pk_bf16_f32 v119, v140, v141
	v_add_f32_e32 v190, v190, v142
	v_add_f32_e32 v191, v191, v143
	v_cvt_pk_bf16_f32 v120, v142, v143
	v_add_f32_e32 v190, v190, v144
	v_add_f32_e32 v191, v191, v145
	v_cvt_pk_bf16_f32 v121, v144, v145
	v_add_f32_e32 v190, v190, v238
	v_add_f32_e32 v191, v191, v239
	v_cvt_pk_bf16_f32 v122, v238, v239
	v_add_f32_e32 v190, v190, v240
	v_add_f32_e32 v191, v191, v241
	v_cvt_pk_bf16_f32 v123, v240, v241
	v_add_f32_e32 v190, v190, v242
	v_add_f32_e32 v191, v191, v243
	v_cvt_pk_bf16_f32 v124, v242, v243
	v_add_f32_e32 v190, v190, v244
	v_add_f32_e32 v191, v191, v245
	v_cvt_pk_bf16_f32 v125, v244, v245
	v_add_f32_e32 v190, v190, v130
	v_add_f32_e32 v191, v191, v131
	v_cvt_pk_bf16_f32 v126, v130, v131
	v_add_f32_e32 v190, v190, v132
	v_add_f32_e32 v191, v191, v133
	v_cvt_pk_bf16_f32 v127, v132, v133
	v_add_f32_e32 v190, v190, v134
	v_add_f32_e32 v191, v191, v135
	v_cvt_pk_bf16_f32 v128, v134, v135
	v_add_f32_e32 v190, v190, v136
	v_add_f32_e32 v191, v191, v137
	v_cvt_pk_bf16_f32 v129, v136, v137
	s_waitcnt lgkmcnt(3)
	v_mfma_f32_32x32x16_bf16 v[66:81], v[166:169], v[114:117], v[66:81]
	ds_read_b128 v[212:215], v234 offset:32768
	s_waitcnt lgkmcnt(3)
	v_mfma_f32_32x32x16_bf16 v[50:65], v[170:173], v[114:117], v[50:65]
	ds_read_b128 v[216:219], v234 offset:36864
	s_waitcnt lgkmcnt(3)
	v_mfma_f32_32x32x16_bf16 v[34:49], v[178:181], v[114:117], v[34:49]
	ds_read_b128 v[220:223], v234 offset:40960
	s_waitcnt lgkmcnt(3)
	v_mfma_f32_32x32x16_bf16 v[18:33], v[182:185], v[114:117], v[18:33]
	ds_read_b128 v[224:227], v234 offset:45056
	s_waitcnt lgkmcnt(11)
	v_mfma_f32_32x32x16_bf16 v[66:81], v[186:189], v[118:121], v[66:81]
	ds_read_b128 v[166:169], v235 offset:32768
	s_waitcnt lgkmcnt(11)
	v_mfma_f32_32x32x16_bf16 v[50:65], v[200:203], v[118:121], v[50:65]
	ds_read_b128 v[170:173], v235 offset:36864
	s_waitcnt lgkmcnt(11)
	v_mfma_f32_32x32x16_bf16 v[34:49], v[204:207], v[118:121], v[34:49]
	ds_read_b128 v[178:181], v235 offset:40960
	s_waitcnt lgkmcnt(11)
	v_mfma_f32_32x32x16_bf16 v[18:33], v[208:211], v[118:121], v[18:33]
	ds_read_b128 v[182:185], v235 offset:45056
	s_waitcnt lgkmcnt(7)
	v_mfma_f32_32x32x16_bf16 v[66:81], v[212:215], v[122:125], v[66:81]
	s_waitcnt lgkmcnt(6)
	v_mfma_f32_32x32x16_bf16 v[50:65], v[216:219], v[122:125], v[50:65]
	s_waitcnt lgkmcnt(5)
	v_mfma_f32_32x32x16_bf16 v[34:49], v[220:223], v[122:125], v[34:49]
	s_waitcnt lgkmcnt(4)
	v_mfma_f32_32x32x16_bf16 v[18:33], v[224:227], v[122:125], v[18:33]
	s_waitcnt lgkmcnt(3)
	v_mfma_f32_32x32x16_bf16 v[66:81], v[166:169], v[126:129], v[66:81]
	s_waitcnt lgkmcnt(2)
	v_mfma_f32_32x32x16_bf16 v[50:65], v[170:173], v[126:129], v[50:65]
	s_waitcnt lgkmcnt(1)
	v_mfma_f32_32x32x16_bf16 v[34:49], v[178:181], v[126:129], v[34:49]
	s_waitcnt lgkmcnt(0)
	v_mfma_f32_32x32x16_bf16 v[18:33], v[182:185], v[126:129], v[18:33]
	v_add_f32_e32 v98, v190, v191
	v_and_b32_e32 v198, 63, v163
	v_bfe_u32 v252, v163, 5, 1
	v_lshlrev_b32_e32 v164, 3, v252
	s_waitcnt lgkmcnt(0)
	s_barrier
; template <int MODE> __device__ __forceinline__ void diff_attn_item(const bf16* __restrict__ Qb, const bf16* __restrict__ Kh, const bf16* __restrict__ Vh, ...
;     ...
;   lsum += __shfl_xor(lsum, 32);
;   const float rl = 1.f / lsum;
;   float* E = (float*)lds;
;   if (map == 1) {
	v_and_b32_e32 v83, 64, v193
	v_xor_b32_e32 v82, 32, v193
	v_add_u32_e32 v83, 64, v83
	v_cmp_lt_i32_e32 vcc, v82, v83
	s_nop 1
	v_cndmask_b32_e32 v82, v193, v82, vcc
	v_lshlrev_b32_e32 v83, 2, v82
	ds_bpermute_b32 v82, v83, v98
	s_nop 0
	s_waitcnt lgkmcnt(0)
	v_add_f32_e32 v82, v98, v82
	v_div_scale_f32 v84, s[8:9], v82, v82, 1.0
	v_rcp_f32_e32 v85, v84
	s_nop 0
	v_fma_f32 v98, -v84, v85, 1.0
	v_fmac_f32_e32 v85, v98, v85
	v_div_scale_f32 v98, vcc, 1.0, v82, 1.0
	s_nop 0
	v_mul_f32_e32 v90, v98, v85
	v_fma_f32 v91, -v84, v90, v98
	v_fmac_f32_e32 v90, v91, v85
	v_fma_f32 v84, -v84, v90, v98
	v_div_fmas_f32 v84, v84, v85, v90
	v_div_fixup_f32 v82, v84, v82, 1.0
	v_cmp_eq_u32_e32 vcc, 1, v197
	s_nop 0
	s_branch .Lda0_join

; template <int MODE> __device__ __forceinline__ void diff_attn_item(const bf16* __restrict__ Qb, const bf16* __restrict__ Kh, const bf16* __restrict__ Vh, ...
;     ...
;   const bf16* Qw = Qb + (long)(rb * 32 + r32) * 128 + map * 64 + hi * 8;
; #pragma unroll
;   for (int d0 = 0; d0 < 4; ++d0) qr[d0] = *reinterpret_cast<const bf16x8*>(Qw + d0 * 16);
;   const int ldsbase = (int)(uintptr_t)(__attribute__((address_space(3))) char*)lds;
;   int voff[4];
; #pragma unroll
;   for (int ks = 0; ks < 4; ++ks) voff[ks] = r32 * 128 + ((((ks << 1) | hi) ^ ((r32 >> 1) & 7)) << 4);
;   int ksrc[2], vsrc[2];
; #pragma unroll
;   for (int i = 0; i < 2; ++i) {
;     const int q = tid + i * 512;
;     const int krow = q >> 4, kc = (q & 15) ^ (krow & 15);
;     ksrc[i] = krow * 128 + kc * 8;
;     const int vrow = q >> 3, vc = (q & 7) ^ ((vrow >> 1) & 7);
;     vsrc[i] = vrow * 64 + vc * 8;
;   }
;     ...
;   const int NTL = seq / KVBLK;
;   f32x16 pc0, pc1, pn0, pn1;
;   SLOADW(0, 0);
;   SLOADW(1, KVBLK);
;   asm volatile("s_waitcnt vmcnt(0)" ::: "memory");
;   __syncthreads();
; template <int AMODE> __device__ __forceinline__ void phase_mixers(int l, int mode) {
;     ...
;       const int bh = isl ? (i >> 6) : (i >> 1), qb = isl ? (i & 63) : (i & 1), b = bh >> 2, h = bh & 3;
;       const size_t base = ((size_t)b * 4 + h) * PTOK * 128 + (isl ? 0 : (size_t)SEQ * 128);
;       const int trow = isl ? (b * SEQ + qb * 128) : (NLAT + b * CTXL + qb * 128);
;       diff_attn_item<AMODE>(qd + base + (size_t)qb * 128 * 128, kd + base, vd + base,
.LBB0_940:
	s_and_b32 s2, s11, 3
	s_lshl_b32 s8, s12, 2
	s_or_b32 s8, s8, s2
	s_and_b64 s[4:5], s[4:5], exec
	s_mul_hi_i32 s9, s8, 0x108000
	s_mul_i32 s8, s8, 0x108000
	s_cselect_b32 s14, 0, 0x100000
	s_add_u32 s4, s8, s14
	s_addc_u32 s5, s9, 0
	s_lshl_b64 s[4:5], s[4:5], 1
	s_add_u32 s8, s83, s4
	s_addc_u32 s9, s24, s5
	s_lshl_b32 s10, s10, 15
	s_add_u32 s16, s8, s10
	s_addc_u32 s17, s9, 0
	s_add_u32 s8, s79, s4
	s_addc_u32 s9, s26, s5
	s_add_u32 s10, s27, s4
	v_mov_b32_e32 v163, v192
	s_addc_u32 s11, s91, s5
	s_load_dwordx2 s[4:5], s[86:87], 0xa0
	v_mov_b32_e32 v203, 0
	v_and_b32_e32 v34, 31, v163
	v_bfe_u32 v165, v163, 6, 2
	v_ashrrev_i32_e32 v197, 8, v163
	v_lshl_or_b32 v162, v165, 5, v34
	v_lshlrev_b32_e32 v16, 8, v162
	v_lshlrev_b32_e32 v20, 6, v197
	v_bfe_u32 v35, v163, 5, 1
	v_lshl_add_u64 v[18:19], s[16:17], 0, v[16:17]
	v_ashrrev_i32_e32 v21, 31, v20
	v_lshl_add_u64 v[18:19], v[20:21], 1, v[18:19]
	v_lshlrev_b32_e32 v16, 4, v35
	v_lshl_add_u64 v[18:19], v[18:19], 0, v[16:17]
	global_load_dwordx4 v[158:161], v[18:19], off
	global_load_dwordx4 v[154:157], v[18:19], off offset:32
	global_load_dwordx4 v[150:153], v[18:19], off offset:64
	global_load_dwordx4 v[146:149], v[18:19], off offset:96
	s_cmpk_eq_i32 s13, 0x81
	s_cbranch_scc1 .Lda0_new
	v_lshrrev_b32_e32 v18, 4, v163
	v_xor_b32_e32 v18, v18, v163
	v_lshlrev_b32_e32 v18, 3, v18
	v_and_b32_e32 v19, 56, v18
	v_ashrrev_i32_e32 v18, 4, v163
	v_xor_b32_e32 v20, v18, v163
	v_lshlrev_b32_e32 v18, 7, v18
	v_lshlrev_b32_e32 v20, 3, v20
	v_add_u32_e32 v21, 0x200, v163
	v_and_or_b32 v18, v20, s21, v18
	v_lshlrev_b32_e32 v20, 3, v163
	v_ashrrev_i32_e32 v22, 4, v21
	v_and_or_b32 v20, v20, s22, v19
	v_xor_b32_e32 v23, v22, v163
	v_lshlrev_b32_e32 v21, 3, v21
	v_lshlrev_b32_e32 v204, 4, v163
	v_lshlrev_b32_e32 v22, 7, v22
	v_lshlrev_b32_e32 v23, 3, v23
	v_and_or_b32 v24, v21, s22, v19
	v_add_u32_e32 v36, 0, v204
	v_ashrrev_i32_e32 v21, 31, v20
	v_and_or_b32 v22, v23, s21, v22
	v_add_u32_e32 v23, 0x4000, v36
	v_lshlrev_b64 v[26:27], 1, v[20:21]
	v_readfirstlane_b32 s15, v36
	v_ashrrev_i32_e32 v19, 31, v18
	v_lshl_add_u64 v[20:21], s[10:11], 0, v[26:27]
	s_mov_b32 m0, s15
	v_lshlrev_b64 v[28:29], 1, v[18:19]
	v_readfirstlane_b32 s15, v23
	v_ashrrev_i32_e32 v25, 31, v24
	global_load_lds_dwordx4 v[20:21], off
	v_lshl_add_u64 v[18:19], s[8:9], 0, v[28:29]
	s_mov_b32 m0, s15
	v_lshlrev_b64 v[30:31], 1, v[24:25]
	v_add_u32_e32 v20, 0x2000, v36
	global_load_lds_dwordx4 v[18:19], off
	v_lshl_add_u64 v[18:19], s[10:11], 0, v[30:31]
	v_readfirstlane_b32 s15, v20
	v_ashrrev_i32_e32 v23, 31, v22
	v_add_u32_e32 v20, 0x6000, v36
	s_add_u32 s10, s10, 0x4000
	s_mov_b32 m0, s15
	v_lshlrev_b64 v[32:33], 1, v[22:23]
	v_readfirstlane_b32 s15, v20
	s_addc_u32 s11, s11, 0
	v_add_u32_e32 v20, 0x8000, v36
	global_load_lds_dwordx4 v[18:19], off
	v_lshl_add_u64 v[18:19], s[8:9], 0, v[32:33]
	s_mov_b32 m0, s15
	s_add_u32 s8, s8, 0x4000
	v_add_u32_e32 v21, 0xc000, v36
	v_readfirstlane_b32 s15, v20
	global_load_lds_dwordx4 v[18:19], off
	s_addc_u32 s9, s9, 0
	v_lshl_add_u64 v[18:19], s[10:11], 0, v[26:27]
	s_mov_b32 m0, s15
	v_readfirstlane_b32 s15, v21
	global_load_lds_dwordx4 v[18:19], off
	v_lshl_add_u64 v[18:19], s[8:9], 0, v[28:29]
	s_mov_b32 m0, s15
	v_add_u32_e32 v20, 0xa000, v36
	global_load_lds_dwordx4 v[18:19], off
	v_lshl_add_u64 v[18:19], s[10:11], 0, v[30:31]
	v_readfirstlane_b32 s10, v20
	s_mov_b32 m0, s10
	v_add_u32_e32 v20, 0xe000, v36
	global_load_lds_dwordx4 v[18:19], off
	v_lshl_add_u64 v[18:19], s[8:9], 0, v[32:33]
	v_readfirstlane_b32 s8, v20
	s_mov_b32 m0, s8
	v_lshl_or_b32 v36, v197, 7, v16
	global_load_lds_dwordx4 v[18:19], off
	v_lshlrev_b32_e32 v37, 8, v34
	v_and_b32_e32 v38, 0xf0, v204
	v_xad_u32 v205, v36, v38, v37
	v_add_u32_e32 v22, 0, v205
	s_waitcnt vmcnt(0)
	s_waitcnt vmcnt(0) lgkmcnt(0)
	s_barrier
; __device__ __forceinline__ void qkt(f32x16& p0, f32x16& p1, const char* Ks, const bf16x8* qr, int r32, int hi, int map, float negM) {
; #pragma unroll
;   for (int r = 0; r < 16; ++r) { p0[r] = negM; p1[r] = negM; }
; #pragma unroll
;   for (int d0 = 0; d0 < 4; ++d0) {
;     int cb = (map * 64 + d0 * 16 + hi * 8) * 2;
;     bf16x8 b0 = *reinterpret_cast<const bf16x8*>(Ks + KSWZ(r32, cb));
;     bf16x8 b1 = *reinterpret_cast<const bf16x8*>(Ks + KSWZ(32 + r32, cb));
;     p0 = __builtin_amdgcn_mfma_f32_32x32x16_bf16(b0, qr[d0], p0, 0, 0, 0);
;     p1 = __builtin_amdgcn_mfma_f32_32x32x16_bf16(b1, qr[d0], p1, 0, 0, 0);
;   }
; template <int MODE> __device__ __forceinline__ void diff_attn_item(const bf16* __restrict__ Qb, const bf16* __restrict__ Kh, const bf16* __restrict__ Vh, ...
;     ...
;   const int ldsbase = (int)(uintptr_t)(__attribute__((address_space(3))) char*)lds;
;   int voff[4];
; #pragma unroll
;   for (int ks = 0; ks < 4; ++ks) voff[ks] = r32 * 128 + ((((ks << 1) | hi) ^ ((r32 >> 1) & 7)) << 4);
;   int ksrc[2], vsrc[2];
; #pragma unroll
;   for (int i = 0; i < 2; ++i) {
;     const int q = tid + i * 512;
;     const int krow = q >> 4, kc = (q & 15) ^ (krow & 15);
;     ksrc[i] = krow * 128 + kc * 8;
;     const int vrow = q >> 3, vc = (q & 7) ^ ((vrow >> 1) & 7);
;     vsrc[i] = vrow * 64 + vc * 8;
;   }
;     ...
;   const int NTL = seq / KVBLK;
;   f32x16 pc0, pc1, pn0, pn1;
;   SLOADW(0, 0);
;   SLOADW(1, KVBLK);
;   asm volatile("s_waitcnt vmcnt(0)" ::: "memory");
;   __syncthreads();
;   qkt(pc0, pc1, lds + SHM_KV, qr, r32, hi, map, negM);
;   int s_cur = 0, s_nxt = 1, s_wr = 2;
	ds_read_b128 v[18:21], v22 offset:16384
	ds_read_b128 v[22:25], v22 offset:24576
	s_waitcnt lgkmcnt(1)
	v_mfma_f32_32x32x16_bf16 v[98:113], v[18:21], v[158:161], v[0:15]
	v_or_b32_e32 v18, 32, v36
	v_xad_u32 v206, v18, v38, v37
	s_mul_hi_i32 s8, s12, 0x840000
	s_mul_i32 s12, s12, 0x840000
	s_mul_i32 s9, s2, 0x210000
	s_add_u32 s9, s12, s9
	s_addc_u32 s8, s8, 0
	s_waitcnt lgkmcnt(0)
	v_mfma_f32_32x32x16_bf16 v[82:97], v[22:25], v[158:161], v[0:15]
	v_add_u32_e32 v22, 0, v206
	ds_read_b128 v[18:21], v22 offset:16384
	ds_read_b128 v[22:25], v22 offset:24576
	s_lshl_b32 s10, s14, 1
	s_add_u32 s10, s9, s10
	s_addc_u32 s12, s8, 0
	s_add_u32 s8, s85, s10
	s_addc_u32 s9, s33, s12
	s_waitcnt lgkmcnt(1)
	v_mfma_f32_32x32x16_bf16 v[98:113], v[18:21], v[154:157], v[98:113]
	v_or_b32_e32 v18, 64, v36
	v_xad_u32 v207, v18, v38, v37
	v_lshlrev_b32_e32 v34, 7, v34
	v_lshl_add_u64 v[138:139], s[8:9], 0, v[32:33]
	v_lshl_add_u64 v[140:141], s[8:9], 0, v[28:29]
	s_add_u32 s8, s84, s10
	s_addc_u32 s9, s90, s12
	s_waitcnt lgkmcnt(0)
	v_mfma_f32_32x32x16_bf16 v[82:97], v[22:25], v[154:157], v[82:97]
	v_add_u32_e32 v22, 0, v207
	ds_read_b128 v[18:21], v22 offset:16384
	ds_read_b128 v[22:25], v22 offset:24576
	v_lshl_add_u64 v[142:143], s[8:9], 0, v[30:31]
	v_lshl_add_u64 v[144:145], s[8:9], 0, v[26:27]
	s_lshl_b32 s8, s13, 14
	s_mov_b32 s11, 2
	s_mov_b32 s16, 0
	s_waitcnt lgkmcnt(1)
	v_mfma_f32_32x32x16_bf16 v[98:113], v[18:21], v[150:153], v[98:113]
	v_or_b32_e32 v18, 0x60, v36
	v_xad_u32 v208, v18, v38, v37
	v_add_u32_e32 v36, 0, v208
	ds_read_b128 v[18:21], v36 offset:16384
	v_bfe_u32 v37, v163, 1, 3
	v_and_b32_e32 v198, 63, v163
	v_lshlrev_b32_e32 v164, 3, v35
	s_waitcnt lgkmcnt(1)
	v_mfma_f32_32x32x16_bf16 v[82:97], v[22:25], v[150:153], v[82:97]
	v_lshrrev_b32_e32 v22, 1, v163
	v_bitop3_b32 v38, v35, v22, 7 bitop3:0x78
	ds_read_b128 v[22:25], v36 offset:24576
	v_lshl_or_b32 v202, v38, 4, v34
	s_add_u32 s12, s8, 0x4000
	s_mov_b64 s[8:9], 0
	v_mov_b32_e32 v66, 0
	s_waitcnt lgkmcnt(1)
	v_mfma_f32_32x32x16_bf16 v[98:113], v[18:21], v[146:149], v[98:113]
	v_bitop3_b32 v18, v35, v37, 2 bitop3:0x36
	v_lshl_or_b32 v201, v18, 4, v34
	v_bitop3_b32 v18, v35, v37, 4 bitop3:0x36
	v_lshl_or_b32 v200, v18, 4, v34
	v_bitop3_b32 v18, v35, v37, 6 bitop3:0x36
	v_lshl_or_b32 v199, v18, 4, v34
	v_mov_b32_e32 v67, v203
	s_waitcnt lgkmcnt(0)
	v_mfma_f32_32x32x16_bf16 v[82:97], v[22:25], v[146:149], v[82:97]
	v_mov_b32_e32 v68, v203
	v_mov_b32_e32 v69, v203
	v_mov_b32_e32 v70, v203
	v_mov_b32_e32 v71, v203
	v_mov_b32_e32 v72, v203
	v_mov_b32_e32 v73, v203
	v_mov_b32_e32 v74, v203
	v_mov_b32_e32 v75, v203
	v_mov_b32_e32 v76, v203
	v_mov_b32_e32 v77, v203
	v_mov_b32_e32 v78, v203
	v_mov_b32_e32 v79, v203
	v_mov_b32_e32 v80, v203
	v_mov_b32_e32 v81, v203
	v_mov_b32_e32 v50, 0
	v_mov_b32_e32 v51, v203
	v_mov_b32_e32 v52, v203
	v_mov_b32_e32 v53, v203
	v_mov_b32_e32 v54, v203
	v_mov_b32_e32 v55, v203
	v_mov_b32_e32 v56, v203
	v_mov_b32_e32 v57, v203
	v_mov_b32_e32 v58, v203
	v_mov_b32_e32 v59, v203
	v_mov_b32_e32 v60, v203
	v_mov_b32_e32 v61, v203
	v_mov_b32_e32 v62, v203
	v_mov_b32_e32 v63, v203
	v_mov_b32_e32 v64, v203
	v_mov_b32_e32 v65, v203
	v_mov_b32_e32 v34, 0
	v_mov_b32_e32 v35, v203
	v_mov_b32_e32 v36, v203
	v_mov_b32_e32 v37, v203
	v_mov_b32_e32 v38, v203
	v_mov_b32_e32 v39, v203
	v_mov_b32_e32 v40, v203
	v_mov_b32_e32 v41, v203
	v_mov_b32_e32 v42, v203
	v_mov_b32_e32 v43, v203
	v_mov_b32_e32 v44, v203
	v_mov_b32_e32 v45, v203
	v_mov_b32_e32 v46, v203
	v_mov_b32_e32 v47, v203
	v_mov_b32_e32 v48, v203
	v_mov_b32_e32 v49, v203
	v_mov_b32_e32 v18, 0
	v_mov_b32_e32 v19, v203
	v_mov_b32_e32 v20, v203
	v_mov_b32_e32 v21, v203
	v_mov_b32_e32 v22, v203
	v_mov_b32_e32 v23, v203
	v_mov_b32_e32 v24, v203
	v_mov_b32_e32 v25, v203
	v_mov_b32_e32 v26, v203
	v_mov_b32_e32 v27, v203
	v_mov_b32_e32 v28, v203
	v_mov_b32_e32 v29, v203
	v_mov_b32_e32 v30, v203
	v_mov_b32_e32 v31, v203
	v_mov_b32_e32 v32, v203
	v_mov_b32_e32 v33, v203

; template <int MODE> __device__ __forceinline__ void diff_attn_item(const bf16* __restrict__ Qb, const bf16* __restrict__ Kh, const bf16* __restrict__ Vh, ...
;     ...
;   if (map == 1) {
;     const float sc1 = lam * rl;
; #pragma unroll
;     for (int d0 = 0; d0 < 4; ++d0)
; #pragma unroll
;       for (int r = 0; r < 16; ++r) E[((rb * 4 + d0) * 16 + r) * 64 + lane] = o[d0][r] * sc1;
;   }
.Lda0_join:
	s_and_saveexec_b64 s[8:9], vcc
	s_cbranch_execz .LBB0_944
	v_mul_f32_e32 v84, v194, v82
	v_lshlrev_b32_e32 v85, 14, v165
	v_lshlrev_b32_e32 v86, 2, v198
	v_mul_f32_e32 v87, v66, v84
	v_add3_u32 v85, 0, v86, v85
	v_mul_f32_e32 v86, v67, v84
	ds_write2st64_b32 v85, v87, v86 offset1:1
	v_mul_f32_e32 v86, v68, v84
	v_mul_f32_e32 v87, v69, v84
	ds_write2st64_b32 v85, v86, v87 offset0:2 offset1:3
	v_mul_f32_e32 v86, v70, v84
	v_mul_f32_e32 v87, v71, v84
	ds_write2st64_b32 v85, v86, v87 offset0:4 offset1:5
	v_mul_f32_e32 v86, v72, v84
	v_mul_f32_e32 v87, v73, v84
	ds_write2st64_b32 v85, v86, v87 offset0:6 offset1:7
	v_mul_f32_e32 v86, v74, v84
	v_mul_f32_e32 v87, v75, v84
	ds_write2st64_b32 v85, v86, v87 offset0:8 offset1:9
	v_mul_f32_e32 v86, v76, v84
	v_mul_f32_e32 v87, v77, v84
	ds_write2st64_b32 v85, v86, v87 offset0:10 offset1:11
	v_mul_f32_e32 v86, v78, v84
	v_mul_f32_e32 v87, v79, v84
	ds_write2st64_b32 v85, v86, v87 offset0:12 offset1:13
	v_mul_f32_e32 v86, v80, v84
	v_mul_f32_e32 v87, v81, v84
	ds_write2st64_b32 v85, v86, v87 offset0:14 offset1:15
	v_mul_f32_e32 v86, v50, v84
	v_mul_f32_e32 v87, v51, v84
	ds_write2st64_b32 v85, v86, v87 offset0:16 offset1:17
	v_mul_f32_e32 v86, v52, v84
	v_mul_f32_e32 v87, v53, v84
	ds_write2st64_b32 v85, v86, v87 offset0:18 offset1:19
	v_mul_f32_e32 v86, v54, v84
	v_mul_f32_e32 v87, v55, v84
	ds_write2st64_b32 v85, v86, v87 offset0:20 offset1:21
	v_mul_f32_e32 v86, v56, v84
	v_mul_f32_e32 v87, v57, v84
	ds_write2st64_b32 v85, v86, v87 offset0:22 offset1:23
	v_mul_f32_e32 v86, v58, v84
	v_mul_f32_e32 v87, v59, v84
	ds_write2st64_b32 v85, v86, v87 offset0:24 offset1:25
	v_mul_f32_e32 v86, v60, v84
	v_mul_f32_e32 v87, v61, v84
	ds_write2st64_b32 v85, v86, v87 offset0:26 offset1:27
	v_mul_f32_e32 v86, v62, v84
	v_mul_f32_e32 v87, v63, v84
	ds_write2st64_b32 v85, v86, v87 offset0:28 offset1:29
	v_mul_f32_e32 v86, v64, v84
	v_mul_f32_e32 v87, v65, v84
	ds_write2st64_b32 v85, v86, v87 offset0:30 offset1:31
	v_mul_f32_e32 v86, v34, v84
	v_mul_f32_e32 v87, v35, v84
	ds_write2st64_b32 v85, v86, v87 offset0:32 offset1:33
	v_mul_f32_e32 v86, v36, v84
	v_mul_f32_e32 v87, v37, v84
	ds_write2st64_b32 v85, v86, v87 offset0:34 offset1:35
	v_mul_f32_e32 v86, v38, v84
	v_mul_f32_e32 v87, v39, v84
	ds_write2st64_b32 v85, v86, v87 offset0:36 offset1:37
	v_mul_f32_e32 v86, v40, v84
	v_mul_f32_e32 v87, v41, v84
	ds_write2st64_b32 v85, v86, v87 offset0:38 offset1:39
	v_mul_f32_e32 v86, v42, v84
	v_mul_f32_e32 v87, v43, v84
	ds_write2st64_b32 v85, v86, v87 offset0:40 offset1:41
	v_mul_f32_e32 v86, v44, v84
	v_mul_f32_e32 v87, v45, v84
	ds_write2st64_b32 v85, v86, v87 offset0:42 offset1:43
	v_mul_f32_e32 v86, v46, v84
	v_mul_f32_e32 v87, v47, v84
	ds_write2st64_b32 v85, v86, v87 offset0:44 offset1:45
	v_mul_f32_e32 v86, v48, v84
	v_mul_f32_e32 v87, v49, v84
	ds_write2st64_b32 v85, v86, v87 offset0:46 offset1:47
	v_mul_f32_e32 v86, v18, v84
	v_mul_f32_e32 v87, v19, v84
	ds_write2st64_b32 v85, v86, v87 offset0:48 offset1:49
	v_mul_f32_e32 v86, v20, v84
	v_mul_f32_e32 v87, v21, v84
	ds_write2st64_b32 v85, v86, v87 offset0:50 offset1:51
	v_mul_f32_e32 v86, v22, v84
	v_mul_f32_e32 v87, v23, v84
	ds_write2st64_b32 v85, v86, v87 offset0:52 offset1:53
	v_mul_f32_e32 v86, v24, v84
	v_mul_f32_e32 v87, v25, v84
	ds_write2st64_b32 v85, v86, v87 offset0:54 offset1:55
	v_mul_f32_e32 v86, v26, v84
	v_mul_f32_e32 v87, v27, v84
	ds_write2st64_b32 v85, v86, v87 offset0:56 offset1:57
	v_mul_f32_e32 v86, v28, v84
	v_mul_f32_e32 v87, v29, v84
	ds_write2st64_b32 v85, v86, v87 offset0:58 offset1:59
	v_mul_f32_e32 v86, v30, v84
	v_mul_f32_e32 v87, v31, v84
	ds_write2st64_b32 v85, v86, v87 offset0:60 offset1:61
	v_mul_f32_e32 v86, v32, v84
	v_mul_f32_e32 v84, v33, v84
	ds_write2st64_b32 v85, v86, v84 offset0:62 offset1:63

; template <int MODE> __device__ __forceinline__ void sm_half(f32x16& p, float& lsum, bf16x8& f0, bf16x8& f1) {
;   if (MODE != 3) {
; #pragma unroll
;   for (int r = 0; r < 16; ++r) p[r] = __builtin_amdgcn_exp2f(p[r]);
;   }
;   float s0 = 0, s1 = 0;
; #pragma unroll
;   for (int r = 0; r < 16; r += 2) { s0 += p[r]; s1 += p[r + 1]; }
;   lsum += s0 + s1;
;   u32x4 w0 = {cvtpk(p[0], p[1]), cvtpk(p[2], p[3]), cvtpk(p[4], p[5]), cvtpk(p[6], p[7])};
;   u32x4 w1 = {cvtpk(p[8], p[9]), cvtpk(p[10], p[11]), cvtpk(p[12], p[13]), cvtpk(p[14], p[15])};
;   f0 = *reinterpret_cast<bf16x8*>(&w0); f1 = *reinterpret_cast<bf16x8*>(&w1);
; template <int MODE> __device__ __forceinline__ void diff_attn_item(const bf16* __restrict__ Qb, const bf16* __restrict__ Kh, const bf16* __restrict__ Vh, ...
;     ...
;   for (int j = 0; j < NTL; ++j) {
;     const bool has1 = (j + 1 < NTL), has2 = (j + 2 < NTL);
;     if (has2 && MODE == 0) SLOADW(s_wr, (j + 2) * KVBLK);
;     bf16x8 f0, f1, f2, f3;
;     if (has1) qkt(pn0, pn1, lds + s_nxt * SHM_BUF + SHM_KV, qr, r32, hi, map, negM);
;     sm_half<MODE>(pc0, lsum, f0, f1);
;     const char* vt = lds + s_cur * SHM_BUF;
;     pv_b128(o, vt + voff[0], f0); pv_b128(o, vt + voff[1], f1);
;     sm_half<MODE>(pc1, lsum, f2, f3);
;     pv_b128(o, vt + voff[2], f2); pv_b128(o, vt + voff[3], f3);
;     asm volatile("s_waitcnt vmcnt(0)" ::: "memory");
;     __syncthreads();
;     pc0 = pn0; pc1 = pn1;
;     const int t = s_cur; s_cur = s_nxt; s_nxt = s_wr; s_wr = t;
;   }
.Lda1_loop:
	s_barrier
	s_waitcnt lgkmcnt(7)
	v_mfma_f32_32x32x16_bf16 v[66:81], v[166:169], v[114:117], v[66:81]
	s_add_u32 s16, s14, 0x8000
	s_mov_b32 m0, s16
	ds_read_b128 v[212:215], v234 offset:0
	global_load_lds_dwordx4 v[246:247], off
	v_exp_f32_e32 v130, v82
	v_exp_f32_e32 v131, v83
	v_add_f32_e32 v190, v190, v130
	s_waitcnt lgkmcnt(7)
	v_mfma_f32_32x32x16_bf16 v[50:65], v[170:173], v[114:117], v[50:65]
	s_add_u32 s16, s14, 0xa000
	s_mov_b32 m0, s16
	ds_read_b128 v[216:219], v234 offset:4096
	global_load_lds_dwordx4 v[250:251], off
	v_lshl_add_u64 v[246:247], v[246:247], 0, s[18:19]
	v_lshl_add_u64 v[250:251], v[250:251], 0, s[18:19]
	v_exp_f32_e32 v132, v84
	v_exp_f32_e32 v133, v85
	v_add_f32_e32 v191, v191, v131
	s_waitcnt lgkmcnt(7)
	v_mfma_f32_32x32x16_bf16 v[34:49], v[178:181], v[114:117], v[34:49]
	s_add_u32 s16, s14, 0x10000
	s_mov_b32 m0, s16
	ds_read_b128 v[220:223], v234 offset:8192
	global_load_lds_dwordx4 v[236:237], off
	v_exp_f32_e32 v134, v86
	v_exp_f32_e32 v135, v87
	v_add_f32_e32 v190, v190, v132
	s_waitcnt lgkmcnt(7)
	v_mfma_f32_32x32x16_bf16 v[18:33], v[182:185], v[114:117], v[18:33]
	s_add_u32 s16, s14, 0x12000
	s_mov_b32 m0, s16
	ds_read_b128 v[224:227], v234 offset:12288
	global_load_lds_dwordx4 v[248:249], off
	v_lshl_add_u64 v[236:237], v[236:237], 0, s[18:19]
	v_lshl_add_u64 v[248:249], v[248:249], 0, s[18:19]
	v_exp_f32_e32 v136, v88
	v_exp_f32_e32 v137, v89
	v_add_f32_e32 v191, v191, v133
	s_waitcnt lgkmcnt(7)
	v_mfma_f32_32x32x16_bf16 v[66:81], v[186:189], v[118:121], v[66:81]
	ds_read_b128 v[166:169], v235 offset:0
	v_exp_f32_e32 v138, v90
	v_exp_f32_e32 v139, v91
	v_cvt_pk_bf16_f32 v114, v130, v131
	s_waitcnt lgkmcnt(7)
	v_mfma_f32_32x32x16_bf16 v[50:65], v[200:203], v[118:121], v[50:65]
	ds_read_b128 v[170:173], v235 offset:4096
	v_exp_f32_e32 v140, v92
	v_exp_f32_e32 v141, v93
	v_cvt_pk_bf16_f32 v115, v132, v133
	s_waitcnt lgkmcnt(7)
	v_mfma_f32_32x32x16_bf16 v[34:49], v[204:207], v[118:121], v[34:49]
	ds_read_b128 v[178:181], v235 offset:8192
	v_exp_f32_e32 v142, v94
	v_exp_f32_e32 v143, v95
	v_add_f32_e32 v190, v190, v134
	s_waitcnt lgkmcnt(7)
	v_mfma_f32_32x32x16_bf16 v[18:33], v[208:211], v[118:121], v[18:33]
	ds_read_b128 v[182:185], v235 offset:12288
	v_exp_f32_e32 v144, v96
	v_exp_f32_e32 v145, v97
	v_add_f32_e32 v191, v191, v135
	s_waitcnt lgkmcnt(7)
	v_mfma_f32_32x32x16_bf16 v[66:81], v[212:215], v[122:125], v[66:81]
	ds_read_b128 v[186:189], v228 offset:32768
	v_exp_f32_e32 v238, v98
	v_exp_f32_e32 v239, v99
	v_cvt_pk_bf16_f32 v116, v134, v135
	s_waitcnt lgkmcnt(7)
	v_mfma_f32_32x32x16_bf16 v[50:65], v[216:219], v[122:125], v[50:65]
	ds_read_b128 v[200:203], v229 offset:32768
	v_exp_f32_e32 v240, v100
	v_exp_f32_e32 v241, v101
	v_add_f32_e32 v190, v190, v136
	s_waitcnt lgkmcnt(7)
	v_mfma_f32_32x32x16_bf16 v[34:49], v[220:223], v[122:125], v[34:49]
	ds_read_b128 v[204:207], v230 offset:32768
	v_exp_f32_e32 v242, v102
	v_exp_f32_e32 v243, v103
	v_add_f32_e32 v191, v191, v137
	s_waitcnt lgkmcnt(7)
	v_mfma_f32_32x32x16_bf16 v[18:33], v[224:227], v[122:125], v[18:33]
	ds_read_b128 v[208:211], v231 offset:32768
	v_exp_f32_e32 v244, v104
	v_exp_f32_e32 v245, v105
	v_cvt_pk_bf16_f32 v117, v136, v137
	s_waitcnt lgkmcnt(7)
	v_mfma_f32_32x32x16_bf16 v[66:81], v[166:169], v[126:129], v[66:81]
	ds_read_b128 v[212:215], v228 offset:40960
	v_exp_f32_e32 v130, v106
	v_exp_f32_e32 v131, v107
	v_add_f32_e32 v190, v190, v138
	s_waitcnt lgkmcnt(7)
	v_mfma_f32_32x32x16_bf16 v[50:65], v[170:173], v[126:129], v[50:65]
	ds_read_b128 v[216:219], v229 offset:40960
	v_exp_f32_e32 v132, v108
	v_exp_f32_e32 v133, v109
	v_add_f32_e32 v191, v191, v139
	s_waitcnt lgkmcnt(7)
	v_mfma_f32_32x32x16_bf16 v[34:49], v[178:181], v[126:129], v[34:49]
	ds_read_b128 v[220:223], v230 offset:40960
	v_exp_f32_e32 v134, v110
	v_exp_f32_e32 v135, v111
	v_add_f32_e32 v190, v190, v140
	s_waitcnt lgkmcnt(7)
	v_mfma_f32_32x32x16_bf16 v[18:33], v[182:185], v[126:129], v[18:33]
	ds_read_b128 v[224:227], v231 offset:40960
	v_exp_f32_e32 v136, v112
	v_exp_f32_e32 v137, v113
	v_add_f32_e32 v191, v191, v141
	s_waitcnt lgkmcnt(7)
	v_mfma_f32_32x32x16_bf16 v[82:97], v[186:189], v[158:161], v[0:15]
	ds_read_b128 v[166:169], v232 offset:16384
	v_cvt_pk_bf16_f32 v118, v138, v139
	v_cvt_pk_bf16_f32 v119, v140, v141
	v_add_f32_e32 v190, v190, v142
	v_add_f32_e32 v191, v191, v143
	s_waitcnt lgkmcnt(7)
	v_mfma_f32_32x32x16_bf16 v[82:97], v[200:203], v[154:157], v[82:97]
	ds_read_b128 v[170:173], v232 offset:20480
	v_cvt_pk_bf16_f32 v120, v142, v143
	v_add_f32_e32 v190, v190, v144
	v_add_f32_e32 v191, v191, v145
	v_cvt_pk_bf16_f32 v121, v144, v145
	s_waitcnt lgkmcnt(7)
	v_mfma_f32_32x32x16_bf16 v[82:97], v[204:207], v[150:153], v[82:97]
	ds_read_b128 v[178:181], v232 offset:24576
	v_add_f32_e32 v190, v190, v238
	v_add_f32_e32 v191, v191, v239
	v_cvt_pk_bf16_f32 v122, v238, v239
	v_add_f32_e32 v190, v190, v240
	s_waitcnt lgkmcnt(7)
	v_mfma_f32_32x32x16_bf16 v[82:97], v[208:211], v[146:149], v[82:97]
	ds_read_b128 v[182:185], v232 offset:28672
	v_add_f32_e32 v191, v191, v241
	v_cvt_pk_bf16_f32 v123, v240, v241
	v_add_f32_e32 v190, v190, v242
	v_add_f32_e32 v191, v191, v243
	s_waitcnt lgkmcnt(7)
	v_mfma_f32_32x32x16_bf16 v[98:113], v[212:215], v[158:161], v[0:15]
	ds_read_b128 v[186:189], v233 offset:16384
	v_cvt_pk_bf16_f32 v124, v242, v243
	v_add_f32_e32 v190, v190, v244
	v_add_f32_e32 v191, v191, v245
	v_cvt_pk_bf16_f32 v125, v244, v245
	s_waitcnt lgkmcnt(7)
	v_mfma_f32_32x32x16_bf16 v[98:113], v[216:219], v[154:157], v[98:113]
	ds_read_b128 v[200:203], v233 offset:20480
	v_add_f32_e32 v190, v190, v130
	v_add_f32_e32 v191, v191, v131
	v_cvt_pk_bf16_f32 v126, v130, v131
	v_add_f32_e32 v190, v190, v132
	s_waitcnt lgkmcnt(7)
	v_mfma_f32_32x32x16_bf16 v[98:113], v[220:223], v[150:153], v[98:113]
	ds_read_b128 v[204:207], v233 offset:24576
	v_add_f32_e32 v191, v191, v133
	v_cvt_pk_bf16_f32 v127, v132, v133
	v_add_f32_e32 v190, v190, v134
	v_add_f32_e32 v191, v191, v135
	s_waitcnt lgkmcnt(7)
	v_mfma_f32_32x32x16_bf16 v[98:113], v[224:227], v[146:149], v[98:113]
	ds_read_b128 v[208:211], v233 offset:28672
	v_cvt_pk_bf16_f32 v128, v134, v135
	v_add_f32_e32 v190, v190, v136
	v_add_f32_e32 v191, v191, v137
	v_cvt_pk_bf16_f32 v129, v136, v137
	s_waitcnt vmcnt(0) lgkmcnt(0)
	s_barrier
; template <int MODE> __device__ __forceinline__ void sm_half(f32x16& p, float& lsum, bf16x8& f0, bf16x8& f1) {
;   if (MODE != 3) {
; #pragma unroll
;   for (int r = 0; r < 16; ++r) p[r] = __builtin_amdgcn_exp2f(p[r]);
;   }
;   float s0 = 0, s1 = 0;
; #pragma unroll
;   for (int r = 0; r < 16; r += 2) { s0 += p[r]; s1 += p[r + 1]; }
;   lsum += s0 + s1;
;   u32x4 w0 = {cvtpk(p[0], p[1]), cvtpk(p[2], p[3]), cvtpk(p[4], p[5]), cvtpk(p[6], p[7])};
;   u32x4 w1 = {cvtpk(p[8], p[9]), cvtpk(p[10], p[11]), cvtpk(p[12], p[13]), cvtpk(p[14], p[15])};
;   f0 = *reinterpret_cast<bf16x8*>(&w0); f1 = *reinterpret_cast<bf16x8*>(&w1);
; template <int MODE> __device__ __forceinline__ void diff_attn_item(const bf16* __restrict__ Qb, const bf16* __restrict__ Kh, const bf16* __restrict__ Vh, ...
;     ...
;   for (int j = 0; j < NTL; ++j) {
;     const bool has1 = (j + 1 < NTL), has2 = (j + 2 < NTL);
;     if (has2 && MODE == 0) SLOADW(s_wr, (j + 2) * KVBLK);
;     bf16x8 f0, f1, f2, f3;
;     if (has1) qkt(pn0, pn1, lds + s_nxt * SHM_BUF + SHM_KV, qr, r32, hi, map, negM);
;     sm_half<MODE>(pc0, lsum, f0, f1);
;     const char* vt = lds + s_cur * SHM_BUF;
;     pv_b128(o, vt + voff[0], f0); pv_b128(o, vt + voff[1], f1);
;     sm_half<MODE>(pc1, lsum, f2, f3);
;     pv_b128(o, vt + voff[2], f2); pv_b128(o, vt + voff[3], f3);
;     asm volatile("s_waitcnt vmcnt(0)" ::: "memory");
;     __syncthreads();
;     pc0 = pn0; pc1 = pn1;
;     const int t = s_cur; s_cur = s_nxt; s_nxt = s_wr; s_wr = t;
;   }
	s_waitcnt lgkmcnt(7)
	v_mfma_f32_32x32x16_bf16 v[66:81], v[166:169], v[114:117], v[66:81]
	s_add_u32 s16, s14, 0x0
	s_mov_b32 m0, s16
	ds_read_b128 v[212:215], v234 offset:16384
	global_load_lds_dwordx4 v[246:247], off
	v_exp_f32_e32 v130, v82
	v_exp_f32_e32 v131, v83
	v_add_f32_e32 v190, v190, v130
	s_waitcnt lgkmcnt(7)
	v_mfma_f32_32x32x16_bf16 v[50:65], v[170:173], v[114:117], v[50:65]
	s_add_u32 s16, s14, 0x2000
	s_mov_b32 m0, s16
	ds_read_b128 v[216:219], v234 offset:20480
	global_load_lds_dwordx4 v[250:251], off
	v_lshl_add_u64 v[246:247], v[246:247], 0, s[18:19]
	v_lshl_add_u64 v[250:251], v[250:251], 0, s[18:19]
	v_exp_f32_e32 v132, v84
	v_exp_f32_e32 v133, v85
	v_add_f32_e32 v191, v191, v131
	s_waitcnt lgkmcnt(7)
	v_mfma_f32_32x32x16_bf16 v[34:49], v[178:181], v[114:117], v[34:49]
	s_add_u32 s16, s14, 0x14000
	s_mov_b32 m0, s16
	ds_read_b128 v[220:223], v234 offset:24576
	global_load_lds_dwordx4 v[236:237], off
	v_exp_f32_e32 v134, v86
	v_exp_f32_e32 v135, v87
	v_add_f32_e32 v190, v190, v132
	s_waitcnt lgkmcnt(7)
	v_mfma_f32_32x32x16_bf16 v[18:33], v[182:185], v[114:117], v[18:33]
	s_add_u32 s16, s14, 0x16000
	s_mov_b32 m0, s16
	ds_read_b128 v[224:227], v234 offset:28672
	global_load_lds_dwordx4 v[248:249], off
	v_lshl_add_u64 v[236:237], v[236:237], 0, s[18:19]
	v_lshl_add_u64 v[248:249], v[248:249], 0, s[18:19]
	v_exp_f32_e32 v136, v88
	v_exp_f32_e32 v137, v89
	v_add_f32_e32 v191, v191, v133
	s_waitcnt lgkmcnt(7)
	v_mfma_f32_32x32x16_bf16 v[66:81], v[186:189], v[118:121], v[66:81]
	ds_read_b128 v[166:169], v235 offset:16384
	v_exp_f32_e32 v138, v90
	v_exp_f32_e32 v139, v91
	v_cvt_pk_bf16_f32 v114, v130, v131
	s_waitcnt lgkmcnt(7)
	v_mfma_f32_32x32x16_bf16 v[50:65], v[200:203], v[118:121], v[50:65]
	ds_read_b128 v[170:173], v235 offset:20480
	v_exp_f32_e32 v140, v92
	v_exp_f32_e32 v141, v93
	v_cvt_pk_bf16_f32 v115, v132, v133
	s_waitcnt lgkmcnt(7)
	v_mfma_f32_32x32x16_bf16 v[34:49], v[204:207], v[118:121], v[34:49]
	ds_read_b128 v[178:181], v235 offset:24576
	v_exp_f32_e32 v142, v94
	v_exp_f32_e32 v143, v95
	v_add_f32_e32 v190, v190, v134
	s_waitcnt lgkmcnt(7)
	v_mfma_f32_32x32x16_bf16 v[18:33], v[208:211], v[118:121], v[18:33]
	ds_read_b128 v[182:185], v235 offset:28672
	v_exp_f32_e32 v144, v96
	v_exp_f32_e32 v145, v97
	v_add_f32_e32 v191, v191, v135
	s_waitcnt lgkmcnt(7)
	v_mfma_f32_32x32x16_bf16 v[66:81], v[212:215], v[122:125], v[66:81]
	ds_read_b128 v[186:189], v228 offset:0
	v_exp_f32_e32 v238, v98
	v_exp_f32_e32 v239, v99
	v_cvt_pk_bf16_f32 v116, v134, v135
	s_waitcnt lgkmcnt(7)
	v_mfma_f32_32x32x16_bf16 v[50:65], v[216:219], v[122:125], v[50:65]
	ds_read_b128 v[200:203], v229 offset:0
	v_exp_f32_e32 v240, v100
	v_exp_f32_e32 v241, v101
	v_add_f32_e32 v190, v190, v136
	s_waitcnt lgkmcnt(7)
	v_mfma_f32_32x32x16_bf16 v[34:49], v[220:223], v[122:125], v[34:49]
	ds_read_b128 v[204:207], v230 offset:0
	v_exp_f32_e32 v242, v102
	v_exp_f32_e32 v243, v103
	v_add_f32_e32 v191, v191, v137
	s_waitcnt lgkmcnt(7)
	v_mfma_f32_32x32x16_bf16 v[18:33], v[224:227], v[122:125], v[18:33]
	ds_read_b128 v[208:211], v231 offset:0
	v_exp_f32_e32 v244, v104
	v_exp_f32_e32 v245, v105
	v_cvt_pk_bf16_f32 v117, v136, v137
	s_waitcnt lgkmcnt(7)
	v_mfma_f32_32x32x16_bf16 v[66:81], v[166:169], v[126:129], v[66:81]
	ds_read_b128 v[212:215], v228 offset:8192
	v_exp_f32_e32 v130, v106
	v_exp_f32_e32 v131, v107
	v_add_f32_e32 v190, v190, v138
	s_waitcnt lgkmcnt(7)
	v_mfma_f32_32x32x16_bf16 v[50:65], v[170:173], v[126:129], v[50:65]
	ds_read_b128 v[216:219], v229 offset:8192
	v_exp_f32_e32 v132, v108
	v_exp_f32_e32 v133, v109
	v_add_f32_e32 v191, v191, v139
	s_waitcnt lgkmcnt(7)
	v_mfma_f32_32x32x16_bf16 v[34:49], v[178:181], v[126:129], v[34:49]
	ds_read_b128 v[220:223], v230 offset:8192
	v_exp_f32_e32 v134, v110
	v_exp_f32_e32 v135, v111
	v_add_f32_e32 v190, v190, v140
	s_waitcnt lgkmcnt(7)
	v_mfma_f32_32x32x16_bf16 v[18:33], v[182:185], v[126:129], v[18:33]
	ds_read_b128 v[224:227], v231 offset:8192
	v_exp_f32_e32 v136, v112
	v_exp_f32_e32 v137, v113
	v_add_f32_e32 v191, v191, v141
	s_waitcnt lgkmcnt(7)
	v_mfma_f32_32x32x16_bf16 v[82:97], v[186:189], v[158:161], v[0:15]
	ds_read_b128 v[166:169], v232 offset:32768
	v_cvt_pk_bf16_f32 v118, v138, v139
	v_cvt_pk_bf16_f32 v119, v140, v141
	v_add_f32_e32 v190, v190, v142
	v_add_f32_e32 v191, v191, v143
	s_waitcnt lgkmcnt(7)
	v_mfma_f32_32x32x16_bf16 v[82:97], v[200:203], v[154:157], v[82:97]
	ds_read_b128 v[170:173], v232 offset:36864
	v_cvt_pk_bf16_f32 v120, v142, v143
	v_add_f32_e32 v190, v190, v144
	v_add_f32_e32 v191, v191, v145
	v_cvt_pk_bf16_f32 v121, v144, v145
	s_waitcnt lgkmcnt(7)
	v_mfma_f32_32x32x16_bf16 v[82:97], v[204:207], v[150:153], v[82:97]
	ds_read_b128 v[178:181], v232 offset:40960
	v_add_f32_e32 v190, v190, v238
	v_add_f32_e32 v191, v191, v239
	v_cvt_pk_bf16_f32 v122, v238, v239
	v_add_f32_e32 v190, v190, v240
	s_waitcnt lgkmcnt(7)
	v_mfma_f32_32x32x16_bf16 v[82:97], v[208:211], v[146:149], v[82:97]
	ds_read_b128 v[182:185], v232 offset:45056
	v_add_f32_e32 v191, v191, v241
	v_cvt_pk_bf16_f32 v123, v240, v241
	v_add_f32_e32 v190, v190, v242
	v_add_f32_e32 v191, v191, v243
	s_waitcnt lgkmcnt(7)
	v_mfma_f32_32x32x16_bf16 v[98:113], v[212:215], v[158:161], v[0:15]
	ds_read_b128 v[186:189], v233 offset:32768
	v_cvt_pk_bf16_f32 v124, v242, v243
	v_add_f32_e32 v190, v190, v244
	v_add_f32_e32 v191, v191, v245
	v_cvt_pk_bf16_f32 v125, v244, v245
	s_waitcnt lgkmcnt(7)
	v_mfma_f32_32x32x16_bf16 v[98:113], v[216:219], v[154:157], v[98:113]
	ds_read_b128 v[200:203], v233 offset:36864
	v_add_f32_e32 v190, v190, v130
	v_add_f32_e32 v191, v191, v131
	v_cvt_pk_bf16_f32 v126, v130, v131
	v_add_f32_e32 v190, v190, v132
	s_waitcnt lgkmcnt(7)
	v_mfma_f32_32x32x16_bf16 v[98:113], v[220:223], v[150:153], v[98:113]
	ds_read_b128 v[204:207], v233 offset:40960
	v_add_f32_e32 v191, v191, v133
	v_cvt_pk_bf16_f32 v127, v132, v133
	v_add_f32_e32 v190, v190, v134
	v_add_f32_e32 v191, v191, v135
	s_waitcnt lgkmcnt(7)
	v_mfma_f32_32x32x16_bf16 v[98:113], v[224:227], v[146:149], v[98:113]
	ds_read_b128 v[208:211], v233 offset:45056
	v_cvt_pk_bf16_f32 v128, v134, v135
	v_add_f32_e32 v190, v190, v136
	v_add_f32_e32 v191, v191, v137
	v_cvt_pk_bf16_f32 v129, v136, v137
	s_waitcnt vmcnt(0) lgkmcnt(0)
	s_barrier
; template <int MODE> __device__ __forceinline__ void sm_half(f32x16& p, float& lsum, bf16x8& f0, bf16x8& f1) {
;   if (MODE != 3) {
; #pragma unroll
;   for (int r = 0; r < 16; ++r) p[r] = __builtin_amdgcn_exp2f(p[r]);
;   }
;   float s0 = 0, s1 = 0;
; #pragma unroll
;   for (int r = 0; r < 16; r += 2) { s0 += p[r]; s1 += p[r + 1]; }
;   lsum += s0 + s1;
;   u32x4 w0 = {cvtpk(p[0], p[1]), cvtpk(p[2], p[3]), cvtpk(p[4], p[5]), cvtpk(p[6], p[7])};
;   u32x4 w1 = {cvtpk(p[8], p[9]), cvtpk(p[10], p[11]), cvtpk(p[12], p[13]), cvtpk(p[14], p[15])};
;   f0 = *reinterpret_cast<bf16x8*>(&w0); f1 = *reinterpret_cast<bf16x8*>(&w1);
; template <int MODE> __device__ __forceinline__ void diff_attn_item(const bf16* __restrict__ Qb, const bf16* __restrict__ Kh, const bf16* __restrict__ Vh, ...
;     ...
;   for (int j = 0; j < NTL; ++j) {
;     const bool has1 = (j + 1 < NTL), has2 = (j + 2 < NTL);
;     if (has2 && MODE == 0) SLOADW(s_wr, (j + 2) * KVBLK);
;     bf16x8 f0, f1, f2, f3;
;     if (has1) qkt(pn0, pn1, lds + s_nxt * SHM_BUF + SHM_KV, qr, r32, hi, map, negM);
;     sm_half<MODE>(pc0, lsum, f0, f1);
;     const char* vt = lds + s_cur * SHM_BUF;
;     pv_b128(o, vt + voff[0], f0); pv_b128(o, vt + voff[1], f1);
;     sm_half<MODE>(pc1, lsum, f2, f3);
;     pv_b128(o, vt + voff[2], f2); pv_b128(o, vt + voff[3], f3);
;     asm volatile("s_waitcnt vmcnt(0)" ::: "memory");
;     __syncthreads();
;     pc0 = pn0; pc1 = pn1;
;     const int t = s_cur; s_cur = s_nxt; s_nxt = s_wr; s_wr = t;
;   }
	s_waitcnt lgkmcnt(7)
	v_mfma_f32_32x32x16_bf16 v[66:81], v[166:169], v[114:117], v[66:81]
	s_add_u32 s16, s14, 0x4000
	s_mov_b32 m0, s16
	ds_read_b128 v[212:215], v234 offset:32768
	global_load_lds_dwordx4 v[246:247], off
	v_exp_f32_e32 v130, v82
	v_exp_f32_e32 v131, v83
	v_add_f32_e32 v190, v190, v130
	s_waitcnt lgkmcnt(7)
	v_mfma_f32_32x32x16_bf16 v[50:65], v[170:173], v[114:117], v[50:65]
	s_add_u32 s16, s14, 0x6000
	s_mov_b32 m0, s16
	ds_read_b128 v[216:219], v234 offset:36864
	global_load_lds_dwordx4 v[250:251], off
	v_lshl_add_u64 v[246:247], v[246:247], 0, s[18:19]
	v_lshl_add_u64 v[250:251], v[250:251], 0, s[18:19]
	v_exp_f32_e32 v132, v84
	v_exp_f32_e32 v133, v85
	v_add_f32_e32 v191, v191, v131
	s_waitcnt lgkmcnt(7)
	v_mfma_f32_32x32x16_bf16 v[34:49], v[178:181], v[114:117], v[34:49]
	s_add_u32 s16, s14, 0xc000
	s_mov_b32 m0, s16
	ds_read_b128 v[220:223], v234 offset:40960
	global_load_lds_dwordx4 v[236:237], off
	v_exp_f32_e32 v134, v86
	v_exp_f32_e32 v135, v87
	v_add_f32_e32 v190, v190, v132
	s_waitcnt lgkmcnt(7)
	v_mfma_f32_32x32x16_bf16 v[18:33], v[182:185], v[114:117], v[18:33]
	s_add_u32 s16, s14, 0xe000
	s_mov_b32 m0, s16
	ds_read_b128 v[224:227], v234 offset:45056
	global_load_lds_dwordx4 v[248:249], off
	v_lshl_add_u64 v[236:237], v[236:237], 0, s[18:19]
	v_lshl_add_u64 v[248:249], v[248:249], 0, s[18:19]
	v_exp_f32_e32 v136, v88
	v_exp_f32_e32 v137, v89
	v_add_f32_e32 v191, v191, v133
	s_waitcnt lgkmcnt(7)
	v_mfma_f32_32x32x16_bf16 v[66:81], v[186:189], v[118:121], v[66:81]
	ds_read_b128 v[166:169], v235 offset:32768
	v_exp_f32_e32 v138, v90
	v_exp_f32_e32 v139, v91
	v_cvt_pk_bf16_f32 v114, v130, v131
	s_waitcnt lgkmcnt(7)
	v_mfma_f32_32x32x16_bf16 v[50:65], v[200:203], v[118:121], v[50:65]
	ds_read_b128 v[170:173], v235 offset:36864
	v_exp_f32_e32 v140, v92
	v_exp_f32_e32 v141, v93
	v_cvt_pk_bf16_f32 v115, v132, v133
	s_waitcnt lgkmcnt(7)
	v_mfma_f32_32x32x16_bf16 v[34:49], v[204:207], v[118:121], v[34:49]
	ds_read_b128 v[178:181], v235 offset:40960
	v_exp_f32_e32 v142, v94
	v_exp_f32_e32 v143, v95
	v_add_f32_e32 v190, v190, v134
	s_waitcnt lgkmcnt(7)
	v_mfma_f32_32x32x16_bf16 v[18:33], v[208:211], v[118:121], v[18:33]
	ds_read_b128 v[182:185], v235 offset:45056
	v_exp_f32_e32 v144, v96
	v_exp_f32_e32 v145, v97
	v_add_f32_e32 v191, v191, v135
	s_waitcnt lgkmcnt(7)
	v_mfma_f32_32x32x16_bf16 v[66:81], v[212:215], v[122:125], v[66:81]
	ds_read_b128 v[186:189], v228 offset:16384
	v_exp_f32_e32 v238, v98
	v_exp_f32_e32 v239, v99
	v_cvt_pk_bf16_f32 v116, v134, v135
	s_waitcnt lgkmcnt(7)
	v_mfma_f32_32x32x16_bf16 v[50:65], v[216:219], v[122:125], v[50:65]
	ds_read_b128 v[200:203], v229 offset:16384
	v_exp_f32_e32 v240, v100
	v_exp_f32_e32 v241, v101
	v_add_f32_e32 v190, v190, v136
	s_waitcnt lgkmcnt(7)
	v_mfma_f32_32x32x16_bf16 v[34:49], v[220:223], v[122:125], v[34:49]
	ds_read_b128 v[204:207], v230 offset:16384
	v_exp_f32_e32 v242, v102
	v_exp_f32_e32 v243, v103
	v_add_f32_e32 v191, v191, v137
	s_waitcnt lgkmcnt(7)
	v_mfma_f32_32x32x16_bf16 v[18:33], v[224:227], v[122:125], v[18:33]
	ds_read_b128 v[208:211], v231 offset:16384
	v_exp_f32_e32 v244, v104
	v_exp_f32_e32 v245, v105
	v_cvt_pk_bf16_f32 v117, v136, v137
	s_waitcnt lgkmcnt(7)
	v_mfma_f32_32x32x16_bf16 v[66:81], v[166:169], v[126:129], v[66:81]
	ds_read_b128 v[212:215], v228 offset:24576
	v_exp_f32_e32 v130, v106
	v_exp_f32_e32 v131, v107
	v_add_f32_e32 v190, v190, v138
	s_waitcnt lgkmcnt(7)
	v_mfma_f32_32x32x16_bf16 v[50:65], v[170:173], v[126:129], v[50:65]
	ds_read_b128 v[216:219], v229 offset:24576
	v_exp_f32_e32 v132, v108
	v_exp_f32_e32 v133, v109
	v_add_f32_e32 v191, v191, v139
	s_waitcnt lgkmcnt(7)
	v_mfma_f32_32x32x16_bf16 v[34:49], v[178:181], v[126:129], v[34:49]
	ds_read_b128 v[220:223], v230 offset:24576
	v_exp_f32_e32 v134, v110
	v_exp_f32_e32 v135, v111
	v_add_f32_e32 v190, v190, v140
	s_waitcnt lgkmcnt(7)
	v_mfma_f32_32x32x16_bf16 v[18:33], v[182:185], v[126:129], v[18:33]
	ds_read_b128 v[224:227], v231 offset:24576
	v_exp_f32_e32 v136, v112
	v_exp_f32_e32 v137, v113
	v_add_f32_e32 v191, v191, v141
	s_waitcnt lgkmcnt(7)
	v_mfma_f32_32x32x16_bf16 v[82:97], v[186:189], v[158:161], v[0:15]
	ds_read_b128 v[166:169], v232 offset:0
	v_cvt_pk_bf16_f32 v118, v138, v139
	v_cvt_pk_bf16_f32 v119, v140, v141
	v_add_f32_e32 v190, v190, v142
	v_add_f32_e32 v191, v191, v143
	s_waitcnt lgkmcnt(7)
	v_mfma_f32_32x32x16_bf16 v[82:97], v[200:203], v[154:157], v[82:97]
	ds_read_b128 v[170:173], v232 offset:4096
	v_cvt_pk_bf16_f32 v120, v142, v143
	v_add_f32_e32 v190, v190, v144
	v_add_f32_e32 v191, v191, v145
	v_cvt_pk_bf16_f32 v121, v144, v145
	s_waitcnt lgkmcnt(7)
	v_mfma_f32_32x32x16_bf16 v[82:97], v[204:207], v[150:153], v[82:97]
	ds_read_b128 v[178:181], v232 offset:8192
	v_add_f32_e32 v190, v190, v238
	v_add_f32_e32 v191, v191, v239
	v_cvt_pk_bf16_f32 v122, v238, v239
	v_add_f32_e32 v190, v190, v240
	s_waitcnt lgkmcnt(7)
	v_mfma_f32_32x32x16_bf16 v[82:97], v[208:211], v[146:149], v[82:97]
	ds_read_b128 v[182:185], v232 offset:12288
	v_add_f32_e32 v191, v191, v241
	v_cvt_pk_bf16_f32 v123, v240, v241
	v_add_f32_e32 v190, v190, v242
	v_add_f32_e32 v191, v191, v243
	s_waitcnt lgkmcnt(7)
	v_mfma_f32_32x32x16_bf16 v[98:113], v[212:215], v[158:161], v[0:15]
	ds_read_b128 v[186:189], v233 offset:0
	v_cvt_pk_bf16_f32 v124, v242, v243
	v_add_f32_e32 v190, v190, v244
	v_add_f32_e32 v191, v191, v245
	v_cvt_pk_bf16_f32 v125, v244, v245
	s_waitcnt lgkmcnt(7)
	v_mfma_f32_32x32x16_bf16 v[98:113], v[216:219], v[154:157], v[98:113]
	ds_read_b128 v[200:203], v233 offset:4096
	v_add_f32_e32 v190, v190, v130
	v_add_f32_e32 v191, v191, v131
	v_cvt_pk_bf16_f32 v126, v130, v131
	v_add_f32_e32 v190, v190, v132
	s_waitcnt lgkmcnt(7)
	v_mfma_f32_32x32x16_bf16 v[98:113], v[220:223], v[150:153], v[98:113]
	ds_read_b128 v[204:207], v233 offset:8192
	v_add_f32_e32 v191, v191, v133
	v_cvt_pk_bf16_f32 v127, v132, v133
	v_add_f32_e32 v190, v190, v134
	v_add_f32_e32 v191, v191, v135
	s_waitcnt lgkmcnt(7)
	v_mfma_f32_32x32x16_bf16 v[98:113], v[224:227], v[146:149], v[98:113]
	ds_read_b128 v[208:211], v233 offset:12288
	v_cvt_pk_bf16_f32 v128, v134, v135
	v_add_f32_e32 v190, v190, v136
	v_add_f32_e32 v191, v191, v137
	v_cvt_pk_bf16_f32 v129, v136, v137
	s_waitcnt vmcnt(0) lgkmcnt(0)
	s_sub_u32 s15, s15, 1
	s_cmp_lg_u32 s15, 0
	s_cbranch_scc1 .Lda1_loop
; template <int MODE> __device__ __forceinline__ void sm_half(f32x16& p, float& lsum, bf16x8& f0, bf16x8& f1) {
;   if (MODE != 3) {
; #pragma unroll
;   for (int r = 0; r < 16; ++r) p[r] = __builtin_amdgcn_exp2f(p[r]);
;   }
;   float s0 = 0, s1 = 0;
; #pragma unroll
;   for (int r = 0; r < 16; r += 2) { s0 += p[r]; s1 += p[r + 1]; }
;   lsum += s0 + s1;
;   u32x4 w0 = {cvtpk(p[0], p[1]), cvtpk(p[2], p[3]), cvtpk(p[4], p[5]), cvtpk(p[6], p[7])};
;   u32x4 w1 = {cvtpk(p[8], p[9]), cvtpk(p[10], p[11]), cvtpk(p[12], p[13]), cvtpk(p[14], p[15])};
;   f0 = *reinterpret_cast<bf16x8*>(&w0); f1 = *reinterpret_cast<bf16x8*>(&w1);
; template <int MODE> __device__ __forceinline__ void diff_attn_item(const bf16* __restrict__ Qb, const bf16* __restrict__ Kh, const bf16* __restrict__ Vh, ...
;     ...
;   for (int j = 0; j < NTL; ++j) {
;     const bool has1 = (j + 1 < NTL), has2 = (j + 2 < NTL);
;     if (has2 && MODE == 0) SLOADW(s_wr, (j + 2) * KVBLK);
;     bf16x8 f0, f1, f2, f3;
;     if (has1) qkt(pn0, pn1, lds + s_nxt * SHM_BUF + SHM_KV, qr, r32, hi, map, negM);
;     sm_half<MODE>(pc0, lsum, f0, f1);
;     const char* vt = lds + s_cur * SHM_BUF;
;     pv_b128(o, vt + voff[0], f0); pv_b128(o, vt + voff[1], f1);
;     sm_half<MODE>(pc1, lsum, f2, f3);
;     pv_b128(o, vt + voff[2], f2); pv_b128(o, vt + voff[3], f3);
;     asm volatile("s_waitcnt vmcnt(0)" ::: "memory");
;     __syncthreads();
;     pc0 = pn0; pc1 = pn1;
;     const int t = s_cur; s_cur = s_nxt; s_nxt = s_wr; s_wr = t;
;   }
	s_barrier
	s_waitcnt lgkmcnt(7)
	v_mfma_f32_32x32x16_bf16 v[66:81], v[166:169], v[114:117], v[66:81]
	s_add_u32 s16, s14, 0x8000
	s_mov_b32 m0, s16
	ds_read_b128 v[212:215], v234 offset:0
	global_load_lds_dwordx4 v[246:247], off
	v_exp_f32_e32 v130, v82
	v_exp_f32_e32 v131, v83
	v_add_f32_e32 v190, v190, v130
	s_waitcnt lgkmcnt(7)
	v_mfma_f32_32x32x16_bf16 v[50:65], v[170:173], v[114:117], v[50:65]
	s_add_u32 s16, s14, 0xa000
	s_mov_b32 m0, s16
	ds_read_b128 v[216:219], v234 offset:4096
	global_load_lds_dwordx4 v[250:251], off
	v_lshl_add_u64 v[246:247], v[246:247], 0, s[18:19]
	v_lshl_add_u64 v[250:251], v[250:251], 0, s[18:19]
	v_exp_f32_e32 v132, v84
	v_exp_f32_e32 v133, v85
	v_add_f32_e32 v191, v191, v131
	s_waitcnt lgkmcnt(7)
	v_mfma_f32_32x32x16_bf16 v[34:49], v[178:181], v[114:117], v[34:49]
	s_add_u32 s16, s14, 0x10000
	s_mov_b32 m0, s16
	ds_read_b128 v[220:223], v234 offset:8192
	global_load_lds_dwordx4 v[236:237], off
	v_exp_f32_e32 v134, v86
	v_exp_f32_e32 v135, v87
	v_add_f32_e32 v190, v190, v132
	s_waitcnt lgkmcnt(7)
	v_mfma_f32_32x32x16_bf16 v[18:33], v[182:185], v[114:117], v[18:33]
	s_add_u32 s16, s14, 0x12000
	s_mov_b32 m0, s16
	ds_read_b128 v[224:227], v234 offset:12288
	global_load_lds_dwordx4 v[248:249], off
	v_lshl_add_u64 v[236:237], v[236:237], 0, s[18:19]
	v_lshl_add_u64 v[248:249], v[248:249], 0, s[18:19]
	v_exp_f32_e32 v136, v88
	v_exp_f32_e32 v137, v89
	v_add_f32_e32 v191, v191, v133
	s_waitcnt lgkmcnt(7)
	v_mfma_f32_32x32x16_bf16 v[66:81], v[186:189], v[118:121], v[66:81]
	ds_read_b128 v[166:169], v235 offset:0
	v_exp_f32_e32 v138, v90
	v_exp_f32_e32 v139, v91
	v_cvt_pk_bf16_f32 v114, v130, v131
	s_waitcnt lgkmcnt(7)
	v_mfma_f32_32x32x16_bf16 v[50:65], v[200:203], v[118:121], v[50:65]
	ds_read_b128 v[170:173], v235 offset:4096
	v_exp_f32_e32 v140, v92
	v_exp_f32_e32 v141, v93
	v_cvt_pk_bf16_f32 v115, v132, v133
	s_waitcnt lgkmcnt(7)
	v_mfma_f32_32x32x16_bf16 v[34:49], v[204:207], v[118:121], v[34:49]
	ds_read_b128 v[178:181], v235 offset:8192
	v_exp_f32_e32 v142, v94
	v_exp_f32_e32 v143, v95
	v_add_f32_e32 v190, v190, v134
	s_waitcnt lgkmcnt(7)
	v_mfma_f32_32x32x16_bf16 v[18:33], v[208:211], v[118:121], v[18:33]
	ds_read_b128 v[182:185], v235 offset:12288
	v_exp_f32_e32 v144, v96
	v_exp_f32_e32 v145, v97
	v_add_f32_e32 v191, v191, v135
	s_waitcnt lgkmcnt(7)
	v_mfma_f32_32x32x16_bf16 v[66:81], v[212:215], v[122:125], v[66:81]
	ds_read_b128 v[186:189], v228 offset:32768
	v_exp_f32_e32 v238, v98
	v_exp_f32_e32 v239, v99
	v_cvt_pk_bf16_f32 v116, v134, v135
	s_waitcnt lgkmcnt(7)
	v_mfma_f32_32x32x16_bf16 v[50:65], v[216:219], v[122:125], v[50:65]
	ds_read_b128 v[200:203], v229 offset:32768
	v_exp_f32_e32 v240, v100
	v_exp_f32_e32 v241, v101
	v_add_f32_e32 v190, v190, v136
	s_waitcnt lgkmcnt(7)
	v_mfma_f32_32x32x16_bf16 v[34:49], v[220:223], v[122:125], v[34:49]
	ds_read_b128 v[204:207], v230 offset:32768
	v_exp_f32_e32 v242, v102
	v_exp_f32_e32 v243, v103
	v_add_f32_e32 v191, v191, v137
	s_waitcnt lgkmcnt(7)
	v_mfma_f32_32x32x16_bf16 v[18:33], v[224:227], v[122:125], v[18:33]
	ds_read_b128 v[208:211], v231 offset:32768
	v_exp_f32_e32 v244, v104
	v_exp_f32_e32 v245, v105
	v_cvt_pk_bf16_f32 v117, v136, v137
	s_waitcnt lgkmcnt(7)
	v_mfma_f32_32x32x16_bf16 v[66:81], v[166:169], v[126:129], v[66:81]
	ds_read_b128 v[212:215], v228 offset:40960
	v_exp_f32_e32 v130, v106
	v_exp_f32_e32 v131, v107
	v_add_f32_e32 v190, v190, v138
	s_waitcnt lgkmcnt(7)
	v_mfma_f32_32x32x16_bf16 v[50:65], v[170:173], v[126:129], v[50:65]
	ds_read_b128 v[216:219], v229 offset:40960
	v_exp_f32_e32 v132, v108
	v_exp_f32_e32 v133, v109
	v_add_f32_e32 v191, v191, v139
	s_waitcnt lgkmcnt(7)
	v_mfma_f32_32x32x16_bf16 v[34:49], v[178:181], v[126:129], v[34:49]
	ds_read_b128 v[220:223], v230 offset:40960
	v_exp_f32_e32 v134, v110
	v_exp_f32_e32 v135, v111
	v_add_f32_e32 v190, v190, v140
	s_waitcnt lgkmcnt(7)
	v_mfma_f32_32x32x16_bf16 v[18:33], v[182:185], v[126:129], v[18:33]
	ds_read_b128 v[224:227], v231 offset:40960
	v_exp_f32_e32 v136, v112
	v_exp_f32_e32 v137, v113
	v_add_f32_e32 v191, v191, v141
	s_waitcnt lgkmcnt(7)
	v_mfma_f32_32x32x16_bf16 v[82:97], v[186:189], v[158:161], v[0:15]
	ds_read_b128 v[166:169], v232 offset:16384
	v_cvt_pk_bf16_f32 v118, v138, v139
	v_cvt_pk_bf16_f32 v119, v140, v141
	v_add_f32_e32 v190, v190, v142
	v_add_f32_e32 v191, v191, v143
	s_waitcnt lgkmcnt(7)
	v_mfma_f32_32x32x16_bf16 v[82:97], v[200:203], v[154:157], v[82:97]
	ds_read_b128 v[170:173], v232 offset:20480
	v_cvt_pk_bf16_f32 v120, v142, v143
	v_add_f32_e32 v190, v190, v144
	v_add_f32_e32 v191, v191, v145
	v_cvt_pk_bf16_f32 v121, v144, v145
	s_waitcnt lgkmcnt(7)
	v_mfma_f32_32x32x16_bf16 v[82:97], v[204:207], v[150:153], v[82:97]
	ds_read_b128 v[178:181], v232 offset:24576
	v_add_f32_e32 v190, v190, v238
	v_add_f32_e32 v191, v191, v239
	v_cvt_pk_bf16_f32 v122, v238, v239
	v_add_f32_e32 v190, v190, v240
	s_waitcnt lgkmcnt(7)
	v_mfma_f32_32x32x16_bf16 v[82:97], v[208:211], v[146:149], v[82:97]
	ds_read_b128 v[182:185], v232 offset:28672
	v_add_f32_e32 v191, v191, v241
	v_cvt_pk_bf16_f32 v123, v240, v241
	v_add_f32_e32 v190, v190, v242
	v_add_f32_e32 v191, v191, v243
	s_waitcnt lgkmcnt(7)
	v_mfma_f32_32x32x16_bf16 v[98:113], v[212:215], v[158:161], v[0:15]
	ds_read_b128 v[186:189], v233 offset:16384
	v_cvt_pk_bf16_f32 v124, v242, v243
	v_add_f32_e32 v190, v190, v244
	v_add_f32_e32 v191, v191, v245
	v_cvt_pk_bf16_f32 v125, v244, v245
	s_waitcnt lgkmcnt(7)
	v_mfma_f32_32x32x16_bf16 v[98:113], v[216:219], v[154:157], v[98:113]
	ds_read_b128 v[200:203], v233 offset:20480
	v_add_f32_e32 v190, v190, v130
	v_add_f32_e32 v191, v191, v131
	v_cvt_pk_bf16_f32 v126, v130, v131
	v_add_f32_e32 v190, v190, v132
	s_waitcnt lgkmcnt(7)
	v_mfma_f32_32x32x16_bf16 v[98:113], v[220:223], v[150:153], v[98:113]
	ds_read_b128 v[204:207], v233 offset:24576
	v_add_f32_e32 v191, v191, v133
	v_cvt_pk_bf16_f32 v127, v132, v133
	v_add_f32_e32 v190, v190, v134
	v_add_f32_e32 v191, v191, v135
	s_waitcnt lgkmcnt(7)
	v_mfma_f32_32x32x16_bf16 v[98:113], v[224:227], v[146:149], v[98:113]
	ds_read_b128 v[208:211], v233 offset:28672
	v_cvt_pk_bf16_f32 v128, v134, v135
	v_add_f32_e32 v190, v190, v136
	v_add_f32_e32 v191, v191, v137
	v_cvt_pk_bf16_f32 v129, v136, v137
	s_waitcnt vmcnt(0) lgkmcnt(0)
	s_barrier
; template <int MODE> __device__ __forceinline__ void sm_half(f32x16& p, float& lsum, bf16x8& f0, bf16x8& f1) {
;   if (MODE != 3) {
; #pragma unroll
;   for (int r = 0; r < 16; ++r) p[r] = __builtin_amdgcn_exp2f(p[r]);
;   }
;   float s0 = 0, s1 = 0;
; #pragma unroll
;   for (int r = 0; r < 16; r += 2) { s0 += p[r]; s1 += p[r + 1]; }
;   lsum += s0 + s1;
;   u32x4 w0 = {cvtpk(p[0], p[1]), cvtpk(p[2], p[3]), cvtpk(p[4], p[5]), cvtpk(p[6], p[7])};
;   u32x4 w1 = {cvtpk(p[8], p[9]), cvtpk(p[10], p[11]), cvtpk(p[12], p[13]), cvtpk(p[14], p[15])};
;   f0 = *reinterpret_cast<bf16x8*>(&w0); f1 = *reinterpret_cast<bf16x8*>(&w1);
; template <int MODE> __device__ __forceinline__ void diff_attn_item(const bf16* __restrict__ Qb, const bf16* __restrict__ Kh, const bf16* __restrict__ Vh, ...
;     ...
;   for (int j = 0; j < NTL; ++j) {
;     const bool has1 = (j + 1 < NTL), has2 = (j + 2 < NTL);
;     if (has2 && MODE == 0) SLOADW(s_wr, (j + 2) * KVBLK);
;     bf16x8 f0, f1, f2, f3;
;     if (has1) qkt(pn0, pn1, lds + s_nxt * SHM_BUF + SHM_KV, qr, r32, hi, map, negM);
;     sm_half<MODE>(pc0, lsum, f0, f1);
;     const char* vt = lds + s_cur * SHM_BUF;
;     pv_b128(o, vt + voff[0], f0); pv_b128(o, vt + voff[1], f1);
;     sm_half<MODE>(pc1, lsum, f2, f3);
;     pv_b128(o, vt + voff[2], f2); pv_b128(o, vt + voff[3], f3);
;     asm volatile("s_waitcnt vmcnt(0)" ::: "memory");
;     __syncthreads();
;     pc0 = pn0; pc1 = pn1;
;     const int t = s_cur; s_cur = s_nxt; s_nxt = s_wr; s_wr = t;
;   }
	s_waitcnt lgkmcnt(7)
	v_mfma_f32_32x32x16_bf16 v[66:81], v[166:169], v[114:117], v[66:81]
	s_add_u32 s16, s14, 0x0
	s_mov_b32 m0, s16
	ds_read_b128 v[212:215], v234 offset:16384
	global_load_lds_dwordx4 v[246:247], off
	v_exp_f32_e32 v130, v82
	v_exp_f32_e32 v131, v83
	v_add_f32_e32 v190, v190, v130
	s_waitcnt lgkmcnt(7)
	v_mfma_f32_32x32x16_bf16 v[50:65], v[170:173], v[114:117], v[50:65]
	s_add_u32 s16, s14, 0x2000
	s_mov_b32 m0, s16
	ds_read_b128 v[216:219], v234 offset:20480
	global_load_lds_dwordx4 v[250:251], off
	v_lshl_add_u64 v[246:247], v[246:247], 0, s[18:19]
	v_lshl_add_u64 v[250:251], v[250:251], 0, s[18:19]
	v_exp_f32_e32 v132, v84
	v_exp_f32_e32 v133, v85
	v_add_f32_e32 v191, v191, v131
	s_waitcnt lgkmcnt(7)
	v_mfma_f32_32x32x16_bf16 v[34:49], v[178:181], v[114:117], v[34:49]
	s_add_u32 s16, s14, 0x14000
	s_mov_b32 m0, s16
	ds_read_b128 v[220:223], v234 offset:24576
	global_load_lds_dwordx4 v[236:237], off
	v_exp_f32_e32 v134, v86
	v_exp_f32_e32 v135, v87
	v_add_f32_e32 v190, v190, v132
	s_waitcnt lgkmcnt(7)
	v_mfma_f32_32x32x16_bf16 v[18:33], v[182:185], v[114:117], v[18:33]
	s_add_u32 s16, s14, 0x16000
	s_mov_b32 m0, s16
	ds_read_b128 v[224:227], v234 offset:28672
	global_load_lds_dwordx4 v[248:249], off
	v_lshl_add_u64 v[236:237], v[236:237], 0, s[18:19]
	v_lshl_add_u64 v[248:249], v[248:249], 0, s[18:19]
	v_exp_f32_e32 v136, v88
	v_exp_f32_e32 v137, v89
	v_add_f32_e32 v191, v191, v133
	s_waitcnt lgkmcnt(7)
	v_mfma_f32_32x32x16_bf16 v[66:81], v[186:189], v[118:121], v[66:81]
	ds_read_b128 v[166:169], v235 offset:16384
	v_exp_f32_e32 v138, v90
	v_exp_f32_e32 v139, v91
	v_cvt_pk_bf16_f32 v114, v130, v131
	s_waitcnt lgkmcnt(7)
	v_mfma_f32_32x32x16_bf16 v[50:65], v[200:203], v[118:121], v[50:65]
	ds_read_b128 v[170:173], v235 offset:20480
	v_exp_f32_e32 v140, v92
	v_exp_f32_e32 v141, v93
	v_cvt_pk_bf16_f32 v115, v132, v133
	s_waitcnt lgkmcnt(7)
	v_mfma_f32_32x32x16_bf16 v[34:49], v[204:207], v[118:121], v[34:49]
	ds_read_b128 v[178:181], v235 offset:24576
	v_exp_f32_e32 v142, v94
	v_exp_f32_e32 v143, v95
	v_add_f32_e32 v190, v190, v134
	s_waitcnt lgkmcnt(7)
	v_mfma_f32_32x32x16_bf16 v[18:33], v[208:211], v[118:121], v[18:33]
	ds_read_b128 v[182:185], v235 offset:28672
	v_exp_f32_e32 v144, v96
	v_exp_f32_e32 v145, v97
	v_add_f32_e32 v191, v191, v135
	s_waitcnt lgkmcnt(7)
	v_mfma_f32_32x32x16_bf16 v[66:81], v[212:215], v[122:125], v[66:81]
	ds_read_b128 v[186:189], v228 offset:0
	v_exp_f32_e32 v238, v98
	v_exp_f32_e32 v239, v99
	v_cvt_pk_bf16_f32 v116, v134, v135
	s_waitcnt lgkmcnt(7)
	v_mfma_f32_32x32x16_bf16 v[50:65], v[216:219], v[122:125], v[50:65]
	ds_read_b128 v[200:203], v229 offset:0
	v_exp_f32_e32 v240, v100
	v_exp_f32_e32 v241, v101
	v_add_f32_e32 v190, v190, v136
	s_waitcnt lgkmcnt(7)
	v_mfma_f32_32x32x16_bf16 v[34:49], v[220:223], v[122:125], v[34:49]
	ds_read_b128 v[204:207], v230 offset:0
	v_exp_f32_e32 v242, v102
	v_exp_f32_e32 v243, v103
	v_add_f32_e32 v191, v191, v137
	s_waitcnt lgkmcnt(7)
	v_mfma_f32_32x32x16_bf16 v[18:33], v[224:227], v[122:125], v[18:33]
	ds_read_b128 v[208:211], v231 offset:0
	v_exp_f32_e32 v244, v104
	v_exp_f32_e32 v245, v105
	v_cvt_pk_bf16_f32 v117, v136, v137
	s_waitcnt lgkmcnt(7)
	v_mfma_f32_32x32x16_bf16 v[66:81], v[166:169], v[126:129], v[66:81]
	ds_read_b128 v[212:215], v228 offset:8192
	v_exp_f32_e32 v130, v106
	v_exp_f32_e32 v131, v107
	v_add_f32_e32 v190, v190, v138
	s_waitcnt lgkmcnt(7)
	v_mfma_f32_32x32x16_bf16 v[50:65], v[170:173], v[126:129], v[50:65]
	ds_read_b128 v[216:219], v229 offset:8192
	v_exp_f32_e32 v132, v108
	v_exp_f32_e32 v133, v109
	v_add_f32_e32 v191, v191, v139
	s_waitcnt lgkmcnt(7)
	v_mfma_f32_32x32x16_bf16 v[34:49], v[178:181], v[126:129], v[34:49]
	ds_read_b128 v[220:223], v230 offset:8192
	v_exp_f32_e32 v134, v110
	v_exp_f32_e32 v135, v111
	v_add_f32_e32 v190, v190, v140
	s_waitcnt lgkmcnt(7)
	v_mfma_f32_32x32x16_bf16 v[18:33], v[182:185], v[126:129], v[18:33]
	ds_read_b128 v[224:227], v231 offset:8192
	v_exp_f32_e32 v136, v112
	v_exp_f32_e32 v137, v113
	v_add_f32_e32 v191, v191, v141
	s_waitcnt lgkmcnt(7)
	v_mfma_f32_32x32x16_bf16 v[82:97], v[186:189], v[158:161], v[0:15]
	ds_read_b128 v[166:169], v232 offset:32768
	v_cvt_pk_bf16_f32 v118, v138, v139
	v_cvt_pk_bf16_f32 v119, v140, v141
	v_add_f32_e32 v190, v190, v142
	v_add_f32_e32 v191, v191, v143
	s_waitcnt lgkmcnt(7)
	v_mfma_f32_32x32x16_bf16 v[82:97], v[200:203], v[154:157], v[82:97]
	ds_read_b128 v[170:173], v232 offset:36864
	v_cvt_pk_bf16_f32 v120, v142, v143
	v_add_f32_e32 v190, v190, v144
	v_add_f32_e32 v191, v191, v145
	v_cvt_pk_bf16_f32 v121, v144, v145
	s_waitcnt lgkmcnt(7)
	v_mfma_f32_32x32x16_bf16 v[82:97], v[204:207], v[150:153], v[82:97]
	ds_read_b128 v[178:181], v232 offset:40960
	v_add_f32_e32 v190, v190, v238
	v_add_f32_e32 v191, v191, v239
	v_cvt_pk_bf16_f32 v122, v238, v239
	v_add_f32_e32 v190, v190, v240
	s_waitcnt lgkmcnt(7)
	v_mfma_f32_32x32x16_bf16 v[82:97], v[208:211], v[146:149], v[82:97]
	ds_read_b128 v[182:185], v232 offset:45056
	v_add_f32_e32 v191, v191, v241
	v_cvt_pk_bf16_f32 v123, v240, v241
	v_add_f32_e32 v190, v190, v242
	v_add_f32_e32 v191, v191, v243
	s_waitcnt lgkmcnt(7)
	v_mfma_f32_32x32x16_bf16 v[98:113], v[212:215], v[158:161], v[0:15]
	ds_read_b128 v[186:189], v233 offset:32768
	v_cvt_pk_bf16_f32 v124, v242, v243
	v_add_f32_e32 v190, v190, v244
	v_add_f32_e32 v191, v191, v245
	v_cvt_pk_bf16_f32 v125, v244, v245
	s_waitcnt lgkmcnt(7)
	v_mfma_f32_32x32x16_bf16 v[98:113], v[216:219], v[154:157], v[98:113]
	ds_read_b128 v[200:203], v233 offset:36864
	v_add_f32_e32 v190, v190, v130
	v_add_f32_e32 v191, v191, v131
	v_cvt_pk_bf16_f32 v126, v130, v131
	v_add_f32_e32 v190, v190, v132
	s_waitcnt lgkmcnt(7)
	v_mfma_f32_32x32x16_bf16 v[98:113], v[220:223], v[150:153], v[98:113]
	ds_read_b128 v[204:207], v233 offset:40960
	v_add_f32_e32 v191, v191, v133
	v_cvt_pk_bf16_f32 v127, v132, v133
	v_add_f32_e32 v190, v190, v134
	v_add_f32_e32 v191, v191, v135
	s_waitcnt lgkmcnt(7)
	v_mfma_f32_32x32x16_bf16 v[98:113], v[224:227], v[146:149], v[98:113]
	ds_read_b128 v[208:211], v233 offset:45056
	v_cvt_pk_bf16_f32 v128, v134, v135
	v_add_f32_e32 v190, v190, v136
	v_add_f32_e32 v191, v191, v137
	v_cvt_pk_bf16_f32 v129, v136, v137
	s_waitcnt vmcnt(0) lgkmcnt(0)
	s_barrier
; template <int MODE> __device__ __forceinline__ void sm_half(f32x16& p, float& lsum, bf16x8& f0, bf16x8& f1) {
;   if (MODE != 3) {
; #pragma unroll
;   for (int r = 0; r < 16; ++r) p[r] = __builtin_amdgcn_exp2f(p[r]);
;   }
;   float s0 = 0, s1 = 0;
; #pragma unroll
;   for (int r = 0; r < 16; r += 2) { s0 += p[r]; s1 += p[r + 1]; }
;   lsum += s0 + s1;
;   u32x4 w0 = {cvtpk(p[0], p[1]), cvtpk(p[2], p[3]), cvtpk(p[4], p[5]), cvtpk(p[6], p[7])};
;   u32x4 w1 = {cvtpk(p[8], p[9]), cvtpk(p[10], p[11]), cvtpk(p[12], p[13]), cvtpk(p[14], p[15])};
;   f0 = *reinterpret_cast<bf16x8*>(&w0); f1 = *reinterpret_cast<bf16x8*>(&w1);
; template <int MODE> __device__ __forceinline__ void diff_attn_item(const bf16* __restrict__ Qb, const bf16* __restrict__ Kh, const bf16* __restrict__ Vh, ...
;     ...
;   for (int j = 0; j < NTL; ++j) {
;     const bool has1 = (j + 1 < NTL), has2 = (j + 2 < NTL);
;     if (has2 && MODE == 0) SLOADW(s_wr, (j + 2) * KVBLK);
;     bf16x8 f0, f1, f2, f3;
;     if (has1) qkt(pn0, pn1, lds + s_nxt * SHM_BUF + SHM_KV, qr, r32, hi, map, negM);
;     sm_half<MODE>(pc0, lsum, f0, f1);
;     const char* vt = lds + s_cur * SHM_BUF;
;     pv_b128(o, vt + voff[0], f0); pv_b128(o, vt + voff[1], f1);
;     sm_half<MODE>(pc1, lsum, f2, f3);
;     pv_b128(o, vt + voff[2], f2); pv_b128(o, vt + voff[3], f3);
;     asm volatile("s_waitcnt vmcnt(0)" ::: "memory");
;     __syncthreads();
;     pc0 = pn0; pc1 = pn1;
;     const int t = s_cur; s_cur = s_nxt; s_nxt = s_wr; s_wr = t;
;   }
	s_waitcnt lgkmcnt(7)
	v_mfma_f32_32x32x16_bf16 v[66:81], v[166:169], v[114:117], v[66:81]
	s_add_u32 s16, s14, 0x4000
	s_mov_b32 m0, s16
	ds_read_b128 v[212:215], v234 offset:32768
	global_load_lds_dwordx4 v[246:247], off
	v_exp_f32_e32 v130, v82
	v_exp_f32_e32 v131, v83
	v_add_f32_e32 v190, v190, v130
	s_waitcnt lgkmcnt(7)
	v_mfma_f32_32x32x16_bf16 v[50:65], v[170:173], v[114:117], v[50:65]
	s_add_u32 s16, s14, 0x6000
	s_mov_b32 m0, s16
	ds_read_b128 v[216:219], v234 offset:36864
	global_load_lds_dwordx4 v[250:251], off
	v_lshl_add_u64 v[246:247], v[246:247], 0, s[18:19]
	v_lshl_add_u64 v[250:251], v[250:251], 0, s[18:19]
	v_exp_f32_e32 v132, v84
	v_exp_f32_e32 v133, v85
	v_add_f32_e32 v191, v191, v131
	s_waitcnt lgkmcnt(7)
	v_mfma_f32_32x32x16_bf16 v[34:49], v[178:181], v[114:117], v[34:49]
	ds_read_b128 v[220:223], v234 offset:40960
	v_exp_f32_e32 v134, v86
	v_exp_f32_e32 v135, v87
	v_add_f32_e32 v190, v190, v132
	s_waitcnt lgkmcnt(7)
	v_mfma_f32_32x32x16_bf16 v[18:33], v[182:185], v[114:117], v[18:33]
	ds_read_b128 v[224:227], v234 offset:45056
	v_exp_f32_e32 v136, v88
	v_exp_f32_e32 v137, v89
	v_add_f32_e32 v191, v191, v133
	s_waitcnt lgkmcnt(7)
	v_mfma_f32_32x32x16_bf16 v[66:81], v[186:189], v[118:121], v[66:81]
	ds_read_b128 v[166:169], v235 offset:32768
	v_exp_f32_e32 v138, v90
	v_exp_f32_e32 v139, v91
	v_cvt_pk_bf16_f32 v114, v130, v131
	s_waitcnt lgkmcnt(7)
	v_mfma_f32_32x32x16_bf16 v[50:65], v[200:203], v[118:121], v[50:65]
	ds_read_b128 v[170:173], v235 offset:36864
	v_exp_f32_e32 v140, v92
	v_exp_f32_e32 v141, v93
	v_cvt_pk_bf16_f32 v115, v132, v133
	s_waitcnt lgkmcnt(7)
	v_mfma_f32_32x32x16_bf16 v[34:49], v[204:207], v[118:121], v[34:49]
	ds_read_b128 v[178:181], v235 offset:40960
	v_exp_f32_e32 v142, v94
	v_exp_f32_e32 v143, v95
	v_add_f32_e32 v190, v190, v134
	s_waitcnt lgkmcnt(7)
	v_mfma_f32_32x32x16_bf16 v[18:33], v[208:211], v[118:121], v[18:33]
	ds_read_b128 v[182:185], v235 offset:45056
	v_exp_f32_e32 v144, v96
	v_exp_f32_e32 v145, v97
	v_add_f32_e32 v191, v191, v135
	s_waitcnt lgkmcnt(7)
	v_mfma_f32_32x32x16_bf16 v[66:81], v[212:215], v[122:125], v[66:81]
	ds_read_b128 v[186:189], v228 offset:16384
	v_exp_f32_e32 v238, v98
	v_exp_f32_e32 v239, v99
	v_cvt_pk_bf16_f32 v116, v134, v135
	s_waitcnt lgkmcnt(7)
	v_mfma_f32_32x32x16_bf16 v[50:65], v[216:219], v[122:125], v[50:65]
	ds_read_b128 v[200:203], v229 offset:16384
	v_exp_f32_e32 v240, v100
	v_exp_f32_e32 v241, v101
	v_add_f32_e32 v190, v190, v136
	s_waitcnt lgkmcnt(7)
	v_mfma_f32_32x32x16_bf16 v[34:49], v[220:223], v[122:125], v[34:49]
	ds_read_b128 v[204:207], v230 offset:16384
	v_exp_f32_e32 v242, v102
	v_exp_f32_e32 v243, v103
	v_add_f32_e32 v191, v191, v137
	s_waitcnt lgkmcnt(7)
	v_mfma_f32_32x32x16_bf16 v[18:33], v[224:227], v[122:125], v[18:33]
	ds_read_b128 v[208:211], v231 offset:16384
	v_exp_f32_e32 v244, v104
	v_exp_f32_e32 v245, v105
	v_cvt_pk_bf16_f32 v117, v136, v137
	s_waitcnt lgkmcnt(7)
	v_mfma_f32_32x32x16_bf16 v[66:81], v[166:169], v[126:129], v[66:81]
	ds_read_b128 v[212:215], v228 offset:24576
	v_exp_f32_e32 v130, v106
	v_exp_f32_e32 v131, v107
	v_add_f32_e32 v190, v190, v138
	s_waitcnt lgkmcnt(7)
	v_mfma_f32_32x32x16_bf16 v[50:65], v[170:173], v[126:129], v[50:65]
	ds_read_b128 v[216:219], v229 offset:24576
	v_exp_f32_e32 v132, v108
	v_exp_f32_e32 v133, v109
	v_add_f32_e32 v191, v191, v139
	s_waitcnt lgkmcnt(7)
	v_mfma_f32_32x32x16_bf16 v[34:49], v[178:181], v[126:129], v[34:49]
	ds_read_b128 v[220:223], v230 offset:24576
	v_exp_f32_e32 v134, v110
	v_exp_f32_e32 v135, v111
	v_add_f32_e32 v190, v190, v140
	s_waitcnt lgkmcnt(7)
	v_mfma_f32_32x32x16_bf16 v[18:33], v[182:185], v[126:129], v[18:33]
	ds_read_b128 v[224:227], v231 offset:24576
	v_exp_f32_e32 v136, v112
	v_exp_f32_e32 v137, v113
	v_add_f32_e32 v191, v191, v141
	s_waitcnt lgkmcnt(7)
	v_mfma_f32_32x32x16_bf16 v[82:97], v[186:189], v[158:161], v[0:15]
	ds_read_b128 v[166:169], v232 offset:0
	v_cvt_pk_bf16_f32 v118, v138, v139
	v_cvt_pk_bf16_f32 v119, v140, v141
	v_add_f32_e32 v190, v190, v142
	v_add_f32_e32 v191, v191, v143
	s_waitcnt lgkmcnt(7)
	v_mfma_f32_32x32x16_bf16 v[82:97], v[200:203], v[154:157], v[82:97]
	ds_read_b128 v[170:173], v232 offset:4096
	v_cvt_pk_bf16_f32 v120, v142, v143
	v_add_f32_e32 v190, v190, v144
	v_add_f32_e32 v191, v191, v145
	v_cvt_pk_bf16_f32 v121, v144, v145
	s_waitcnt lgkmcnt(7)
	v_mfma_f32_32x32x16_bf16 v[82:97], v[204:207], v[150:153], v[82:97]
	ds_read_b128 v[178:181], v232 offset:8192
	v_add_f32_e32 v190, v190, v238
	v_add_f32_e32 v191, v191, v239
	v_cvt_pk_bf16_f32 v122, v238, v239
	v_add_f32_e32 v190, v190, v240
	s_waitcnt lgkmcnt(7)
	v_mfma_f32_32x32x16_bf16 v[82:97], v[208:211], v[146:149], v[82:97]
	ds_read_b128 v[182:185], v232 offset:12288
	v_add_f32_e32 v191, v191, v241
	v_cvt_pk_bf16_f32 v123, v240, v241
	v_add_f32_e32 v190, v190, v242
	v_add_f32_e32 v191, v191, v243
	s_waitcnt lgkmcnt(7)
	v_mfma_f32_32x32x16_bf16 v[98:113], v[212:215], v[158:161], v[0:15]
	ds_read_b128 v[186:189], v233 offset:0
	v_cvt_pk_bf16_f32 v124, v242, v243
	v_add_f32_e32 v190, v190, v244
	v_add_f32_e32 v191, v191, v245
	v_cvt_pk_bf16_f32 v125, v244, v245
	s_waitcnt lgkmcnt(7)
	v_mfma_f32_32x32x16_bf16 v[98:113], v[216:219], v[154:157], v[98:113]
	ds_read_b128 v[200:203], v233 offset:4096
	v_add_f32_e32 v190, v190, v130
	v_add_f32_e32 v191, v191, v131
	v_cvt_pk_bf16_f32 v126, v130, v131
	v_add_f32_e32 v190, v190, v132
	s_waitcnt lgkmcnt(7)
	v_mfma_f32_32x32x16_bf16 v[98:113], v[220:223], v[150:153], v[98:113]
	ds_read_b128 v[204:207], v233 offset:8192
	v_add_f32_e32 v191, v191, v133
	v_cvt_pk_bf16_f32 v127, v132, v133
	v_add_f32_e32 v190, v190, v134
	v_add_f32_e32 v191, v191, v135
	s_waitcnt lgkmcnt(7)
	v_mfma_f32_32x32x16_bf16 v[98:113], v[224:227], v[146:149], v[98:113]
	ds_read_b128 v[208:211], v233 offset:12288
	v_cvt_pk_bf16_f32 v128, v134, v135
	v_add_f32_e32 v190, v190, v136
	v_add_f32_e32 v191, v191, v137
	v_cvt_pk_bf16_f32 v129, v136, v137
	s_waitcnt vmcnt(0) lgkmcnt(0)
	s_barrier
; template <int MODE> __device__ __forceinline__ void sm_half(f32x16& p, float& lsum, bf16x8& f0, bf16x8& f1) {
;   if (MODE != 3) {
; #pragma unroll
;   for (int r = 0; r < 16; ++r) p[r] = __builtin_amdgcn_exp2f(p[r]);
;   }
;   float s0 = 0, s1 = 0;
; #pragma unroll
;   for (int r = 0; r < 16; r += 2) { s0 += p[r]; s1 += p[r + 1]; }
;   lsum += s0 + s1;
;   u32x4 w0 = {cvtpk(p[0], p[1]), cvtpk(p[2], p[3]), cvtpk(p[4], p[5]), cvtpk(p[6], p[7])};
;   u32x4 w1 = {cvtpk(p[8], p[9]), cvtpk(p[10], p[11]), cvtpk(p[12], p[13]), cvtpk(p[14], p[15])};
;   f0 = *reinterpret_cast<bf16x8*>(&w0); f1 = *reinterpret_cast<bf16x8*>(&w1);
; template <int MODE> __device__ __forceinline__ void diff_attn_item(const bf16* __restrict__ Qb, const bf16* __restrict__ Kh, const bf16* __restrict__ Vh, ...
;     ...
;   for (int j = 0; j < NTL; ++j) {
;     const bool has1 = (j + 1 < NTL), has2 = (j + 2 < NTL);
;     if (has2 && MODE == 0) SLOADW(s_wr, (j + 2) * KVBLK);
;     bf16x8 f0, f1, f2, f3;
;     if (has1) qkt(pn0, pn1, lds + s_nxt * SHM_BUF + SHM_KV, qr, r32, hi, map, negM);
;     sm_half<MODE>(pc0, lsum, f0, f1);
;     const char* vt = lds + s_cur * SHM_BUF;
;     pv_b128(o, vt + voff[0], f0); pv_b128(o, vt + voff[1], f1);
;     sm_half<MODE>(pc1, lsum, f2, f3);
;     pv_b128(o, vt + voff[2], f2); pv_b128(o, vt + voff[3], f3);
;     asm volatile("s_waitcnt vmcnt(0)" ::: "memory");
;     __syncthreads();
;     pc0 = pn0; pc1 = pn1;
;     const int t = s_cur; s_cur = s_nxt; s_nxt = s_wr; s_wr = t;
;   }
	s_waitcnt lgkmcnt(7)
	v_mfma_f32_32x32x16_bf16 v[66:81], v[166:169], v[114:117], v[66:81]
	s_add_u32 s16, s14, 0x8000
	s_mov_b32 m0, s16
	ds_read_b128 v[212:215], v234 offset:0
	global_load_lds_dwordx4 v[246:247], off
	v_exp_f32_e32 v130, v82
	v_exp_f32_e32 v131, v83
	v_add_f32_e32 v190, v190, v130
	s_waitcnt lgkmcnt(7)
	v_mfma_f32_32x32x16_bf16 v[50:65], v[170:173], v[114:117], v[50:65]
	s_add_u32 s16, s14, 0xa000
	s_mov_b32 m0, s16
	ds_read_b128 v[216:219], v234 offset:4096
	global_load_lds_dwordx4 v[250:251], off
	v_lshl_add_u64 v[246:247], v[246:247], 0, s[18:19]
	v_lshl_add_u64 v[250:251], v[250:251], 0, s[18:19]
	v_exp_f32_e32 v132, v84
	v_exp_f32_e32 v133, v85
	v_add_f32_e32 v191, v191, v131
	s_waitcnt lgkmcnt(7)
	v_mfma_f32_32x32x16_bf16 v[34:49], v[178:181], v[114:117], v[34:49]
	ds_read_b128 v[220:223], v234 offset:8192
	v_exp_f32_e32 v134, v86
	v_exp_f32_e32 v135, v87
	v_add_f32_e32 v190, v190, v132
	s_waitcnt lgkmcnt(7)
	v_mfma_f32_32x32x16_bf16 v[18:33], v[182:185], v[114:117], v[18:33]
	ds_read_b128 v[224:227], v234 offset:12288
	v_exp_f32_e32 v136, v88
	v_exp_f32_e32 v137, v89
	v_add_f32_e32 v191, v191, v133
	s_waitcnt lgkmcnt(7)
	v_mfma_f32_32x32x16_bf16 v[66:81], v[186:189], v[118:121], v[66:81]
	ds_read_b128 v[166:169], v235 offset:0
	v_exp_f32_e32 v138, v90
	v_exp_f32_e32 v139, v91
	v_cvt_pk_bf16_f32 v114, v130, v131
	s_waitcnt lgkmcnt(7)
	v_mfma_f32_32x32x16_bf16 v[50:65], v[200:203], v[118:121], v[50:65]
	ds_read_b128 v[170:173], v235 offset:4096
	v_exp_f32_e32 v140, v92
	v_exp_f32_e32 v141, v93
	v_cvt_pk_bf16_f32 v115, v132, v133
	s_waitcnt lgkmcnt(7)
	v_mfma_f32_32x32x16_bf16 v[34:49], v[204:207], v[118:121], v[34:49]
	ds_read_b128 v[178:181], v235 offset:8192
	v_exp_f32_e32 v142, v94
	v_exp_f32_e32 v143, v95
	v_add_f32_e32 v190, v190, v134
	s_waitcnt lgkmcnt(7)
	v_mfma_f32_32x32x16_bf16 v[18:33], v[208:211], v[118:121], v[18:33]
	ds_read_b128 v[182:185], v235 offset:12288
	v_exp_f32_e32 v144, v96
	v_exp_f32_e32 v145, v97
	v_add_f32_e32 v191, v191, v135
	s_waitcnt lgkmcnt(7)
	v_mfma_f32_32x32x16_bf16 v[66:81], v[212:215], v[122:125], v[66:81]
	ds_read_b128 v[186:189], v228 offset:32768
	v_exp_f32_e32 v238, v98
	v_exp_f32_e32 v239, v99
	v_cvt_pk_bf16_f32 v116, v134, v135
	s_waitcnt lgkmcnt(7)
	v_mfma_f32_32x32x16_bf16 v[50:65], v[216:219], v[122:125], v[50:65]
	ds_read_b128 v[200:203], v229 offset:32768
	v_exp_f32_e32 v240, v100
	v_exp_f32_e32 v241, v101
	v_add_f32_e32 v190, v190, v136
	s_waitcnt lgkmcnt(7)
	v_mfma_f32_32x32x16_bf16 v[34:49], v[220:223], v[122:125], v[34:49]
	ds_read_b128 v[204:207], v230 offset:32768
	v_exp_f32_e32 v242, v102
	v_exp_f32_e32 v243, v103
	v_add_f32_e32 v191, v191, v137
	s_waitcnt lgkmcnt(7)
	v_mfma_f32_32x32x16_bf16 v[18:33], v[224:227], v[122:125], v[18:33]
	ds_read_b128 v[208:211], v231 offset:32768
	v_exp_f32_e32 v244, v104
	v_exp_f32_e32 v245, v105
	v_cvt_pk_bf16_f32 v117, v136, v137
	s_waitcnt lgkmcnt(7)
	v_mfma_f32_32x32x16_bf16 v[66:81], v[166:169], v[126:129], v[66:81]
	ds_read_b128 v[212:215], v228 offset:40960
	v_exp_f32_e32 v130, v106
	v_exp_f32_e32 v131, v107
	v_add_f32_e32 v190, v190, v138
	s_waitcnt lgkmcnt(7)
	v_mfma_f32_32x32x16_bf16 v[50:65], v[170:173], v[126:129], v[50:65]
	ds_read_b128 v[216:219], v229 offset:40960
	v_exp_f32_e32 v132, v108
	v_exp_f32_e32 v133, v109
	v_add_f32_e32 v191, v191, v139
	s_waitcnt lgkmcnt(7)
	v_mfma_f32_32x32x16_bf16 v[34:49], v[178:181], v[126:129], v[34:49]
	ds_read_b128 v[220:223], v230 offset:40960
	v_exp_f32_e32 v134, v110
	v_exp_f32_e32 v135, v111
	v_add_f32_e32 v190, v190, v140
	s_waitcnt lgkmcnt(7)
	v_mfma_f32_32x32x16_bf16 v[18:33], v[182:185], v[126:129], v[18:33]
	ds_read_b128 v[224:227], v231 offset:40960
	v_exp_f32_e32 v136, v112
	v_exp_f32_e32 v137, v113
	v_add_f32_e32 v191, v191, v141
	s_waitcnt lgkmcnt(7)
	v_mfma_f32_32x32x16_bf16 v[82:97], v[186:189], v[158:161], v[0:15]
	ds_read_b128 v[166:169], v232 offset:16384
	v_cvt_pk_bf16_f32 v118, v138, v139
	v_cvt_pk_bf16_f32 v119, v140, v141
	v_add_f32_e32 v190, v190, v142
	v_add_f32_e32 v191, v191, v143
	s_waitcnt lgkmcnt(7)
	v_mfma_f32_32x32x16_bf16 v[82:97], v[200:203], v[154:157], v[82:97]
	ds_read_b128 v[170:173], v232 offset:20480
	v_cvt_pk_bf16_f32 v120, v142, v143
	v_add_f32_e32 v190, v190, v144
	v_add_f32_e32 v191, v191, v145
	v_cvt_pk_bf16_f32 v121, v144, v145
	s_waitcnt lgkmcnt(7)
	v_mfma_f32_32x32x16_bf16 v[82:97], v[204:207], v[150:153], v[82:97]
	ds_read_b128 v[178:181], v232 offset:24576
	v_add_f32_e32 v190, v190, v238
	v_add_f32_e32 v191, v191, v239
	v_cvt_pk_bf16_f32 v122, v238, v239
	v_add_f32_e32 v190, v190, v240
	s_waitcnt lgkmcnt(7)
	v_mfma_f32_32x32x16_bf16 v[82:97], v[208:211], v[146:149], v[82:97]
	ds_read_b128 v[182:185], v232 offset:28672
	v_add_f32_e32 v191, v191, v241
	v_cvt_pk_bf16_f32 v123, v240, v241
	v_add_f32_e32 v190, v190, v242
	v_add_f32_e32 v191, v191, v243
	s_waitcnt lgkmcnt(7)
	v_mfma_f32_32x32x16_bf16 v[98:113], v[212:215], v[158:161], v[0:15]
	ds_read_b128 v[186:189], v233 offset:16384
	v_cvt_pk_bf16_f32 v124, v242, v243
	v_add_f32_e32 v190, v190, v244
	v_add_f32_e32 v191, v191, v245
	v_cvt_pk_bf16_f32 v125, v244, v245
	s_waitcnt lgkmcnt(7)
	v_mfma_f32_32x32x16_bf16 v[98:113], v[216:219], v[154:157], v[98:113]
	ds_read_b128 v[200:203], v233 offset:20480
	v_add_f32_e32 v190, v190, v130
	v_add_f32_e32 v191, v191, v131
	v_cvt_pk_bf16_f32 v126, v130, v131
	v_add_f32_e32 v190, v190, v132
	s_waitcnt lgkmcnt(7)
	v_mfma_f32_32x32x16_bf16 v[98:113], v[220:223], v[150:153], v[98:113]
	ds_read_b128 v[204:207], v233 offset:24576
	v_add_f32_e32 v191, v191, v133
	v_cvt_pk_bf16_f32 v127, v132, v133
	v_add_f32_e32 v190, v190, v134
	v_add_f32_e32 v191, v191, v135
	s_waitcnt lgkmcnt(7)
	v_mfma_f32_32x32x16_bf16 v[98:113], v[224:227], v[146:149], v[98:113]
	ds_read_b128 v[208:211], v233 offset:28672
	v_cvt_pk_bf16_f32 v128, v134, v135
	v_add_f32_e32 v190, v190, v136
	v_add_f32_e32 v191, v191, v137
	v_cvt_pk_bf16_f32 v129, v136, v137
	s_waitcnt vmcnt(0) lgkmcnt(0)
	s_barrier
; template <int MODE> __device__ __forceinline__ void sm_half(f32x16& p, float& lsum, bf16x8& f0, bf16x8& f1) {
;   if (MODE != 3) {
; #pragma unroll
;   for (int r = 0; r < 16; ++r) p[r] = __builtin_amdgcn_exp2f(p[r]);
;   }
;   float s0 = 0, s1 = 0;
; #pragma unroll
;   for (int r = 0; r < 16; r += 2) { s0 += p[r]; s1 += p[r + 1]; }
;   lsum += s0 + s1;
;   u32x4 w0 = {cvtpk(p[0], p[1]), cvtpk(p[2], p[3]), cvtpk(p[4], p[5]), cvtpk(p[6], p[7])};
;   u32x4 w1 = {cvtpk(p[8], p[9]), cvtpk(p[10], p[11]), cvtpk(p[12], p[13]), cvtpk(p[14], p[15])};
;   f0 = *reinterpret_cast<bf16x8*>(&w0); f1 = *reinterpret_cast<bf16x8*>(&w1);
; template <int MODE> __device__ __forceinline__ void diff_attn_item(const bf16* __restrict__ Qb, const bf16* __restrict__ Kh, const bf16* __restrict__ Vh, ...
;     ...
;     if (has1) qkt(pn0, pn1, lds + s_nxt * SHM_BUF + SHM_KV, qr, r32, hi, map, negM);
;     sm_half<MODE>(pc0, lsum, f0, f1);
;     const char* vt = lds + s_cur * SHM_BUF;
;     pv_b128(o, vt + voff[0], f0); pv_b128(o, vt + voff[1], f1);
;     sm_half<MODE>(pc1, lsum, f2, f3);
;     pv_b128(o, vt + voff[2], f2); pv_b128(o, vt + voff[3], f3);
;     asm volatile("s_waitcnt vmcnt(0)" ::: "memory");
;     __syncthreads();
;     pc0 = pn0; pc1 = pn1;
;     const int t = s_cur; s_cur = s_nxt; s_nxt = s_wr; s_wr = t;
;   }
;   lsum += __shfl_xor(lsum, 32);
	s_waitcnt lgkmcnt(7)
	v_mfma_f32_32x32x16_bf16 v[66:81], v[166:169], v[114:117], v[66:81]
	ds_read_b128 v[212:215], v234 offset:16384
	v_exp_f32_e32 v130, v82
	v_exp_f32_e32 v131, v83
	v_add_f32_e32 v190, v190, v130
	s_waitcnt lgkmcnt(7)
	v_mfma_f32_32x32x16_bf16 v[50:65], v[170:173], v[114:117], v[50:65]
	ds_read_b128 v[216:219], v234 offset:20480
	v_exp_f32_e32 v132, v84
	v_exp_f32_e32 v133, v85
	v_add_f32_e32 v191, v191, v131
	s_waitcnt lgkmcnt(7)
	v_mfma_f32_32x32x16_bf16 v[34:49], v[178:181], v[114:117], v[34:49]
	ds_read_b128 v[220:223], v234 offset:24576
	v_exp_f32_e32 v134, v86
	v_exp_f32_e32 v135, v87
	v_add_f32_e32 v190, v190, v132
	s_waitcnt lgkmcnt(7)
	v_mfma_f32_32x32x16_bf16 v[18:33], v[182:185], v[114:117], v[18:33]
	ds_read_b128 v[224:227], v234 offset:28672
	v_exp_f32_e32 v136, v88
	v_exp_f32_e32 v137, v89
	v_add_f32_e32 v191, v191, v133
	s_waitcnt lgkmcnt(7)
	v_mfma_f32_32x32x16_bf16 v[66:81], v[186:189], v[118:121], v[66:81]
	ds_read_b128 v[166:169], v235 offset:16384
	v_exp_f32_e32 v138, v90
	v_exp_f32_e32 v139, v91
	v_cvt_pk_bf16_f32 v114, v130, v131
	s_waitcnt lgkmcnt(7)
	v_mfma_f32_32x32x16_bf16 v[50:65], v[200:203], v[118:121], v[50:65]
	ds_read_b128 v[170:173], v235 offset:20480
	v_exp_f32_e32 v140, v92
	v_exp_f32_e32 v141, v93
	v_cvt_pk_bf16_f32 v115, v132, v133
	s_waitcnt lgkmcnt(7)
	v_mfma_f32_32x32x16_bf16 v[34:49], v[204:207], v[118:121], v[34:49]
	ds_read_b128 v[178:181], v235 offset:24576
	v_exp_f32_e32 v142, v94
	v_exp_f32_e32 v143, v95
	v_add_f32_e32 v190, v190, v134
	s_waitcnt lgkmcnt(7)
	v_mfma_f32_32x32x16_bf16 v[18:33], v[208:211], v[118:121], v[18:33]
	ds_read_b128 v[182:185], v235 offset:28672
	v_exp_f32_e32 v144, v96
	v_exp_f32_e32 v145, v97
	v_add_f32_e32 v191, v191, v135
	s_waitcnt lgkmcnt(7)
	v_mfma_f32_32x32x16_bf16 v[66:81], v[212:215], v[122:125], v[66:81]
	ds_read_b128 v[186:189], v233 offset:32768
	v_exp_f32_e32 v238, v98
	v_exp_f32_e32 v239, v99
	v_cvt_pk_bf16_f32 v116, v134, v135
	s_waitcnt lgkmcnt(7)
	v_mfma_f32_32x32x16_bf16 v[50:65], v[216:219], v[122:125], v[50:65]
	ds_read_b128 v[200:203], v233 offset:36864
	v_exp_f32_e32 v240, v100
	v_exp_f32_e32 v241, v101
	v_add_f32_e32 v190, v190, v136
	s_waitcnt lgkmcnt(7)
	v_mfma_f32_32x32x16_bf16 v[34:49], v[220:223], v[122:125], v[34:49]
	ds_read_b128 v[204:207], v233 offset:40960
	v_exp_f32_e32 v242, v102
	v_exp_f32_e32 v243, v103
	v_add_f32_e32 v191, v191, v137
	s_waitcnt lgkmcnt(7)
	v_mfma_f32_32x32x16_bf16 v[18:33], v[224:227], v[122:125], v[18:33]
	ds_read_b128 v[208:211], v233 offset:45056
	v_exp_f32_e32 v244, v104
	v_exp_f32_e32 v245, v105
	v_cvt_pk_bf16_f32 v117, v136, v137
	s_waitcnt lgkmcnt(7)
	v_mfma_f32_32x32x16_bf16 v[66:81], v[166:169], v[126:129], v[66:81]
	ds_read_b128 v[166:169], v232 offset:32768
	v_exp_f32_e32 v130, v106
	v_exp_f32_e32 v131, v107
	v_add_f32_e32 v190, v190, v138
	s_waitcnt lgkmcnt(7)
	v_mfma_f32_32x32x16_bf16 v[50:65], v[170:173], v[126:129], v[50:65]
	ds_read_b128 v[170:173], v232 offset:36864
	v_exp_f32_e32 v132, v108
	v_exp_f32_e32 v133, v109
	v_add_f32_e32 v191, v191, v139
	s_waitcnt lgkmcnt(7)
	v_mfma_f32_32x32x16_bf16 v[34:49], v[178:181], v[126:129], v[34:49]
	ds_read_b128 v[178:181], v232 offset:40960
	v_exp_f32_e32 v134, v110
	v_exp_f32_e32 v135, v111
	v_add_f32_e32 v190, v190, v140
	s_waitcnt lgkmcnt(7)
	v_mfma_f32_32x32x16_bf16 v[18:33], v[182:185], v[126:129], v[18:33]
	ds_read_b128 v[182:185], v232 offset:45056
	v_exp_f32_e32 v136, v112
	v_exp_f32_e32 v137, v113
	v_add_f32_e32 v191, v191, v141
	v_cvt_pk_bf16_f32 v118, v138, v139
	v_cvt_pk_bf16_f32 v119, v140, v141
	v_add_f32_e32 v190, v190, v142
	v_add_f32_e32 v191, v191, v143
	v_cvt_pk_bf16_f32 v120, v142, v143
	v_add_f32_e32 v190, v190, v144
	v_add_f32_e32 v191, v191, v145
	v_cvt_pk_bf16_f32 v121, v144, v145
	v_add_f32_e32 v190, v190, v238
	v_add_f32_e32 v191, v191, v239
	v_cvt_pk_bf16_f32 v122, v238, v239
	v_add_f32_e32 v190, v190, v240
	v_add_f32_e32 v191, v191, v241
	v_cvt_pk_bf16_f32 v123, v240, v241
	v_add_f32_e32 v190, v190, v242
	v_add_f32_e32 v191, v191, v243
	v_cvt_pk_bf16_f32 v124, v242, v243
	v_add_f32_e32 v190, v190, v244
	v_add_f32_e32 v191, v191, v245
	v_cvt_pk_bf16_f32 v125, v244, v245
	v_add_f32_e32 v190, v190, v130
	v_add_f32_e32 v191, v191, v131
	v_cvt_pk_bf16_f32 v126, v130, v131
	v_add_f32_e32 v190, v190, v132
	v_add_f32_e32 v191, v191, v133
	v_cvt_pk_bf16_f32 v127, v132, v133
	v_add_f32_e32 v190, v190, v134
	v_add_f32_e32 v191, v191, v135
	v_cvt_pk_bf16_f32 v128, v134, v135
	v_add_f32_e32 v190, v190, v136
	v_add_f32_e32 v191, v191, v137
	v_cvt_pk_bf16_f32 v129, v136, v137
	s_waitcnt lgkmcnt(3)
	v_mfma_f32_32x32x16_bf16 v[66:81], v[166:169], v[114:117], v[66:81]
	ds_read_b128 v[212:215], v234 offset:32768
	s_waitcnt lgkmcnt(3)
	v_mfma_f32_32x32x16_bf16 v[50:65], v[170:173], v[114:117], v[50:65]
	ds_read_b128 v[216:219], v234 offset:36864
	s_waitcnt lgkmcnt(3)
	v_mfma_f32_32x32x16_bf16 v[34:49], v[178:181], v[114:117], v[34:49]
	ds_read_b128 v[220:223], v234 offset:40960
	s_waitcnt lgkmcnt(3)
	v_mfma_f32_32x32x16_bf16 v[18:33], v[182:185], v[114:117], v[18:33]
	ds_read_b128 v[224:227], v234 offset:45056
	s_waitcnt lgkmcnt(11)
	v_mfma_f32_32x32x16_bf16 v[66:81], v[186:189], v[118:121], v[66:81]
	ds_read_b128 v[166:169], v235 offset:32768
	s_waitcnt lgkmcnt(11)
	v_mfma_f32_32x32x16_bf16 v[50:65], v[200:203], v[118:121], v[50:65]
	ds_read_b128 v[170:173], v235 offset:36864
	s_waitcnt lgkmcnt(11)
	v_mfma_f32_32x32x16_bf16 v[34:49], v[204:207], v[118:121], v[34:49]
	ds_read_b128 v[178:181], v235 offset:40960
	s_waitcnt lgkmcnt(11)
	v_mfma_f32_32x32x16_bf16 v[18:33], v[208:211], v[118:121], v[18:33]
	ds_read_b128 v[182:185], v235 offset:45056
	s_waitcnt lgkmcnt(7)
	v_mfma_f32_32x32x16_bf16 v[66:81], v[212:215], v[122:125], v[66:81]
	s_waitcnt lgkmcnt(6)
	v_mfma_f32_32x32x16_bf16 v[50:65], v[216:219], v[122:125], v[50:65]
	s_waitcnt lgkmcnt(5)
	v_mfma_f32_32x32x16_bf16 v[34:49], v[220:223], v[122:125], v[34:49]
	s_waitcnt lgkmcnt(4)
	v_mfma_f32_32x32x16_bf16 v[18:33], v[224:227], v[122:125], v[18:33]
	s_waitcnt lgkmcnt(3)
	v_mfma_f32_32x32x16_bf16 v[66:81], v[166:169], v[126:129], v[66:81]
	s_waitcnt lgkmcnt(2)
	v_mfma_f32_32x32x16_bf16 v[50:65], v[170:173], v[126:129], v[50:65]
	s_waitcnt lgkmcnt(1)
	v_mfma_f32_32x32x16_bf16 v[34:49], v[178:181], v[126:129], v[34:49]
	s_waitcnt lgkmcnt(0)
	v_mfma_f32_32x32x16_bf16 v[18:33], v[182:185], v[126:129], v[18:33]
	v_add_f32_e32 v98, v190, v191
	v_and_b32_e32 v178, 63, v163
	v_bfe_u32 v252, v163, 5, 1
	v_lshlrev_b32_e32 v164, 3, v252
	s_waitcnt lgkmcnt(0)
	s_barrier
; template <int MODE> __device__ __forceinline__ void diff_attn_item(const bf16* __restrict__ Qb, const bf16* __restrict__ Kh, const bf16* __restrict__ Vh, ...
;     ...
;   lsum += __shfl_xor(lsum, 32);
;   const float rl = 1.f / lsum;
;   float* E = (float*)lds;
;   if (map == 1) {
	v_and_b32_e32 v83, 64, v193
	v_xor_b32_e32 v82, 32, v193
	v_add_u32_e32 v83, 64, v83
	v_cmp_lt_i32_e32 vcc, v82, v83
	s_nop 1
	v_cndmask_b32_e32 v82, v193, v82, vcc
	v_lshlrev_b32_e32 v83, 2, v82
	ds_bpermute_b32 v82, v83, v98
	s_nop 0
	s_waitcnt lgkmcnt(0)
	v_add_f32_e32 v82, v98, v82
	v_div_scale_f32 v84, s[4:5], v82, v82, 1.0
	v_rcp_f32_e32 v85, v84
	s_nop 0
	v_fma_f32 v98, -v84, v85, 1.0
	v_fmac_f32_e32 v85, v98, v85
	v_div_scale_f32 v98, vcc, 1.0, v82, 1.0
	s_nop 0
	v_mul_f32_e32 v90, v98, v85
	v_fma_f32 v91, -v84, v90, v98
	v_fmac_f32_e32 v90, v91, v85
	v_fma_f32 v84, -v84, v90, v98
	v_div_fmas_f32 v84, v84, v85, v90
	v_div_fixup_f32 v82, v84, v82, 1.0
	v_cmp_eq_u32_e32 vcc, 1, v177
	s_nop 0
	s_branch .Lda1_join

; template <int MODE> __device__ __forceinline__ void diff_attn_item(const bf16* __restrict__ Qb, const bf16* __restrict__ Kh, const bf16* __restrict__ Vh, ...
;     ...
;   const bf16* Qw = Qb + (long)(rb * 32 + r32) * 128 + map * 64 + hi * 8;
; #pragma unroll
;   for (int d0 = 0; d0 < 4; ++d0) qr[d0] = *reinterpret_cast<const bf16x8*>(Qw + d0 * 16);
;   const int ldsbase = (int)(uintptr_t)(__attribute__((address_space(3))) char*)lds;
;   int voff[4];
; #pragma unroll
;   for (int ks = 0; ks < 4; ++ks) voff[ks] = r32 * 128 + ((((ks << 1) | hi) ^ ((r32 >> 1) & 7)) << 4);
;   int ksrc[2], vsrc[2];
; #pragma unroll
;   for (int i = 0; i < 2; ++i) {
;     const int q = tid + i * 512;
;     const int krow = q >> 4, kc = (q & 15) ^ (krow & 15);
;     ksrc[i] = krow * 128 + kc * 8;
;     const int vrow = q >> 3, vc = (q & 7) ^ ((vrow >> 1) & 7);
;     vsrc[i] = vrow * 64 + vc * 8;
;   }
;     ...
;   const int NTL = seq / KVBLK;
;   f32x16 pc0, pc1, pn0, pn1;
;   SLOADW(0, 0);
;   SLOADW(1, KVBLK);
;   asm volatile("s_waitcnt vmcnt(0)" ::: "memory");
;   __syncthreads();
;   qkt(pc0, pc1, lds + SHM_KV, qr, r32, hi, map, negM);
;   int s_cur = 0, s_nxt = 1, s_wr = 2;
;   for (int j = 0; j < NTL; ++j) {
;     const bool has1 = (j + 1 < NTL), has2 = (j + 2 < NTL);
;     if (has2 && MODE == 0) SLOADW(s_wr, (j + 2) * KVBLK);
;     bf16x8 f0, f1, f2, f3;
;     if (has1) qkt(pn0, pn1, lds + s_nxt * SHM_BUF + SHM_KV, qr, r32, hi, map, negM);
;     sm_half<MODE>(pc0, lsum, f0, f1);
;     const char* vt = lds + s_cur * SHM_BUF;
;     pv_b128(o, vt + voff[0], f0); pv_b128(o, vt + voff[1], f1);
;     sm_half<MODE>(pc1, lsum, f2, f3);
;     pv_b128(o, vt + voff[2], f2); pv_b128(o, vt + voff[3], f3);
;     asm volatile("s_waitcnt vmcnt(0)" ::: "memory");
;     __syncthreads();
; template <int AMODE> __device__ __forceinline__ void phase_mixers(int l, int mode) {
;     ...
;       const int i = isl ? it : it - e0;
;       const int bh = isl ? (i >> 6) : (i >> 1), qb = isl ? (i & 63) : (i & 1), b = bh >> 2, h = bh & 3;
;       const size_t base = ((size_t)b * 4 + h) * PTOK * 128 + (isl ? 0 : (size_t)SEQ * 128);
;       const int trow = isl ? (b * SEQ + qb * 128) : (NLAT + b * CTXL + qb * 128);
;       diff_attn_item<AMODE>(qd + base + (size_t)qb * 128 * 128, kd + base, vd + base,
;                      mix + (size_t)trow * 1024 + 512 + h * 128, isl ? PTOK : CTXL, lam, negM, p.da_sub_g + l * 128, oscale);
.LBB0_1992:
	s_ashr_i32 s13, s83, 8
	s_bfe_u32 s3, s83, 0x20006
	s_lshl_b32 s4, s13, 2
	s_or_b32 s4, s4, s3
	s_and_b32 s12, s83, 63
	s_mul_i32 s7, s4, 0x210000
	s_mul_hi_i32 s6, s4, 0x210000
	s_add_u32 s4, s88, s7
	s_addc_u32 s5, s89, s6
	s_lshl_b32 s8, s12, 15
	s_add_u32 s4, s4, s8
	s_addc_u32 s5, s5, 0
	s_add_u32 s8, s90, s7
	s_addc_u32 s9, s91, s6
	s_add_u32 s10, s27, s7
	v_mov_b32_e32 v163, v192
	s_addc_u32 s11, s29, s6
	s_load_dwordx2 s[6:7], s[0:1], 0xa0
	v_mov_b32_e32 v183, 0
	v_and_b32_e32 v34, 31, v163
	v_bfe_u32 v165, v163, 6, 2
	v_ashrrev_i32_e32 v177, 8, v163
	v_lshl_or_b32 v162, v165, 5, v34
	v_lshlrev_b32_e32 v16, 8, v162
	v_lshlrev_b32_e32 v20, 6, v177
	v_bfe_u32 v35, v163, 5, 1
	v_lshl_add_u64 v[18:19], s[4:5], 0, v[16:17]
	v_ashrrev_i32_e32 v21, 31, v20
	v_lshl_add_u64 v[18:19], v[20:21], 1, v[18:19]
	v_lshlrev_b32_e32 v16, 4, v35
	v_lshl_add_u64 v[18:19], v[18:19], 0, v[16:17]
	global_load_dwordx4 v[158:161], v[18:19], off
	global_load_dwordx4 v[154:157], v[18:19], off offset:32
	global_load_dwordx4 v[150:153], v[18:19], off offset:64
	global_load_dwordx4 v[146:149], v[18:19], off offset:96
	s_branch .Lda1_new
.Lda1_join:
	s_and_saveexec_b64 s[8:9], vcc
	s_cbranch_execz .LBB0_1996
	v_mul_f32_e32 v84, v174, v82
	v_lshlrev_b32_e32 v85, 14, v165
	v_lshlrev_b32_e32 v86, 2, v178
	v_mul_f32_e32 v87, v66, v84
	v_add3_u32 v85, 0, v86, v85
	v_mul_f32_e32 v86, v67, v84
	ds_write2st64_b32 v85, v87, v86 offset1:1
	v_mul_f32_e32 v86, v68, v84
	v_mul_f32_e32 v87, v69, v84
	ds_write2st64_b32 v85, v86, v87 offset0:2 offset1:3
	v_mul_f32_e32 v86, v70, v84
	v_mul_f32_e32 v87, v71, v84
	ds_write2st64_b32 v85, v86, v87 offset0:4 offset1:5
	v_mul_f32_e32 v86, v72, v84
	v_mul_f32_e32 v87, v73, v84
	ds_write2st64_b32 v85, v86, v87 offset0:6 offset1:7
	v_mul_f32_e32 v86, v74, v84
	v_mul_f32_e32 v87, v75, v84
	ds_write2st64_b32 v85, v86, v87 offset0:8 offset1:9
	v_mul_f32_e32 v86, v76, v84
	v_mul_f32_e32 v87, v77, v84
	ds_write2st64_b32 v85, v86, v87 offset0:10 offset1:11
	v_mul_f32_e32 v86, v78, v84
	v_mul_f32_e32 v87, v79, v84
	ds_write2st64_b32 v85, v86, v87 offset0:12 offset1:13
	v_mul_f32_e32 v86, v80, v84
	v_mul_f32_e32 v87, v81, v84
	ds_write2st64_b32 v85, v86, v87 offset0:14 offset1:15
	v_mul_f32_e32 v86, v50, v84
	v_mul_f32_e32 v87, v51, v84
	ds_write2st64_b32 v85, v86, v87 offset0:16 offset1:17
	v_mul_f32_e32 v86, v52, v84
	v_mul_f32_e32 v87, v53, v84
	ds_write2st64_b32 v85, v86, v87 offset0:18 offset1:19
	v_mul_f32_e32 v86, v54, v84
	v_mul_f32_e32 v87, v55, v84
	ds_write2st64_b32 v85, v86, v87 offset0:20 offset1:21
	v_mul_f32_e32 v86, v56, v84
	v_mul_f32_e32 v87, v57, v84
	ds_write2st64_b32 v85, v86, v87 offset0:22 offset1:23
	v_mul_f32_e32 v86, v58, v84
	v_mul_f32_e32 v87, v59, v84
	ds_write2st64_b32 v85, v86, v87 offset0:24 offset1:25
	v_mul_f32_e32 v86, v60, v84
	v_mul_f32_e32 v87, v61, v84
	ds_write2st64_b32 v85, v86, v87 offset0:26 offset1:27
	v_mul_f32_e32 v86, v62, v84
	v_mul_f32_e32 v87, v63, v84
	ds_write2st64_b32 v85, v86, v87 offset0:28 offset1:29
	v_mul_f32_e32 v86, v64, v84
	v_mul_f32_e32 v87, v65, v84
	ds_write2st64_b32 v85, v86, v87 offset0:30 offset1:31
	v_mul_f32_e32 v86, v34, v84
	v_mul_f32_e32 v87, v35, v84
	ds_write2st64_b32 v85, v86, v87 offset0:32 offset1:33
	v_mul_f32_e32 v86, v36, v84
	v_mul_f32_e32 v87, v37, v84
	ds_write2st64_b32 v85, v86, v87 offset0:34 offset1:35
	v_mul_f32_e32 v86, v38, v84
	v_mul_f32_e32 v87, v39, v84
	ds_write2st64_b32 v85, v86, v87 offset0:36 offset1:37
	v_mul_f32_e32 v86, v40, v84
	v_mul_f32_e32 v87, v41, v84
	ds_write2st64_b32 v85, v86, v87 offset0:38 offset1:39
	v_mul_f32_e32 v86, v42, v84
	v_mul_f32_e32 v87, v43, v84
	ds_write2st64_b32 v85, v86, v87 offset0:40 offset1:41
	v_mul_f32_e32 v86, v44, v84
	v_mul_f32_e32 v87, v45, v84
	ds_write2st64_b32 v85, v86, v87 offset0:42 offset1:43
	v_mul_f32_e32 v86, v46, v84
	v_mul_f32_e32 v87, v47, v84
	ds_write2st64_b32 v85, v86, v87 offset0:44 offset1:45
	v_mul_f32_e32 v86, v48, v84
	v_mul_f32_e32 v87, v49, v84
	ds_write2st64_b32 v85, v86, v87 offset0:46 offset1:47
	v_mul_f32_e32 v86, v18, v84
	v_mul_f32_e32 v87, v19, v84
	ds_write2st64_b32 v85, v86, v87 offset0:48 offset1:49
	v_mul_f32_e32 v86, v20, v84
	v_mul_f32_e32 v87, v21, v84
	ds_write2st64_b32 v85, v86, v87 offset0:50 offset1:51
	v_mul_f32_e32 v86, v22, v84
	v_mul_f32_e32 v87, v23, v84
	ds_write2st64_b32 v85, v86, v87 offset0:52 offset1:53
	v_mul_f32_e32 v86, v24, v84
	v_mul_f32_e32 v87, v25, v84
	ds_write2st64_b32 v85, v86, v87 offset0:54 offset1:55
	v_mul_f32_e32 v86, v26, v84
	v_mul_f32_e32 v87, v27, v84
	ds_write2st64_b32 v85, v86, v87 offset0:56 offset1:57
	v_mul_f32_e32 v86, v28, v84
	v_mul_f32_e32 v87, v29, v84
	ds_write2st64_b32 v85, v86, v87 offset0:58 offset1:59
	v_mul_f32_e32 v86, v30, v84
	v_mul_f32_e32 v87, v31, v84
	ds_write2st64_b32 v85, v86, v87 offset0:60 offset1:61
	v_mul_f32_e32 v86, v32, v84
	v_mul_f32_e32 v84, v33, v84
	ds_write2st64_b32 v85, v86, v84 offset0:62 offset1:63
